# K-loops: LDS fragment reads issued one by one between the MFMAs instead of in two bursts
# speedup vs baseline: 1.0310x; 1.0088x over previous
.LBB0_147:
	s_and_b32 s13, s12, 0x18000
	v_add_u32_e32 v222, s13, v180
	s_add_i32 s13, s12, 0xfffe8000
	s_and_b32 s13, s13, 0x18000
	v_or_b32_e32 v223, s13, v179
	v_add_u32_e32 v233, s13, v176
	s_waitcnt vmcnt(8) lgkmcnt(0)
	s_barrier
	v_mfma_f32_32x32x16_bf16 v[112:127], v[150:153], v[142:145], v[112:127]
	v_mfma_f32_32x32x16_bf16 v[96:111], v[150:153], v[130:133], v[96:111]
	v_add_u32_e32 v206, v223, v177
	v_add_u32_e32 v234, v233, v177
	ds_read_b128 v[202:205], v206 offset:16384
	ds_read_b128 v[206:209], v206 offset:18432
	ds_read_b128 v[210:213], v234
	v_mfma_f32_32x32x16_bf16 v[80:95], v[146:149], v[142:145], v[80:95]
	v_mfma_f32_32x32x16_bf16 v[64:79], v[146:149], v[130:133], v[64:79]
	ds_read_b128 v[214:217], v234 offset:2048
	v_readfirstlane_b32 s13, v222
	s_mov_b32 m0, s13
	s_nop 0
	global_load_lds_dwordx4 v[170:171], off
	v_mfma_f32_32x32x16_bf16 v[48:63], v[138:141], v[142:145], v[48:63]
	v_mfma_f32_32x32x16_bf16 v[32:47], v[138:141], v[130:133], v[32:47]
	ds_read_b128 v[224:227], v234 offset:4096
	s_add_i32 s14, s13, 0x2000
	v_lshl_add_u64 v[150:151], v[170:171], 0, s[34:35]
	s_mov_b32 m0, s14
	s_nop 0
	global_load_lds_dwordx4 v[150:151], off
	v_mfma_f32_32x32x16_bf16 v[16:31], v[134:137], v[142:145], v[16:31]
	v_mfma_f32_32x32x16_bf16 v[0:15], v[134:137], v[130:133], v[0:15]
	ds_read_b128 v[234:237], v234 offset:6144
	s_waitcnt lgkmcnt(3)
	v_mfma_f32_32x32x16_bf16 v[112:127], v[210:213], v[202:205], v[112:127]
	v_add_u32_e32 v130, v223, v178
	v_add_u32_e32 v134, v233, v178
	ds_read_b128 v[142:145], v130 offset:16384
	v_mfma_f32_32x32x16_bf16 v[96:111], v[210:213], v[206:209], v[96:111]
	ds_read_b128 v[130:133], v130 offset:18432
	s_add_i32 s14, s13, 0x6000
	s_addk_i32 s13, 0x4000
	s_mov_b32 m0, s13
	s_nop 0
	global_load_lds_dwordx4 v[172:173], off
	s_waitcnt lgkmcnt(4)
	v_mfma_f32_32x32x16_bf16 v[80:95], v[214:217], v[202:205], v[80:95]
	ds_read_b128 v[150:153], v134
	v_mfma_f32_32x32x16_bf16 v[64:79], v[214:217], v[206:209], v[64:79]
	ds_read_b128 v[146:149], v134 offset:2048
	s_waitcnt lgkmcnt(5)
	v_mfma_f32_32x32x16_bf16 v[48:63], v[224:227], v[202:205], v[48:63]
	ds_read_b128 v[138:141], v134 offset:4096
	v_mfma_f32_32x32x16_bf16 v[32:47], v[224:227], v[206:209], v[32:47]
	ds_read_b128 v[134:137], v134 offset:6144
	v_lshl_add_u64 v[222:223], v[172:173], 0, s[34:35]
	s_mov_b32 m0, s14
	s_nop 0
	global_load_lds_dwordx4 v[222:223], off
	s_waitcnt lgkmcnt(6)
	v_mfma_f32_32x32x16_bf16 v[16:31], v[234:237], v[202:205], v[16:31]
	s_add_i32 s12, s12, 0x8000
	v_lshl_add_u64 v[170:171], v[170:171], 0, 64
	v_lshl_add_u64 v[172:173], v[172:173], 0, 64
	s_cmp_eq_u32 s12, 0x100000
	v_mfma_f32_32x32x16_bf16 v[0:15], v[234:237], v[206:209], v[0:15]
	s_cbranch_scc0 .LBB0_147
	s_waitcnt vmcnt(8) lgkmcnt(0)
	s_barrier
	v_add_u32_e32 v202, v179, v177
	v_add_u32_e32 v222, v176, v177
	ds_read_b128 v[170:173], v202 offset:49152
	ds_read_b128 v[202:205], v202 offset:51200
	ds_read_b128 v[206:209], v222 offset:32768
	ds_read_b128 v[210:213], v222 offset:34816
	ds_read_b128 v[214:217], v222 offset:36864
	ds_read_b128 v[224:227], v222 offset:38912
	s_waitcnt lgkmcnt(9)
	v_mfma_f32_32x32x16_bf16 v[112:127], v[150:153], v[142:145], v[112:127]
	v_mfma_f32_32x32x16_bf16 v[96:111], v[150:153], v[130:133], v[96:111]
	s_waitcnt lgkmcnt(8)
	v_mfma_f32_32x32x16_bf16 v[80:95], v[146:149], v[142:145], v[80:95]
	v_mfma_f32_32x32x16_bf16 v[64:79], v[146:149], v[130:133], v[64:79]
	s_waitcnt lgkmcnt(7)
	v_mfma_f32_32x32x16_bf16 v[48:63], v[138:141], v[142:145], v[48:63]
	v_mfma_f32_32x32x16_bf16 v[32:47], v[138:141], v[130:133], v[32:47]
	s_waitcnt lgkmcnt(6)
	v_mfma_f32_32x32x16_bf16 v[16:31], v[134:137], v[142:145], v[16:31]
	v_mfma_f32_32x32x16_bf16 v[0:15], v[134:137], v[130:133], v[0:15]
	v_add_u32_e32 v134, v179, v178
	v_add_u32_e32 v150, v176, v178
	ds_read_b128 v[130:133], v134 offset:49152
	ds_read_b128 v[134:137], v134 offset:51200
	ds_read_b128 v[138:141], v150 offset:32768
	ds_read_b128 v[142:145], v150 offset:34816
	ds_read_b128 v[146:149], v150 offset:36864
	ds_read_b128 v[150:153], v150 offset:38912
	s_waitcnt lgkmcnt(9)
	v_mfma_f32_32x32x16_bf16 v[112:127], v[206:209], v[170:173], v[112:127]
	v_mfma_f32_32x32x16_bf16 v[96:111], v[206:209], v[202:205], v[96:111]
	s_waitcnt lgkmcnt(8)
	v_mfma_f32_32x32x16_bf16 v[80:95], v[210:213], v[170:173], v[80:95]
	v_mfma_f32_32x32x16_bf16 v[64:79], v[210:213], v[202:205], v[64:79]
	s_waitcnt lgkmcnt(7)
	v_mfma_f32_32x32x16_bf16 v[48:63], v[214:217], v[170:173], v[48:63]
	v_mfma_f32_32x32x16_bf16 v[32:47], v[214:217], v[202:205], v[32:47]
	s_waitcnt lgkmcnt(6)
	v_mfma_f32_32x32x16_bf16 v[0:15], v[224:227], v[202:205], v[0:15]
	s_waitcnt vmcnt(4) lgkmcnt(0)
	s_barrier
	v_add_u32_e32 v202, v199, v177
	v_add_u32_e32 v222, v200, v177
	v_mfma_f32_32x32x16_bf16 v[16:31], v[224:227], v[170:173], v[16:31]
	ds_read_b128 v[170:173], v202 offset:16384
	ds_read_b128 v[202:205], v202 offset:18432
	ds_read_b128 v[206:209], v222
	ds_read_b128 v[210:213], v222 offset:2048
	ds_read_b128 v[214:217], v222 offset:4096
	ds_read_b128 v[224:227], v222 offset:6144
	s_waitcnt lgkmcnt(9)
	v_mfma_f32_32x32x16_bf16 v[112:127], v[138:141], v[130:133], v[112:127]
	v_mfma_f32_32x32x16_bf16 v[96:111], v[138:141], v[134:137], v[96:111]
	s_waitcnt lgkmcnt(8)
	v_mfma_f32_32x32x16_bf16 v[80:95], v[142:145], v[130:133], v[80:95]
	v_mfma_f32_32x32x16_bf16 v[64:79], v[142:145], v[134:137], v[64:79]
	s_waitcnt lgkmcnt(7)
	v_mfma_f32_32x32x16_bf16 v[48:63], v[146:149], v[130:133], v[48:63]
	v_mfma_f32_32x32x16_bf16 v[32:47], v[146:149], v[134:137], v[32:47]
	s_waitcnt lgkmcnt(6)
	v_mfma_f32_32x32x16_bf16 v[16:31], v[150:153], v[130:133], v[16:31]
	v_mfma_f32_32x32x16_bf16 v[0:15], v[150:153], v[134:137], v[0:15]
	v_add_u32_e32 v134, v199, v178
	v_add_u32_e32 v150, v200, v178
	ds_read_b128 v[130:133], v134 offset:16384
	ds_read_b128 v[134:137], v134 offset:18432
	ds_read_b128 v[138:141], v150
	ds_read_b128 v[142:145], v150 offset:2048
	ds_read_b128 v[146:149], v150 offset:4096
	ds_read_b128 v[150:153], v150 offset:6144
	s_waitcnt lgkmcnt(9)
	v_mfma_f32_32x32x16_bf16 v[112:127], v[206:209], v[170:173], v[112:127]
	v_mfma_f32_32x32x16_bf16 v[96:111], v[206:209], v[202:205], v[96:111]
	s_waitcnt lgkmcnt(8)
	v_mfma_f32_32x32x16_bf16 v[80:95], v[210:213], v[170:173], v[80:95]
	v_mfma_f32_32x32x16_bf16 v[64:79], v[210:213], v[202:205], v[64:79]
	s_waitcnt lgkmcnt(7)
	v_mfma_f32_32x32x16_bf16 v[48:63], v[214:217], v[170:173], v[48:63]
	v_mfma_f32_32x32x16_bf16 v[32:47], v[214:217], v[202:205], v[32:47]
	s_waitcnt lgkmcnt(6)
	v_mfma_f32_32x32x16_bf16 v[0:15], v[224:227], v[202:205], v[0:15]
	s_waitcnt vmcnt(0) lgkmcnt(0)
	s_barrier
	v_add_u32_e32 v202, v197, v177
	v_add_u32_e32 v222, v198, v177
	v_mfma_f32_32x32x16_bf16 v[16:31], v[224:227], v[170:173], v[16:31]
	ds_read_b128 v[170:173], v202 offset:16384
	ds_read_b128 v[202:205], v202 offset:18432
	ds_read_b128 v[206:209], v222
	ds_read_b128 v[210:213], v222 offset:2048
	ds_read_b128 v[214:217], v222 offset:4096
	ds_read_b128 v[224:227], v222 offset:6144
	s_waitcnt lgkmcnt(9)
	v_mfma_f32_32x32x16_bf16 v[112:127], v[138:141], v[130:133], v[112:127]
	v_mfma_f32_32x32x16_bf16 v[96:111], v[138:141], v[134:137], v[96:111]
	s_waitcnt lgkmcnt(8)
	v_mfma_f32_32x32x16_bf16 v[80:95], v[142:145], v[130:133], v[80:95]
	v_mfma_f32_32x32x16_bf16 v[64:79], v[142:145], v[134:137], v[64:79]
	s_waitcnt lgkmcnt(7)
	v_mfma_f32_32x32x16_bf16 v[48:63], v[146:149], v[130:133], v[48:63]
	v_mfma_f32_32x32x16_bf16 v[32:47], v[146:149], v[134:137], v[32:47]
	s_waitcnt lgkmcnt(6)
	v_mfma_f32_32x32x16_bf16 v[16:31], v[150:153], v[130:133], v[16:31]
	v_mfma_f32_32x32x16_bf16 v[0:15], v[150:153], v[134:137], v[0:15]
	v_add_u32_e32 v134, v197, v178
	v_add_u32_e32 v150, v198, v178
	ds_read_b128 v[130:133], v134 offset:16384
	ds_read_b128 v[134:137], v134 offset:18432
	ds_read_b128 v[138:141], v150
	ds_read_b128 v[142:145], v150 offset:2048
	ds_read_b128 v[146:149], v150 offset:4096
	ds_read_b128 v[150:153], v150 offset:6144
	s_waitcnt lgkmcnt(9)
	v_mfma_f32_32x32x16_bf16 v[112:127], v[206:209], v[170:173], v[112:127]
	v_mfma_f32_32x32x16_bf16 v[96:111], v[206:209], v[202:205], v[96:111]
	s_waitcnt lgkmcnt(8)
	v_mfma_f32_32x32x16_bf16 v[80:95], v[210:213], v[170:173], v[80:95]
	v_mfma_f32_32x32x16_bf16 v[64:79], v[210:213], v[202:205], v[64:79]
	s_waitcnt lgkmcnt(7)
	v_mfma_f32_32x32x16_bf16 v[48:63], v[214:217], v[170:173], v[48:63]
	v_mfma_f32_32x32x16_bf16 v[32:47], v[214:217], v[202:205], v[32:47]
	s_waitcnt lgkmcnt(6)
	v_mfma_f32_32x32x16_bf16 v[16:31], v[224:227], v[170:173], v[16:31]
	v_mfma_f32_32x32x16_bf16 v[0:15], v[224:227], v[202:205], v[0:15]
	s_waitcnt lgkmcnt(3)
	v_mfma_f32_32x32x16_bf16 v[96:111], v[138:141], v[134:137], v[96:111]
	v_mfma_f32_32x32x16_bf16 v[112:127], v[138:141], v[130:133], v[112:127]
	s_nop 10
	v_cvt_pk_bf16_f32 v96, v96, s0
	v_cvt_pk_bf16_f32 v98, v98, s0
	s_waitcnt lgkmcnt(2)
	v_mfma_f32_32x32x16_bf16 v[80:95], v[142:145], v[130:133], v[80:95]
	v_cvt_pk_bf16_f32 v112, v112, s0
	s_waitcnt lgkmcnt(1)
	v_mfma_f32_32x32x16_bf16 v[48:63], v[146:149], v[130:133], v[48:63]
	s_nop 8
	v_cvt_pk_bf16_f32 v80, v80, s0
	s_waitcnt lgkmcnt(0)
	v_mfma_f32_32x32x16_bf16 v[16:31], v[150:153], v[130:133], v[16:31]
	v_or_b32_e32 v130, s11, v174
	v_ashrrev_i32_e32 v131, 31, v130
	v_lshl_add_u64 v[130:131], v[130:131], 1, v[158:159]
	v_cvt_pk_bf16_f32 v48, v48, s0
	v_mfma_f32_32x32x16_bf16 v[64:79], v[142:145], v[134:137], v[64:79]
	s_nop 6
	v_cvt_pk_bf16_f32 v16, v16, s0
	v_mfma_f32_32x32x16_bf16 v[32:47], v[146:149], v[134:137], v[32:47]
	s_nop 2
	v_cvt_pk_bf16_f32 v64, v64, s0
	v_cvt_pk_bf16_f32 v66, v66, s0
	v_mfma_f32_32x32x16_bf16 v[0:15], v[150:153], v[134:137], v[0:15]
	v_add_u32_e32 v134, s7, v128
	v_or_b32_e32 v132, v134, v181
	s_movk_i32 s7, 0x1800
	v_mad_i64_i32 v[132:133], s[12:13], v132, s7, v[130:131]
	global_store_short v[132:133], v96, off offset:64
	v_or_b32_e32 v96, v134, v182
	global_store_short v[132:133], v112, off
	v_mad_i64_i32 v[132:133], s[12:13], v96, s7, v[130:131]
	v_cvt_pk_bf16_f32 v96, v113, s0
	global_store_short v[132:133], v96, off
	v_cvt_pk_bf16_f32 v96, v97, s0
	global_store_short v[132:133], v96, off offset:64
	v_or_b32_e32 v96, v134, v183
	v_mad_i64_i32 v[96:97], s[12:13], v96, s7, v[130:131]
	v_cvt_pk_bf16_f32 v112, v114, s0
	global_store_short v[96:97], v112, off
	global_store_short v[96:97], v98, off offset:64
	v_or_b32_e32 v96, v134, v184
	v_mad_i64_i32 v[96:97], s[12:13], v96, s7, v[130:131]
	v_cvt_pk_bf16_f32 v98, v115, s0
	global_store_short v[96:97], v98, off
	v_cvt_pk_bf16_f32 v98, v99, s0
	global_store_short v[96:97], v98, off offset:64
	v_or_b32_e32 v96, v134, v185
	v_mad_i64_i32 v[96:97], s[12:13], v96, s7, v[130:131]
	v_cvt_pk_bf16_f32 v98, v116, s0
	global_store_short v[96:97], v98, off
	v_cvt_pk_bf16_f32 v98, v100, s0
	global_store_short v[96:97], v98, off offset:64
	v_or_b32_e32 v96, v134, v186
	v_mad_i64_i32 v[96:97], s[12:13], v96, s7, v[130:131]
	v_cvt_pk_bf16_f32 v98, v117, s0
	global_store_short v[96:97], v98, off
	v_cvt_pk_bf16_f32 v98, v101, s0
	global_store_short v[96:97], v98, off offset:64
	v_or_b32_e32 v96, v134, v187
	v_mad_i64_i32 v[96:97], s[12:13], v96, s7, v[130:131]
	v_cvt_pk_bf16_f32 v98, v118, s0
	global_store_short v[96:97], v98, off
	v_cvt_pk_bf16_f32 v98, v102, s0
	global_store_short v[96:97], v98, off offset:64
	v_or_b32_e32 v96, v134, v188
	v_mad_i64_i32 v[96:97], s[12:13], v96, s7, v[130:131]
	v_cvt_pk_bf16_f32 v98, v119, s0
	global_store_short v[96:97], v98, off
	v_cvt_pk_bf16_f32 v98, v103, s0
	global_store_short v[96:97], v98, off offset:64
	v_or_b32_e32 v96, v134, v189
	v_mad_i64_i32 v[96:97], s[12:13], v96, s7, v[130:131]
	v_cvt_pk_bf16_f32 v98, v120, s0
	global_store_short v[96:97], v98, off
	v_cvt_pk_bf16_f32 v98, v104, s0
	global_store_short v[96:97], v98, off offset:64
	v_or_b32_e32 v96, v134, v190
	v_mad_i64_i32 v[96:97], s[12:13], v96, s7, v[130:131]
	v_cvt_pk_bf16_f32 v98, v121, s0
	global_store_short v[96:97], v98, off
	v_cvt_pk_bf16_f32 v98, v105, s0
	global_store_short v[96:97], v98, off offset:64
	v_or_b32_e32 v96, v134, v191
	v_mad_i64_i32 v[96:97], s[12:13], v96, s7, v[130:131]
	v_cvt_pk_bf16_f32 v98, v122, s0
	global_store_short v[96:97], v98, off
	v_cvt_pk_bf16_f32 v98, v106, s0
	global_store_short v[96:97], v98, off offset:64
	v_or_b32_e32 v96, v134, v192
	v_mad_i64_i32 v[96:97], s[12:13], v96, s7, v[130:131]
	v_cvt_pk_bf16_f32 v98, v123, s0
	global_store_short v[96:97], v98, off
	v_cvt_pk_bf16_f32 v98, v107, s0
	global_store_short v[96:97], v98, off offset:64
	v_or_b32_e32 v96, v134, v193
	v_mad_i64_i32 v[96:97], s[12:13], v96, s7, v[130:131]
	v_cvt_pk_bf16_f32 v98, v124, s0
	global_store_short v[96:97], v98, off
	v_cvt_pk_bf16_f32 v98, v108, s0
	global_store_short v[96:97], v98, off offset:64
	v_or_b32_e32 v96, v134, v194
	v_mad_i64_i32 v[96:97], s[12:13], v96, s7, v[130:131]
	v_cvt_pk_bf16_f32 v98, v125, s0
	global_store_short v[96:97], v98, off
	v_cvt_pk_bf16_f32 v98, v109, s0
	global_store_short v[96:97], v98, off offset:64
	v_or_b32_e32 v96, v134, v195
	v_mad_i64_i32 v[96:97], s[12:13], v96, s7, v[130:131]
	v_cvt_pk_bf16_f32 v98, v126, s0
	global_store_short v[96:97], v98, off
	v_cvt_pk_bf16_f32 v98, v110, s0
	global_store_short v[96:97], v98, off offset:64
	v_or_b32_e32 v96, v134, v196
	v_mad_i64_i32 v[96:97], s[12:13], v96, s7, v[130:131]
	v_cvt_pk_bf16_f32 v98, v127, s0
	global_store_short v[96:97], v98, off
	v_cvt_pk_bf16_f32 v98, v111, s0
	global_store_short v[96:97], v98, off offset:64
	v_or_b32_e32 v98, 32, v134
	v_or_b32_e32 v96, v98, v181
	v_mad_i64_i32 v[96:97], s[12:13], v96, s7, v[130:131]
	global_store_short v[96:97], v64, off offset:64
	v_or_b32_e32 v64, v98, v182
	global_store_short v[96:97], v80, off
	v_mad_i64_i32 v[96:97], s[12:13], v64, s7, v[130:131]
	v_cvt_pk_bf16_f32 v64, v81, s0
	global_store_short v[96:97], v64, off
	v_cvt_pk_bf16_f32 v64, v65, s0
	global_store_short v[96:97], v64, off offset:64
	v_or_b32_e32 v64, v98, v183
	v_mad_i64_i32 v[64:65], s[12:13], v64, s7, v[130:131]
	v_cvt_pk_bf16_f32 v80, v82, s0
	global_store_short v[64:65], v80, off
	global_store_short v[64:65], v66, off offset:64
	v_or_b32_e32 v64, v98, v184
	v_mad_i64_i32 v[64:65], s[12:13], v64, s7, v[130:131]
	v_cvt_pk_bf16_f32 v66, v83, s0
	global_store_short v[64:65], v66, off
	v_cvt_pk_bf16_f32 v66, v67, s0
	global_store_short v[64:65], v66, off offset:64
	v_or_b32_e32 v64, v98, v185
	v_mad_i64_i32 v[64:65], s[12:13], v64, s7, v[130:131]
	v_cvt_pk_bf16_f32 v66, v84, s0
	global_store_short v[64:65], v66, off
	v_cvt_pk_bf16_f32 v66, v68, s0
	global_store_short v[64:65], v66, off offset:64
	v_or_b32_e32 v64, v98, v186
	v_mad_i64_i32 v[64:65], s[12:13], v64, s7, v[130:131]
	v_cvt_pk_bf16_f32 v66, v85, s0
	global_store_short v[64:65], v66, off
	v_cvt_pk_bf16_f32 v66, v69, s0
	global_store_short v[64:65], v66, off offset:64
	v_or_b32_e32 v64, v98, v187
	v_mad_i64_i32 v[64:65], s[12:13], v64, s7, v[130:131]
	v_cvt_pk_bf16_f32 v66, v86, s0
	global_store_short v[64:65], v66, off
	v_cvt_pk_bf16_f32 v66, v70, s0
	global_store_short v[64:65], v66, off offset:64
	v_or_b32_e32 v64, v98, v188
	v_mad_i64_i32 v[64:65], s[12:13], v64, s7, v[130:131]
	v_cvt_pk_bf16_f32 v66, v87, s0
	global_store_short v[64:65], v66, off
	v_cvt_pk_bf16_f32 v66, v71, s0
	global_store_short v[64:65], v66, off offset:64
	v_or_b32_e32 v64, v98, v189
	v_mad_i64_i32 v[64:65], s[12:13], v64, s7, v[130:131]
	v_cvt_pk_bf16_f32 v66, v88, s0
	global_store_short v[64:65], v66, off
	v_cvt_pk_bf16_f32 v66, v72, s0
	global_store_short v[64:65], v66, off offset:64
	v_or_b32_e32 v64, v98, v190
	v_mad_i64_i32 v[64:65], s[12:13], v64, s7, v[130:131]
	v_cvt_pk_bf16_f32 v66, v89, s0
	global_store_short v[64:65], v66, off
	v_cvt_pk_bf16_f32 v66, v73, s0
	global_store_short v[64:65], v66, off offset:64
	v_or_b32_e32 v64, v98, v191
	v_mad_i64_i32 v[64:65], s[12:13], v64, s7, v[130:131]
	v_cvt_pk_bf16_f32 v66, v90, s0
	global_store_short v[64:65], v66, off
	v_cvt_pk_bf16_f32 v66, v74, s0
	global_store_short v[64:65], v66, off offset:64
	v_or_b32_e32 v64, v98, v192
	v_mad_i64_i32 v[64:65], s[12:13], v64, s7, v[130:131]
	v_cvt_pk_bf16_f32 v66, v91, s0
	global_store_short v[64:65], v66, off
	v_cvt_pk_bf16_f32 v66, v75, s0
	global_store_short v[64:65], v66, off offset:64
	v_or_b32_e32 v64, v98, v193
	v_mad_i64_i32 v[64:65], s[12:13], v64, s7, v[130:131]
	v_cvt_pk_bf16_f32 v66, v92, s0
	global_store_short v[64:65], v66, off
	v_cvt_pk_bf16_f32 v66, v76, s0
	global_store_short v[64:65], v66, off offset:64
	v_or_b32_e32 v64, v98, v194
	v_mad_i64_i32 v[64:65], s[12:13], v64, s7, v[130:131]
	v_cvt_pk_bf16_f32 v66, v93, s0
	global_store_short v[64:65], v66, off
	v_cvt_pk_bf16_f32 v66, v77, s0
	global_store_short v[64:65], v66, off offset:64
	v_or_b32_e32 v64, v98, v195
	v_mad_i64_i32 v[64:65], s[12:13], v64, s7, v[130:131]
	v_cvt_pk_bf16_f32 v66, v94, s0
	global_store_short v[64:65], v66, off
	v_cvt_pk_bf16_f32 v66, v78, s0
	global_store_short v[64:65], v66, off offset:64
	v_or_b32_e32 v64, v98, v196
	v_mad_i64_i32 v[64:65], s[12:13], v64, s7, v[130:131]
	v_cvt_pk_bf16_f32 v66, v95, s0
	global_store_short v[64:65], v66, off
	v_cvt_pk_bf16_f32 v66, v79, s0
	global_store_short v[64:65], v66, off offset:64
	v_or_b32_e32 v66, 64, v134
	v_or_b32_e32 v64, v66, v181
	v_mad_i64_i32 v[64:65], s[12:13], v64, s7, v[130:131]
	v_cvt_pk_bf16_f32 v32, v32, s0
	global_store_short v[64:65], v32, off offset:64
	v_or_b32_e32 v32, v66, v182
	global_store_short v[64:65], v48, off
	v_mad_i64_i32 v[64:65], s[12:13], v32, s7, v[130:131]
	v_cvt_pk_bf16_f32 v32, v49, s0
	global_store_short v[64:65], v32, off
	v_cvt_pk_bf16_f32 v32, v33, s0
	global_store_short v[64:65], v32, off offset:64
	v_or_b32_e32 v32, v66, v183
	v_mad_i64_i32 v[32:33], s[12:13], v32, s7, v[130:131]
	v_cvt_pk_bf16_f32 v48, v50, s0
	v_cvt_pk_bf16_f32 v34, v34, s0
	global_store_short v[32:33], v48, off
	global_store_short v[32:33], v34, off offset:64
	v_or_b32_e32 v32, v66, v184
	v_mad_i64_i32 v[32:33], s[12:13], v32, s7, v[130:131]
	v_cvt_pk_bf16_f32 v34, v51, s0
	global_store_short v[32:33], v34, off
	v_cvt_pk_bf16_f32 v34, v35, s0
	global_store_short v[32:33], v34, off offset:64
	v_or_b32_e32 v32, v66, v185
	v_mad_i64_i32 v[32:33], s[12:13], v32, s7, v[130:131]
	v_cvt_pk_bf16_f32 v34, v52, s0
	global_store_short v[32:33], v34, off
	v_cvt_pk_bf16_f32 v34, v36, s0
	global_store_short v[32:33], v34, off offset:64
	v_or_b32_e32 v32, v66, v186
	v_mad_i64_i32 v[32:33], s[12:13], v32, s7, v[130:131]
	v_cvt_pk_bf16_f32 v34, v53, s0
	global_store_short v[32:33], v34, off
	v_cvt_pk_bf16_f32 v34, v37, s0
	global_store_short v[32:33], v34, off offset:64
	v_or_b32_e32 v32, v66, v187
	v_mad_i64_i32 v[32:33], s[12:13], v32, s7, v[130:131]
	v_cvt_pk_bf16_f32 v34, v54, s0
	global_store_short v[32:33], v34, off
	v_cvt_pk_bf16_f32 v34, v38, s0
	global_store_short v[32:33], v34, off offset:64
	v_or_b32_e32 v32, v66, v188
	v_mad_i64_i32 v[32:33], s[12:13], v32, s7, v[130:131]
	v_cvt_pk_bf16_f32 v34, v55, s0
	global_store_short v[32:33], v34, off
	v_cvt_pk_bf16_f32 v34, v39, s0
	global_store_short v[32:33], v34, off offset:64
	v_or_b32_e32 v32, v66, v189
	v_mad_i64_i32 v[32:33], s[12:13], v32, s7, v[130:131]
	v_cvt_pk_bf16_f32 v34, v56, s0
	global_store_short v[32:33], v34, off
	v_cvt_pk_bf16_f32 v34, v40, s0
	global_store_short v[32:33], v34, off offset:64
	v_or_b32_e32 v32, v66, v190
	v_mad_i64_i32 v[32:33], s[12:13], v32, s7, v[130:131]
	v_cvt_pk_bf16_f32 v34, v57, s0
	global_store_short v[32:33], v34, off
	v_cvt_pk_bf16_f32 v34, v41, s0
	global_store_short v[32:33], v34, off offset:64
	v_or_b32_e32 v32, v66, v191
	v_mad_i64_i32 v[32:33], s[12:13], v32, s7, v[130:131]
	v_cvt_pk_bf16_f32 v34, v58, s0
	global_store_short v[32:33], v34, off
	v_cvt_pk_bf16_f32 v34, v42, s0
	global_store_short v[32:33], v34, off offset:64
	v_or_b32_e32 v32, v66, v192
	v_mad_i64_i32 v[32:33], s[12:13], v32, s7, v[130:131]
	v_cvt_pk_bf16_f32 v34, v59, s0
	global_store_short v[32:33], v34, off
	v_cvt_pk_bf16_f32 v34, v43, s0
	global_store_short v[32:33], v34, off offset:64
	v_or_b32_e32 v32, v66, v193
	v_mad_i64_i32 v[32:33], s[12:13], v32, s7, v[130:131]
	v_cvt_pk_bf16_f32 v34, v60, s0
	global_store_short v[32:33], v34, off
	v_cvt_pk_bf16_f32 v34, v44, s0
	global_store_short v[32:33], v34, off offset:64
	v_or_b32_e32 v32, v66, v194
	v_mad_i64_i32 v[32:33], s[12:13], v32, s7, v[130:131]
	v_cvt_pk_bf16_f32 v34, v61, s0
	global_store_short v[32:33], v34, off
	v_cvt_pk_bf16_f32 v34, v45, s0
	global_store_short v[32:33], v34, off offset:64
	v_or_b32_e32 v32, v66, v195
	v_mad_i64_i32 v[32:33], s[12:13], v32, s7, v[130:131]
	v_cvt_pk_bf16_f32 v34, v62, s0
	global_store_short v[32:33], v34, off
	v_cvt_pk_bf16_f32 v34, v46, s0
	global_store_short v[32:33], v34, off offset:64
	v_or_b32_e32 v32, v66, v196
	v_mad_i64_i32 v[32:33], s[12:13], v32, s7, v[130:131]
	v_cvt_pk_bf16_f32 v34, v63, s0
	global_store_short v[32:33], v34, off
	v_cvt_pk_bf16_f32 v34, v47, s0
	global_store_short v[32:33], v34, off offset:64
	v_or_b32_e32 v34, 0x60, v134
	v_or_b32_e32 v32, v34, v181
	v_mad_i64_i32 v[32:33], s[12:13], v32, s7, v[130:131]
	v_cvt_pk_bf16_f32 v0, v0, s0
	global_store_short v[32:33], v0, off offset:64
	v_or_b32_e32 v0, v34, v182
	global_store_short v[32:33], v16, off
	v_mad_i64_i32 v[32:33], s[12:13], v0, s7, v[130:131]
	v_cvt_pk_bf16_f32 v0, v17, s0
	global_store_short v[32:33], v0, off
	v_cvt_pk_bf16_f32 v0, v1, s0
	global_store_short v[32:33], v0, off offset:64
	v_or_b32_e32 v0, v34, v183
	v_mad_i64_i32 v[0:1], s[12:13], v0, s7, v[130:131]
	v_cvt_pk_bf16_f32 v16, v18, s0
	v_cvt_pk_bf16_f32 v2, v2, s0
	global_store_short v[0:1], v16, off
	global_store_short v[0:1], v2, off offset:64
	v_or_b32_e32 v0, v34, v184
	v_mad_i64_i32 v[0:1], s[12:13], v0, s7, v[130:131]
	v_cvt_pk_bf16_f32 v2, v19, s0
	global_store_short v[0:1], v2, off
	v_cvt_pk_bf16_f32 v2, v3, s0
	global_store_short v[0:1], v2, off offset:64
	v_or_b32_e32 v0, v34, v185
	v_mad_i64_i32 v[0:1], s[12:13], v0, s7, v[130:131]
	v_cvt_pk_bf16_f32 v2, v20, s0
	global_store_short v[0:1], v2, off
	v_cvt_pk_bf16_f32 v2, v4, s0
	global_store_short v[0:1], v2, off offset:64
	v_or_b32_e32 v0, v34, v186
	v_mad_i64_i32 v[0:1], s[12:13], v0, s7, v[130:131]
	v_cvt_pk_bf16_f32 v2, v21, s0
	global_store_short v[0:1], v2, off
	v_cvt_pk_bf16_f32 v2, v5, s0
	global_store_short v[0:1], v2, off offset:64
	v_or_b32_e32 v0, v34, v187
	v_mad_i64_i32 v[0:1], s[12:13], v0, s7, v[130:131]
	v_cvt_pk_bf16_f32 v2, v22, s0
	global_store_short v[0:1], v2, off
	v_cvt_pk_bf16_f32 v2, v6, s0
	global_store_short v[0:1], v2, off offset:64
	v_or_b32_e32 v0, v34, v188
	v_mad_i64_i32 v[0:1], s[12:13], v0, s7, v[130:131]
	v_cvt_pk_bf16_f32 v2, v23, s0
	global_store_short v[0:1], v2, off
	v_cvt_pk_bf16_f32 v2, v7, s0
	global_store_short v[0:1], v2, off offset:64
	v_or_b32_e32 v0, v34, v189
	v_mad_i64_i32 v[0:1], s[12:13], v0, s7, v[130:131]
	v_cvt_pk_bf16_f32 v2, v24, s0
	global_store_short v[0:1], v2, off
	v_cvt_pk_bf16_f32 v2, v8, s0
	global_store_short v[0:1], v2, off offset:64
	v_or_b32_e32 v0, v34, v190
	v_mad_i64_i32 v[0:1], s[12:13], v0, s7, v[130:131]
	v_cvt_pk_bf16_f32 v2, v25, s0
	global_store_short v[0:1], v2, off
	v_cvt_pk_bf16_f32 v2, v9, s0
	global_store_short v[0:1], v2, off offset:64
	v_or_b32_e32 v0, v34, v191
	v_mad_i64_i32 v[0:1], s[12:13], v0, s7, v[130:131]
	v_cvt_pk_bf16_f32 v2, v26, s0
	global_store_short v[0:1], v2, off
	v_cvt_pk_bf16_f32 v2, v10, s0
	global_store_short v[0:1], v2, off offset:64
	v_or_b32_e32 v0, v34, v192
	v_mad_i64_i32 v[0:1], s[12:13], v0, s7, v[130:131]
	v_cvt_pk_bf16_f32 v2, v27, s0
	global_store_short v[0:1], v2, off
	v_cvt_pk_bf16_f32 v2, v11, s0
	global_store_short v[0:1], v2, off offset:64
	v_or_b32_e32 v0, v34, v193
	v_mad_i64_i32 v[0:1], s[12:13], v0, s7, v[130:131]
	v_cvt_pk_bf16_f32 v2, v28, s0
	global_store_short v[0:1], v2, off
	v_cvt_pk_bf16_f32 v2, v12, s0
	global_store_short v[0:1], v2, off offset:64
	v_or_b32_e32 v0, v34, v194
	v_mad_i64_i32 v[0:1], s[12:13], v0, s7, v[130:131]
	v_cvt_pk_bf16_f32 v2, v29, s0
	global_store_short v[0:1], v2, off
	v_cvt_pk_bf16_f32 v2, v13, s0
	global_store_short v[0:1], v2, off offset:64
	v_or_b32_e32 v0, v34, v195
	v_mad_i64_i32 v[0:1], s[12:13], v0, s7, v[130:131]
	v_cvt_pk_bf16_f32 v2, v30, s0
	global_store_short v[0:1], v2, off
	v_cvt_pk_bf16_f32 v2, v14, s0
	global_store_short v[0:1], v2, off offset:64
	v_or_b32_e32 v0, v34, v196
	v_mad_i64_i32 v[0:1], s[12:13], v0, s7, v[130:131]
	v_readlane_b32 s7, v252, 7
	s_add_i32 s10, s10, s7
	s_add_i32 s4, s4, s7
	v_readlane_b32 s7, v252, 8
	v_cvt_pk_bf16_f32 v2, v31, s0
	s_add_i32 s6, s6, s7
	global_store_short v[0:1], v2, off
	v_cvt_pk_bf16_f32 v2, v15, s0
	s_cmpk_gt_i32 s10, 0x5f
	global_store_short v[0:1], v2, off offset:64
	s_cbranch_scc0 .LBB0_146

.LBB0_263:
	s_and_b32 s11, s10, 0x18000
	v_add_u32_e32 v222, s11, v180
	s_add_i32 s11, s10, 0xfffe8000
	s_and_b32 s11, s11, 0x18000
	v_or_b32_e32 v223, s11, v179
	v_add_u32_e32 v233, s11, v176
	s_waitcnt vmcnt(8) lgkmcnt(0)
	s_barrier
	v_mfma_f32_32x32x16_bf16 v[112:127], v[150:153], v[142:145], v[112:127]
	v_mfma_f32_32x32x16_bf16 v[96:111], v[150:153], v[130:133], v[96:111]
	v_add_u32_e32 v206, v223, v177
	v_add_u32_e32 v234, v233, v177
	ds_read_b128 v[202:205], v206 offset:16384
	ds_read_b128 v[206:209], v206 offset:18432
	ds_read_b128 v[210:213], v234
	v_mfma_f32_32x32x16_bf16 v[80:95], v[146:149], v[142:145], v[80:95]
	v_mfma_f32_32x32x16_bf16 v[64:79], v[146:149], v[130:133], v[64:79]
	ds_read_b128 v[214:217], v234 offset:2048
	v_readfirstlane_b32 s11, v222
	s_mov_b32 m0, s11
	s_nop 0
	global_load_lds_dwordx4 v[170:171], off
	v_mfma_f32_32x32x16_bf16 v[48:63], v[138:141], v[142:145], v[48:63]
	v_mfma_f32_32x32x16_bf16 v[32:47], v[138:141], v[130:133], v[32:47]
	ds_read_b128 v[224:227], v234 offset:4096
	s_add_i32 s12, s11, 0x2000
	v_lshl_add_u64 v[150:151], v[170:171], 0, s[34:35]
	s_mov_b32 m0, s12
	s_nop 0
	global_load_lds_dwordx4 v[150:151], off
	v_mfma_f32_32x32x16_bf16 v[16:31], v[134:137], v[142:145], v[16:31]
	v_mfma_f32_32x32x16_bf16 v[0:15], v[134:137], v[130:133], v[0:15]
	ds_read_b128 v[234:237], v234 offset:6144
	s_waitcnt lgkmcnt(3)
	v_mfma_f32_32x32x16_bf16 v[112:127], v[210:213], v[202:205], v[112:127]
	v_add_u32_e32 v130, v223, v178
	v_add_u32_e32 v134, v233, v178
	ds_read_b128 v[142:145], v130 offset:16384
	v_mfma_f32_32x32x16_bf16 v[96:111], v[210:213], v[206:209], v[96:111]
	ds_read_b128 v[130:133], v130 offset:18432
	s_add_i32 s12, s11, 0x6000
	s_addk_i32 s11, 0x4000
	s_mov_b32 m0, s11
	s_nop 0
	global_load_lds_dwordx4 v[172:173], off
	s_waitcnt lgkmcnt(4)
	v_mfma_f32_32x32x16_bf16 v[80:95], v[214:217], v[202:205], v[80:95]
	ds_read_b128 v[150:153], v134
	v_mfma_f32_32x32x16_bf16 v[64:79], v[214:217], v[206:209], v[64:79]
	ds_read_b128 v[146:149], v134 offset:2048
	s_waitcnt lgkmcnt(5)
	v_mfma_f32_32x32x16_bf16 v[48:63], v[224:227], v[202:205], v[48:63]
	ds_read_b128 v[138:141], v134 offset:4096
	v_mfma_f32_32x32x16_bf16 v[32:47], v[224:227], v[206:209], v[32:47]
	ds_read_b128 v[134:137], v134 offset:6144
	v_lshl_add_u64 v[222:223], v[172:173], 0, s[34:35]
	s_mov_b32 m0, s12
	s_nop 0
	global_load_lds_dwordx4 v[222:223], off
	s_waitcnt lgkmcnt(6)
	v_mfma_f32_32x32x16_bf16 v[16:31], v[234:237], v[202:205], v[16:31]
	s_add_i32 s10, s10, 0x8000
	v_lshl_add_u64 v[170:171], v[170:171], 0, 64
	v_lshl_add_u64 v[172:173], v[172:173], 0, 64
	s_cmp_eq_u32 s10, 0x100000
	v_mfma_f32_32x32x16_bf16 v[0:15], v[234:237], v[206:209], v[0:15]
	s_cbranch_scc0 .LBB0_263
	s_waitcnt vmcnt(8) lgkmcnt(0)
	s_barrier
	v_add_u32_e32 v202, v179, v177
	v_add_u32_e32 v222, v176, v177
	ds_read_b128 v[170:173], v202 offset:49152
	ds_read_b128 v[202:205], v202 offset:51200
	ds_read_b128 v[206:209], v222 offset:32768
	ds_read_b128 v[210:213], v222 offset:34816
	ds_read_b128 v[214:217], v222 offset:36864
	ds_read_b128 v[224:227], v222 offset:38912
	s_waitcnt lgkmcnt(9)
	v_mfma_f32_32x32x16_bf16 v[112:127], v[150:153], v[142:145], v[112:127]
	v_mfma_f32_32x32x16_bf16 v[96:111], v[150:153], v[130:133], v[96:111]
	s_waitcnt lgkmcnt(8)
	v_mfma_f32_32x32x16_bf16 v[80:95], v[146:149], v[142:145], v[80:95]
	v_mfma_f32_32x32x16_bf16 v[64:79], v[146:149], v[130:133], v[64:79]
	s_waitcnt lgkmcnt(7)
	v_mfma_f32_32x32x16_bf16 v[48:63], v[138:141], v[142:145], v[48:63]
	v_mfma_f32_32x32x16_bf16 v[32:47], v[138:141], v[130:133], v[32:47]
	s_waitcnt lgkmcnt(6)
	v_mfma_f32_32x32x16_bf16 v[16:31], v[134:137], v[142:145], v[16:31]
	v_mfma_f32_32x32x16_bf16 v[0:15], v[134:137], v[130:133], v[0:15]
	v_add_u32_e32 v134, v179, v178
	v_add_u32_e32 v150, v176, v178
	ds_read_b128 v[130:133], v134 offset:49152
	ds_read_b128 v[134:137], v134 offset:51200
	ds_read_b128 v[138:141], v150 offset:32768
	ds_read_b128 v[142:145], v150 offset:34816
	ds_read_b128 v[146:149], v150 offset:36864
	ds_read_b128 v[150:153], v150 offset:38912
	s_waitcnt lgkmcnt(9)
	v_mfma_f32_32x32x16_bf16 v[112:127], v[206:209], v[170:173], v[112:127]
	v_mfma_f32_32x32x16_bf16 v[96:111], v[206:209], v[202:205], v[96:111]
	s_waitcnt lgkmcnt(8)
	v_mfma_f32_32x32x16_bf16 v[80:95], v[210:213], v[170:173], v[80:95]
	v_mfma_f32_32x32x16_bf16 v[64:79], v[210:213], v[202:205], v[64:79]
	s_waitcnt lgkmcnt(7)
	v_mfma_f32_32x32x16_bf16 v[48:63], v[214:217], v[170:173], v[48:63]
	v_mfma_f32_32x32x16_bf16 v[32:47], v[214:217], v[202:205], v[32:47]
	s_waitcnt lgkmcnt(6)
	v_mfma_f32_32x32x16_bf16 v[0:15], v[224:227], v[202:205], v[0:15]
	s_waitcnt vmcnt(4) lgkmcnt(0)
	s_barrier
	v_add_u32_e32 v202, v199, v177
	v_add_u32_e32 v222, v200, v177
	v_mfma_f32_32x32x16_bf16 v[16:31], v[224:227], v[170:173], v[16:31]
	ds_read_b128 v[170:173], v202 offset:16384
	ds_read_b128 v[202:205], v202 offset:18432
	ds_read_b128 v[206:209], v222
	ds_read_b128 v[210:213], v222 offset:2048
	ds_read_b128 v[214:217], v222 offset:4096
	ds_read_b128 v[224:227], v222 offset:6144
	s_waitcnt lgkmcnt(9)
	v_mfma_f32_32x32x16_bf16 v[112:127], v[138:141], v[130:133], v[112:127]
	v_mfma_f32_32x32x16_bf16 v[96:111], v[138:141], v[134:137], v[96:111]
	s_waitcnt lgkmcnt(8)
	v_mfma_f32_32x32x16_bf16 v[80:95], v[142:145], v[130:133], v[80:95]
	v_mfma_f32_32x32x16_bf16 v[64:79], v[142:145], v[134:137], v[64:79]
	s_waitcnt lgkmcnt(7)
	v_mfma_f32_32x32x16_bf16 v[48:63], v[146:149], v[130:133], v[48:63]
	v_mfma_f32_32x32x16_bf16 v[32:47], v[146:149], v[134:137], v[32:47]
	s_waitcnt lgkmcnt(6)
	v_mfma_f32_32x32x16_bf16 v[16:31], v[150:153], v[130:133], v[16:31]
	v_mfma_f32_32x32x16_bf16 v[0:15], v[150:153], v[134:137], v[0:15]
	v_add_u32_e32 v134, v199, v178
	v_add_u32_e32 v150, v200, v178
	ds_read_b128 v[130:133], v134 offset:16384
	ds_read_b128 v[134:137], v134 offset:18432
	ds_read_b128 v[138:141], v150
	ds_read_b128 v[142:145], v150 offset:2048
	ds_read_b128 v[146:149], v150 offset:4096
	ds_read_b128 v[150:153], v150 offset:6144
	s_waitcnt lgkmcnt(9)
	v_mfma_f32_32x32x16_bf16 v[112:127], v[206:209], v[170:173], v[112:127]
	v_mfma_f32_32x32x16_bf16 v[96:111], v[206:209], v[202:205], v[96:111]
	s_waitcnt lgkmcnt(8)
	v_mfma_f32_32x32x16_bf16 v[80:95], v[210:213], v[170:173], v[80:95]
	v_mfma_f32_32x32x16_bf16 v[64:79], v[210:213], v[202:205], v[64:79]
	s_waitcnt lgkmcnt(7)
	v_mfma_f32_32x32x16_bf16 v[48:63], v[214:217], v[170:173], v[48:63]
	v_mfma_f32_32x32x16_bf16 v[32:47], v[214:217], v[202:205], v[32:47]
	s_waitcnt lgkmcnt(6)
	v_mfma_f32_32x32x16_bf16 v[0:15], v[224:227], v[202:205], v[0:15]
	s_waitcnt vmcnt(0) lgkmcnt(0)
	s_barrier
	v_add_u32_e32 v202, v197, v177
	v_add_u32_e32 v222, v198, v177
	v_mfma_f32_32x32x16_bf16 v[16:31], v[224:227], v[170:173], v[16:31]
	ds_read_b128 v[170:173], v202 offset:16384
	ds_read_b128 v[202:205], v202 offset:18432
	ds_read_b128 v[206:209], v222
	ds_read_b128 v[210:213], v222 offset:2048
	ds_read_b128 v[214:217], v222 offset:4096
	ds_read_b128 v[224:227], v222 offset:6144
	s_waitcnt lgkmcnt(9)
	v_mfma_f32_32x32x16_bf16 v[112:127], v[138:141], v[130:133], v[112:127]
	v_mfma_f32_32x32x16_bf16 v[96:111], v[138:141], v[134:137], v[96:111]
	s_waitcnt lgkmcnt(8)
	v_mfma_f32_32x32x16_bf16 v[80:95], v[142:145], v[130:133], v[80:95]
	v_mfma_f32_32x32x16_bf16 v[64:79], v[142:145], v[134:137], v[64:79]
	s_waitcnt lgkmcnt(7)
	v_mfma_f32_32x32x16_bf16 v[48:63], v[146:149], v[130:133], v[48:63]
	v_mfma_f32_32x32x16_bf16 v[32:47], v[146:149], v[134:137], v[32:47]
	s_waitcnt lgkmcnt(6)
	v_mfma_f32_32x32x16_bf16 v[16:31], v[150:153], v[130:133], v[16:31]
	v_mfma_f32_32x32x16_bf16 v[0:15], v[150:153], v[134:137], v[0:15]
	v_add_u32_e32 v134, v197, v178
	v_add_u32_e32 v150, v198, v178
	ds_read_b128 v[130:133], v134 offset:16384
	ds_read_b128 v[134:137], v134 offset:18432
	ds_read_b128 v[138:141], v150
	ds_read_b128 v[142:145], v150 offset:2048
	ds_read_b128 v[146:149], v150 offset:4096
	ds_read_b128 v[150:153], v150 offset:6144
	s_waitcnt lgkmcnt(9)
	v_mfma_f32_32x32x16_bf16 v[112:127], v[206:209], v[170:173], v[112:127]
	v_mfma_f32_32x32x16_bf16 v[96:111], v[206:209], v[202:205], v[96:111]
	s_waitcnt lgkmcnt(8)
	v_mfma_f32_32x32x16_bf16 v[80:95], v[210:213], v[170:173], v[80:95]
	v_mfma_f32_32x32x16_bf16 v[64:79], v[210:213], v[202:205], v[64:79]
	s_waitcnt lgkmcnt(7)
	v_mfma_f32_32x32x16_bf16 v[48:63], v[214:217], v[170:173], v[48:63]
	v_mfma_f32_32x32x16_bf16 v[32:47], v[214:217], v[202:205], v[32:47]
	s_waitcnt lgkmcnt(6)
	v_mfma_f32_32x32x16_bf16 v[16:31], v[224:227], v[170:173], v[16:31]
	v_mfma_f32_32x32x16_bf16 v[0:15], v[224:227], v[202:205], v[0:15]
	s_waitcnt lgkmcnt(3)
	v_mfma_f32_32x32x16_bf16 v[112:127], v[138:141], v[130:133], v[112:127]
	v_mfma_f32_32x32x16_bf16 v[96:111], v[138:141], v[134:137], v[96:111]
	s_nop 10
	v_cvt_pk_bf16_f32 v112, v112, s0
	s_waitcnt lgkmcnt(2)
	v_mfma_f32_32x32x16_bf16 v[80:95], v[142:145], v[130:133], v[80:95]
	v_cvt_pk_bf16_f32 v96, v96, s0
	v_cvt_pk_bf16_f32 v98, v98, s0
	s_waitcnt lgkmcnt(1)
	v_mfma_f32_32x32x16_bf16 v[48:63], v[146:149], v[130:133], v[48:63]
	s_nop 7
	v_cvt_pk_bf16_f32 v80, v80, s0
	s_waitcnt lgkmcnt(0)
	v_mfma_f32_32x32x16_bf16 v[16:31], v[150:153], v[130:133], v[16:31]
	v_add_u32_e32 v132, s5, v128
	v_or_b32_e32 v130, s7, v174
	v_ashrrev_i32_e32 v131, 31, v130
	v_lshl_add_u64 v[130:131], v[130:131], 1, v[158:159]
	v_cvt_pk_bf16_f32 v48, v48, s0
	v_readlane_b32 s5, v252, 7
	s_add_i32 s6, s6, s5
	v_mfma_f32_32x32x16_bf16 v[64:79], v[142:145], v[134:137], v[64:79]
	s_nop 3
	v_cvt_pk_bf16_f32 v16, v16, s0
	s_add_i32 s2, s2, s5
	v_readlane_b32 s5, v252, 8
	s_add_i32 s4, s4, s5
	s_cmp_gt_i32 s6, 31
	s_nop 2
	v_cvt_pk_bf16_f32 v64, v64, s0
	v_mfma_f32_32x32x16_bf16 v[32:47], v[146:149], v[134:137], v[32:47]
	v_cvt_pk_bf16_f32 v66, v66, s0
	v_mfma_f32_32x32x16_bf16 v[0:15], v[150:153], v[134:137], v[0:15]
	v_or_b32_e32 v134, v132, v181
	v_ashrrev_i32_e32 v135, 31, v134
	v_lshlrev_b64 v[134:135], 11, v[134:135]
	v_lshl_add_u64 v[134:135], v[130:131], 0, v[134:135]
	global_store_short v[134:135], v112, off
	global_store_short v[134:135], v96, off offset:64
	v_or_b32_e32 v134, v132, v182
	v_ashrrev_i32_e32 v135, 31, v134
	v_lshlrev_b64 v[134:135], 11, v[134:135]
	v_lshl_add_u64 v[134:135], v[130:131], 0, v[134:135]
	v_cvt_pk_bf16_f32 v96, v113, s0
	global_store_short v[134:135], v96, off
	v_cvt_pk_bf16_f32 v96, v97, s0
	global_store_short v[134:135], v96, off offset:64
	v_or_b32_e32 v96, v132, v183
	v_ashrrev_i32_e32 v97, 31, v96
	v_lshlrev_b64 v[96:97], 11, v[96:97]
	v_lshl_add_u64 v[96:97], v[130:131], 0, v[96:97]
	v_cvt_pk_bf16_f32 v112, v114, s0
	global_store_short v[96:97], v112, off
	global_store_short v[96:97], v98, off offset:64
	v_or_b32_e32 v96, v132, v184
	v_ashrrev_i32_e32 v97, 31, v96
	v_lshlrev_b64 v[96:97], 11, v[96:97]
	v_lshl_add_u64 v[96:97], v[130:131], 0, v[96:97]
	v_cvt_pk_bf16_f32 v98, v115, s0
	global_store_short v[96:97], v98, off
	v_cvt_pk_bf16_f32 v98, v99, s0
	global_store_short v[96:97], v98, off offset:64
	v_or_b32_e32 v96, v132, v185
	v_ashrrev_i32_e32 v97, 31, v96
	v_lshlrev_b64 v[96:97], 11, v[96:97]
	v_lshl_add_u64 v[96:97], v[130:131], 0, v[96:97]
	v_cvt_pk_bf16_f32 v98, v116, s0
	global_store_short v[96:97], v98, off
	v_cvt_pk_bf16_f32 v98, v100, s0
	global_store_short v[96:97], v98, off offset:64
	v_or_b32_e32 v96, v132, v186
	v_ashrrev_i32_e32 v97, 31, v96
	v_lshlrev_b64 v[96:97], 11, v[96:97]
	v_lshl_add_u64 v[96:97], v[130:131], 0, v[96:97]
	v_cvt_pk_bf16_f32 v98, v117, s0
	global_store_short v[96:97], v98, off
	v_cvt_pk_bf16_f32 v98, v101, s0
	global_store_short v[96:97], v98, off offset:64
	v_or_b32_e32 v96, v132, v187
	v_ashrrev_i32_e32 v97, 31, v96
	v_lshlrev_b64 v[96:97], 11, v[96:97]
	v_lshl_add_u64 v[96:97], v[130:131], 0, v[96:97]
	v_cvt_pk_bf16_f32 v98, v118, s0
	global_store_short v[96:97], v98, off
	v_cvt_pk_bf16_f32 v98, v102, s0
	global_store_short v[96:97], v98, off offset:64
	v_or_b32_e32 v96, v132, v188
	v_ashrrev_i32_e32 v97, 31, v96
	v_lshlrev_b64 v[96:97], 11, v[96:97]
	v_lshl_add_u64 v[96:97], v[130:131], 0, v[96:97]
	v_cvt_pk_bf16_f32 v98, v119, s0
	global_store_short v[96:97], v98, off
	v_cvt_pk_bf16_f32 v98, v103, s0
	global_store_short v[96:97], v98, off offset:64
	v_or_b32_e32 v96, v132, v189
	v_ashrrev_i32_e32 v97, 31, v96
	v_lshlrev_b64 v[96:97], 11, v[96:97]
	v_lshl_add_u64 v[96:97], v[130:131], 0, v[96:97]
	v_cvt_pk_bf16_f32 v98, v120, s0
	global_store_short v[96:97], v98, off
	v_cvt_pk_bf16_f32 v98, v104, s0
	global_store_short v[96:97], v98, off offset:64
	v_or_b32_e32 v96, v132, v190
	v_ashrrev_i32_e32 v97, 31, v96
	v_lshlrev_b64 v[96:97], 11, v[96:97]
	v_lshl_add_u64 v[96:97], v[130:131], 0, v[96:97]
	v_cvt_pk_bf16_f32 v98, v121, s0
	global_store_short v[96:97], v98, off
	v_cvt_pk_bf16_f32 v98, v105, s0
	global_store_short v[96:97], v98, off offset:64
	v_or_b32_e32 v96, v132, v191
	v_ashrrev_i32_e32 v97, 31, v96
	v_lshlrev_b64 v[96:97], 11, v[96:97]
	v_lshl_add_u64 v[96:97], v[130:131], 0, v[96:97]
	v_cvt_pk_bf16_f32 v98, v122, s0
	global_store_short v[96:97], v98, off
	v_cvt_pk_bf16_f32 v98, v106, s0
	global_store_short v[96:97], v98, off offset:64
	v_or_b32_e32 v96, v132, v192
	v_ashrrev_i32_e32 v97, 31, v96
	v_lshlrev_b64 v[96:97], 11, v[96:97]
	v_lshl_add_u64 v[96:97], v[130:131], 0, v[96:97]
	v_cvt_pk_bf16_f32 v98, v123, s0
	global_store_short v[96:97], v98, off
	v_cvt_pk_bf16_f32 v98, v107, s0
	global_store_short v[96:97], v98, off offset:64
	v_or_b32_e32 v96, v132, v193
	v_ashrrev_i32_e32 v97, 31, v96
	v_lshlrev_b64 v[96:97], 11, v[96:97]
	v_lshl_add_u64 v[96:97], v[130:131], 0, v[96:97]
	v_cvt_pk_bf16_f32 v98, v124, s0
	global_store_short v[96:97], v98, off
	v_cvt_pk_bf16_f32 v98, v108, s0
	global_store_short v[96:97], v98, off offset:64
	v_or_b32_e32 v96, v132, v194
	v_ashrrev_i32_e32 v97, 31, v96
	v_lshlrev_b64 v[96:97], 11, v[96:97]
	v_lshl_add_u64 v[96:97], v[130:131], 0, v[96:97]
	v_cvt_pk_bf16_f32 v98, v125, s0
	global_store_short v[96:97], v98, off
	v_cvt_pk_bf16_f32 v98, v109, s0
	global_store_short v[96:97], v98, off offset:64
	v_or_b32_e32 v96, v132, v195
	v_ashrrev_i32_e32 v97, 31, v96
	v_lshlrev_b64 v[96:97], 11, v[96:97]
	v_lshl_add_u64 v[96:97], v[130:131], 0, v[96:97]
	v_cvt_pk_bf16_f32 v98, v126, s0
	global_store_short v[96:97], v98, off
	v_cvt_pk_bf16_f32 v98, v110, s0
	global_store_short v[96:97], v98, off offset:64
	v_or_b32_e32 v96, v132, v196
	v_ashrrev_i32_e32 v97, 31, v96
	v_lshlrev_b64 v[96:97], 11, v[96:97]
	v_lshl_add_u64 v[96:97], v[130:131], 0, v[96:97]
	v_cvt_pk_bf16_f32 v98, v127, s0
	global_store_short v[96:97], v98, off
	v_cvt_pk_bf16_f32 v98, v111, s0
	global_store_short v[96:97], v98, off offset:64
	v_or_b32_e32 v98, 32, v132
	v_or_b32_e32 v96, v98, v181
	v_ashrrev_i32_e32 v97, 31, v96
	v_lshlrev_b64 v[96:97], 11, v[96:97]
	v_lshl_add_u64 v[96:97], v[130:131], 0, v[96:97]
	global_store_short v[96:97], v80, off
	global_store_short v[96:97], v64, off offset:64
	v_or_b32_e32 v96, v98, v182
	v_ashrrev_i32_e32 v97, 31, v96
	v_lshlrev_b64 v[96:97], 11, v[96:97]
	v_lshl_add_u64 v[96:97], v[130:131], 0, v[96:97]
	v_cvt_pk_bf16_f32 v64, v81, s0
	global_store_short v[96:97], v64, off
	v_cvt_pk_bf16_f32 v64, v65, s0
	global_store_short v[96:97], v64, off offset:64
	v_or_b32_e32 v64, v98, v183
	v_ashrrev_i32_e32 v65, 31, v64
	v_lshlrev_b64 v[64:65], 11, v[64:65]
	v_lshl_add_u64 v[64:65], v[130:131], 0, v[64:65]
	v_cvt_pk_bf16_f32 v80, v82, s0
	global_store_short v[64:65], v80, off
	global_store_short v[64:65], v66, off offset:64
	v_or_b32_e32 v64, v98, v184
	v_ashrrev_i32_e32 v65, 31, v64
	v_lshlrev_b64 v[64:65], 11, v[64:65]
	v_lshl_add_u64 v[64:65], v[130:131], 0, v[64:65]
	v_cvt_pk_bf16_f32 v66, v83, s0
	global_store_short v[64:65], v66, off
	v_cvt_pk_bf16_f32 v66, v67, s0
	global_store_short v[64:65], v66, off offset:64
	v_or_b32_e32 v64, v98, v185
	v_ashrrev_i32_e32 v65, 31, v64
	v_lshlrev_b64 v[64:65], 11, v[64:65]
	v_lshl_add_u64 v[64:65], v[130:131], 0, v[64:65]
	v_cvt_pk_bf16_f32 v66, v84, s0
	global_store_short v[64:65], v66, off
	v_cvt_pk_bf16_f32 v66, v68, s0
	global_store_short v[64:65], v66, off offset:64
	v_or_b32_e32 v64, v98, v186
	v_ashrrev_i32_e32 v65, 31, v64
	v_lshlrev_b64 v[64:65], 11, v[64:65]
	v_lshl_add_u64 v[64:65], v[130:131], 0, v[64:65]
	v_cvt_pk_bf16_f32 v66, v85, s0
	global_store_short v[64:65], v66, off
	v_cvt_pk_bf16_f32 v66, v69, s0
	global_store_short v[64:65], v66, off offset:64
	v_or_b32_e32 v64, v98, v187
	v_ashrrev_i32_e32 v65, 31, v64
	v_lshlrev_b64 v[64:65], 11, v[64:65]
	v_lshl_add_u64 v[64:65], v[130:131], 0, v[64:65]
	v_cvt_pk_bf16_f32 v66, v86, s0
	global_store_short v[64:65], v66, off
	v_cvt_pk_bf16_f32 v66, v70, s0
	global_store_short v[64:65], v66, off offset:64
	v_or_b32_e32 v64, v98, v188
	v_ashrrev_i32_e32 v65, 31, v64
	v_lshlrev_b64 v[64:65], 11, v[64:65]
	v_lshl_add_u64 v[64:65], v[130:131], 0, v[64:65]
	v_cvt_pk_bf16_f32 v66, v87, s0
	global_store_short v[64:65], v66, off
	v_cvt_pk_bf16_f32 v66, v71, s0
	global_store_short v[64:65], v66, off offset:64
	v_or_b32_e32 v64, v98, v189
	v_ashrrev_i32_e32 v65, 31, v64
	v_lshlrev_b64 v[64:65], 11, v[64:65]
	v_lshl_add_u64 v[64:65], v[130:131], 0, v[64:65]
	v_cvt_pk_bf16_f32 v66, v88, s0
	global_store_short v[64:65], v66, off
	v_cvt_pk_bf16_f32 v66, v72, s0
	global_store_short v[64:65], v66, off offset:64
	v_or_b32_e32 v64, v98, v190
	v_ashrrev_i32_e32 v65, 31, v64
	v_lshlrev_b64 v[64:65], 11, v[64:65]
	v_lshl_add_u64 v[64:65], v[130:131], 0, v[64:65]
	v_cvt_pk_bf16_f32 v66, v89, s0
	global_store_short v[64:65], v66, off
	v_cvt_pk_bf16_f32 v66, v73, s0
	global_store_short v[64:65], v66, off offset:64
	v_or_b32_e32 v64, v98, v191
	v_ashrrev_i32_e32 v65, 31, v64
	v_lshlrev_b64 v[64:65], 11, v[64:65]
	v_lshl_add_u64 v[64:65], v[130:131], 0, v[64:65]
	v_cvt_pk_bf16_f32 v66, v90, s0
	global_store_short v[64:65], v66, off
	v_cvt_pk_bf16_f32 v66, v74, s0
	global_store_short v[64:65], v66, off offset:64
	v_or_b32_e32 v64, v98, v192
	v_ashrrev_i32_e32 v65, 31, v64
	v_lshlrev_b64 v[64:65], 11, v[64:65]
	v_lshl_add_u64 v[64:65], v[130:131], 0, v[64:65]
	v_cvt_pk_bf16_f32 v66, v91, s0
	global_store_short v[64:65], v66, off
	v_cvt_pk_bf16_f32 v66, v75, s0
	global_store_short v[64:65], v66, off offset:64
	v_or_b32_e32 v64, v98, v193
	v_ashrrev_i32_e32 v65, 31, v64
	v_lshlrev_b64 v[64:65], 11, v[64:65]
	v_lshl_add_u64 v[64:65], v[130:131], 0, v[64:65]
	v_cvt_pk_bf16_f32 v66, v92, s0
	global_store_short v[64:65], v66, off
	v_cvt_pk_bf16_f32 v66, v76, s0
	global_store_short v[64:65], v66, off offset:64
	v_or_b32_e32 v64, v98, v194
	v_ashrrev_i32_e32 v65, 31, v64
	v_lshlrev_b64 v[64:65], 11, v[64:65]
	v_lshl_add_u64 v[64:65], v[130:131], 0, v[64:65]
	v_cvt_pk_bf16_f32 v66, v93, s0
	global_store_short v[64:65], v66, off
	v_cvt_pk_bf16_f32 v66, v77, s0
	global_store_short v[64:65], v66, off offset:64
	v_or_b32_e32 v64, v98, v195
	v_ashrrev_i32_e32 v65, 31, v64
	v_lshlrev_b64 v[64:65], 11, v[64:65]
	v_lshl_add_u64 v[64:65], v[130:131], 0, v[64:65]
	v_cvt_pk_bf16_f32 v66, v94, s0
	global_store_short v[64:65], v66, off
	v_cvt_pk_bf16_f32 v66, v78, s0
	global_store_short v[64:65], v66, off offset:64
	v_or_b32_e32 v64, v98, v196
	v_ashrrev_i32_e32 v65, 31, v64
	v_lshlrev_b64 v[64:65], 11, v[64:65]
	v_lshl_add_u64 v[64:65], v[130:131], 0, v[64:65]
	v_cvt_pk_bf16_f32 v66, v95, s0
	global_store_short v[64:65], v66, off
	v_cvt_pk_bf16_f32 v66, v79, s0
	global_store_short v[64:65], v66, off offset:64
	v_or_b32_e32 v66, 64, v132
	v_or_b32_e32 v64, v66, v181
	v_ashrrev_i32_e32 v65, 31, v64
	v_lshlrev_b64 v[64:65], 11, v[64:65]
	v_lshl_add_u64 v[64:65], v[130:131], 0, v[64:65]
	v_cvt_pk_bf16_f32 v32, v32, s0
	global_store_short v[64:65], v48, off
	global_store_short v[64:65], v32, off offset:64
	v_or_b32_e32 v64, v66, v182
	v_ashrrev_i32_e32 v65, 31, v64
	v_lshlrev_b64 v[64:65], 11, v[64:65]
	v_lshl_add_u64 v[64:65], v[130:131], 0, v[64:65]
	v_cvt_pk_bf16_f32 v32, v49, s0
	global_store_short v[64:65], v32, off
	v_cvt_pk_bf16_f32 v32, v33, s0
	global_store_short v[64:65], v32, off offset:64
	v_or_b32_e32 v32, v66, v183
	v_ashrrev_i32_e32 v33, 31, v32
	v_lshlrev_b64 v[32:33], 11, v[32:33]
	v_lshl_add_u64 v[32:33], v[130:131], 0, v[32:33]
	v_cvt_pk_bf16_f32 v48, v50, s0
	v_cvt_pk_bf16_f32 v34, v34, s0
	global_store_short v[32:33], v48, off
	global_store_short v[32:33], v34, off offset:64
	v_or_b32_e32 v32, v66, v184
	v_ashrrev_i32_e32 v33, 31, v32
	v_lshlrev_b64 v[32:33], 11, v[32:33]
	v_lshl_add_u64 v[32:33], v[130:131], 0, v[32:33]
	v_cvt_pk_bf16_f32 v34, v51, s0
	global_store_short v[32:33], v34, off
	v_cvt_pk_bf16_f32 v34, v35, s0
	global_store_short v[32:33], v34, off offset:64
	v_or_b32_e32 v32, v66, v185
	v_ashrrev_i32_e32 v33, 31, v32
	v_lshlrev_b64 v[32:33], 11, v[32:33]
	v_lshl_add_u64 v[32:33], v[130:131], 0, v[32:33]
	v_cvt_pk_bf16_f32 v34, v52, s0
	global_store_short v[32:33], v34, off
	v_cvt_pk_bf16_f32 v34, v36, s0
	global_store_short v[32:33], v34, off offset:64
	v_or_b32_e32 v32, v66, v186
	v_ashrrev_i32_e32 v33, 31, v32
	v_lshlrev_b64 v[32:33], 11, v[32:33]
	v_lshl_add_u64 v[32:33], v[130:131], 0, v[32:33]
	v_cvt_pk_bf16_f32 v34, v53, s0
	global_store_short v[32:33], v34, off
	v_cvt_pk_bf16_f32 v34, v37, s0
	global_store_short v[32:33], v34, off offset:64
	v_or_b32_e32 v32, v66, v187
	v_ashrrev_i32_e32 v33, 31, v32
	v_lshlrev_b64 v[32:33], 11, v[32:33]
	v_lshl_add_u64 v[32:33], v[130:131], 0, v[32:33]
	v_cvt_pk_bf16_f32 v34, v54, s0
	global_store_short v[32:33], v34, off
	v_cvt_pk_bf16_f32 v34, v38, s0
	global_store_short v[32:33], v34, off offset:64
	v_or_b32_e32 v32, v66, v188
	v_ashrrev_i32_e32 v33, 31, v32
	v_lshlrev_b64 v[32:33], 11, v[32:33]
	v_lshl_add_u64 v[32:33], v[130:131], 0, v[32:33]
	v_cvt_pk_bf16_f32 v34, v55, s0
	global_store_short v[32:33], v34, off
	v_cvt_pk_bf16_f32 v34, v39, s0
	global_store_short v[32:33], v34, off offset:64
	v_or_b32_e32 v32, v66, v189
	v_ashrrev_i32_e32 v33, 31, v32
	v_lshlrev_b64 v[32:33], 11, v[32:33]
	v_lshl_add_u64 v[32:33], v[130:131], 0, v[32:33]
	v_cvt_pk_bf16_f32 v34, v56, s0
	global_store_short v[32:33], v34, off
	v_cvt_pk_bf16_f32 v34, v40, s0
	global_store_short v[32:33], v34, off offset:64
	v_or_b32_e32 v32, v66, v190
	v_ashrrev_i32_e32 v33, 31, v32
	v_lshlrev_b64 v[32:33], 11, v[32:33]
	v_lshl_add_u64 v[32:33], v[130:131], 0, v[32:33]
	v_cvt_pk_bf16_f32 v34, v57, s0
	global_store_short v[32:33], v34, off
	v_cvt_pk_bf16_f32 v34, v41, s0
	global_store_short v[32:33], v34, off offset:64
	v_or_b32_e32 v32, v66, v191
	v_ashrrev_i32_e32 v33, 31, v32
	v_lshlrev_b64 v[32:33], 11, v[32:33]
	v_lshl_add_u64 v[32:33], v[130:131], 0, v[32:33]
	v_cvt_pk_bf16_f32 v34, v58, s0
	global_store_short v[32:33], v34, off
	v_cvt_pk_bf16_f32 v34, v42, s0
	global_store_short v[32:33], v34, off offset:64
	v_or_b32_e32 v32, v66, v192
	v_ashrrev_i32_e32 v33, 31, v32
	v_lshlrev_b64 v[32:33], 11, v[32:33]
	v_lshl_add_u64 v[32:33], v[130:131], 0, v[32:33]
	v_cvt_pk_bf16_f32 v34, v59, s0
	global_store_short v[32:33], v34, off
	v_cvt_pk_bf16_f32 v34, v43, s0
	global_store_short v[32:33], v34, off offset:64
	v_or_b32_e32 v32, v66, v193
	v_ashrrev_i32_e32 v33, 31, v32
	v_lshlrev_b64 v[32:33], 11, v[32:33]
	v_lshl_add_u64 v[32:33], v[130:131], 0, v[32:33]
	v_cvt_pk_bf16_f32 v34, v60, s0
	global_store_short v[32:33], v34, off
	v_cvt_pk_bf16_f32 v34, v44, s0
	global_store_short v[32:33], v34, off offset:64
	v_or_b32_e32 v32, v66, v194
	v_ashrrev_i32_e32 v33, 31, v32
	v_lshlrev_b64 v[32:33], 11, v[32:33]
	v_lshl_add_u64 v[32:33], v[130:131], 0, v[32:33]
	v_cvt_pk_bf16_f32 v34, v61, s0
	global_store_short v[32:33], v34, off
	v_cvt_pk_bf16_f32 v34, v45, s0
	global_store_short v[32:33], v34, off offset:64
	v_or_b32_e32 v32, v66, v195
	v_ashrrev_i32_e32 v33, 31, v32
	v_lshlrev_b64 v[32:33], 11, v[32:33]
	v_lshl_add_u64 v[32:33], v[130:131], 0, v[32:33]
	v_cvt_pk_bf16_f32 v34, v62, s0
	global_store_short v[32:33], v34, off
	v_cvt_pk_bf16_f32 v34, v46, s0
	global_store_short v[32:33], v34, off offset:64
	v_or_b32_e32 v32, v66, v196
	v_ashrrev_i32_e32 v33, 31, v32
	v_lshlrev_b64 v[32:33], 11, v[32:33]
	v_lshl_add_u64 v[32:33], v[130:131], 0, v[32:33]
	v_cvt_pk_bf16_f32 v34, v63, s0
	global_store_short v[32:33], v34, off
	v_cvt_pk_bf16_f32 v34, v47, s0
	global_store_short v[32:33], v34, off offset:64
	v_or_b32_e32 v34, 0x60, v132
	v_or_b32_e32 v32, v34, v181
	v_ashrrev_i32_e32 v33, 31, v32
	v_lshlrev_b64 v[32:33], 11, v[32:33]
	v_lshl_add_u64 v[32:33], v[130:131], 0, v[32:33]
	v_cvt_pk_bf16_f32 v0, v0, s0
	global_store_short v[32:33], v16, off
	global_store_short v[32:33], v0, off offset:64
	v_or_b32_e32 v32, v34, v182
	v_ashrrev_i32_e32 v33, 31, v32
	v_lshlrev_b64 v[32:33], 11, v[32:33]
	v_lshl_add_u64 v[32:33], v[130:131], 0, v[32:33]
	v_cvt_pk_bf16_f32 v0, v17, s0
	global_store_short v[32:33], v0, off
	v_cvt_pk_bf16_f32 v0, v1, s0
	global_store_short v[32:33], v0, off offset:64
	v_or_b32_e32 v0, v34, v183
	v_ashrrev_i32_e32 v1, 31, v0
	v_lshlrev_b64 v[0:1], 11, v[0:1]
	v_lshl_add_u64 v[0:1], v[130:131], 0, v[0:1]
	v_cvt_pk_bf16_f32 v16, v18, s0
	v_cvt_pk_bf16_f32 v2, v2, s0
	global_store_short v[0:1], v16, off
	global_store_short v[0:1], v2, off offset:64
	v_or_b32_e32 v0, v34, v184
	v_ashrrev_i32_e32 v1, 31, v0
	v_lshlrev_b64 v[0:1], 11, v[0:1]
	v_lshl_add_u64 v[0:1], v[130:131], 0, v[0:1]
	v_cvt_pk_bf16_f32 v2, v19, s0
	global_store_short v[0:1], v2, off
	v_cvt_pk_bf16_f32 v2, v3, s0
	global_store_short v[0:1], v2, off offset:64
	v_or_b32_e32 v0, v34, v185
	v_ashrrev_i32_e32 v1, 31, v0
	v_lshlrev_b64 v[0:1], 11, v[0:1]
	v_lshl_add_u64 v[0:1], v[130:131], 0, v[0:1]
	v_cvt_pk_bf16_f32 v2, v20, s0
	global_store_short v[0:1], v2, off
	v_cvt_pk_bf16_f32 v2, v4, s0
	global_store_short v[0:1], v2, off offset:64
	v_or_b32_e32 v0, v34, v186
	v_ashrrev_i32_e32 v1, 31, v0
	v_lshlrev_b64 v[0:1], 11, v[0:1]
	v_lshl_add_u64 v[0:1], v[130:131], 0, v[0:1]
	v_cvt_pk_bf16_f32 v2, v21, s0
	global_store_short v[0:1], v2, off
	v_cvt_pk_bf16_f32 v2, v5, s0
	global_store_short v[0:1], v2, off offset:64
	v_or_b32_e32 v0, v34, v187
	v_ashrrev_i32_e32 v1, 31, v0
	v_lshlrev_b64 v[0:1], 11, v[0:1]
	v_lshl_add_u64 v[0:1], v[130:131], 0, v[0:1]
	v_cvt_pk_bf16_f32 v2, v22, s0
	global_store_short v[0:1], v2, off
	v_cvt_pk_bf16_f32 v2, v6, s0
	global_store_short v[0:1], v2, off offset:64
	v_or_b32_e32 v0, v34, v188
	v_ashrrev_i32_e32 v1, 31, v0
	v_lshlrev_b64 v[0:1], 11, v[0:1]
	v_lshl_add_u64 v[0:1], v[130:131], 0, v[0:1]
	v_cvt_pk_bf16_f32 v2, v23, s0
	global_store_short v[0:1], v2, off
	v_cvt_pk_bf16_f32 v2, v7, s0
	global_store_short v[0:1], v2, off offset:64
	v_or_b32_e32 v0, v34, v189
	v_ashrrev_i32_e32 v1, 31, v0
	v_lshlrev_b64 v[0:1], 11, v[0:1]
	v_lshl_add_u64 v[0:1], v[130:131], 0, v[0:1]
	v_cvt_pk_bf16_f32 v2, v24, s0
	global_store_short v[0:1], v2, off
	v_cvt_pk_bf16_f32 v2, v8, s0
	global_store_short v[0:1], v2, off offset:64
	v_or_b32_e32 v0, v34, v190
	v_ashrrev_i32_e32 v1, 31, v0
	v_lshlrev_b64 v[0:1], 11, v[0:1]
	v_lshl_add_u64 v[0:1], v[130:131], 0, v[0:1]
	v_cvt_pk_bf16_f32 v2, v25, s0
	global_store_short v[0:1], v2, off
	v_cvt_pk_bf16_f32 v2, v9, s0
	global_store_short v[0:1], v2, off offset:64
	v_or_b32_e32 v0, v34, v191
	v_ashrrev_i32_e32 v1, 31, v0
	v_lshlrev_b64 v[0:1], 11, v[0:1]
	v_lshl_add_u64 v[0:1], v[130:131], 0, v[0:1]
	v_cvt_pk_bf16_f32 v2, v26, s0
	global_store_short v[0:1], v2, off
	v_cvt_pk_bf16_f32 v2, v10, s0
	global_store_short v[0:1], v2, off offset:64
	v_or_b32_e32 v0, v34, v192
	v_ashrrev_i32_e32 v1, 31, v0
	v_lshlrev_b64 v[0:1], 11, v[0:1]
	v_lshl_add_u64 v[0:1], v[130:131], 0, v[0:1]
	v_cvt_pk_bf16_f32 v2, v27, s0
	global_store_short v[0:1], v2, off
	v_cvt_pk_bf16_f32 v2, v11, s0
	global_store_short v[0:1], v2, off offset:64
	v_or_b32_e32 v0, v34, v193
	v_ashrrev_i32_e32 v1, 31, v0
	v_lshlrev_b64 v[0:1], 11, v[0:1]
	v_lshl_add_u64 v[0:1], v[130:131], 0, v[0:1]
	v_cvt_pk_bf16_f32 v2, v28, s0
	global_store_short v[0:1], v2, off
	v_cvt_pk_bf16_f32 v2, v12, s0
	global_store_short v[0:1], v2, off offset:64
	v_or_b32_e32 v0, v34, v194
	v_ashrrev_i32_e32 v1, 31, v0
	v_lshlrev_b64 v[0:1], 11, v[0:1]
	v_lshl_add_u64 v[0:1], v[130:131], 0, v[0:1]
	v_cvt_pk_bf16_f32 v2, v29, s0
	global_store_short v[0:1], v2, off
	v_cvt_pk_bf16_f32 v2, v13, s0
	global_store_short v[0:1], v2, off offset:64
	v_or_b32_e32 v0, v34, v195
	v_ashrrev_i32_e32 v1, 31, v0
	v_lshlrev_b64 v[0:1], 11, v[0:1]
	v_lshl_add_u64 v[0:1], v[130:131], 0, v[0:1]
	v_cvt_pk_bf16_f32 v2, v30, s0
	global_store_short v[0:1], v2, off
	v_cvt_pk_bf16_f32 v2, v14, s0
	global_store_short v[0:1], v2, off offset:64
	v_or_b32_e32 v0, v34, v196
	v_ashrrev_i32_e32 v1, 31, v0
	v_lshlrev_b64 v[0:1], 11, v[0:1]
	v_lshl_add_u64 v[0:1], v[130:131], 0, v[0:1]
	v_cvt_pk_bf16_f32 v2, v31, s0
	global_store_short v[0:1], v2, off
	v_cvt_pk_bf16_f32 v2, v15, s0
	global_store_short v[0:1], v2, off offset:64
	s_cbranch_scc0 .LBB0_262

.LBB0_330:
	s_and_b32 s3, s2, 0x18000
	v_add_u32_e32 v128, s3, v182
	s_add_i32 s3, s2, 0xfffe8000
	s_and_b32 s3, s3, 0x18000
	v_or_b32_e32 v214, s3, v181
	v_add_u32_e32 v215, s3, v178
	s_waitcnt vmcnt(8) lgkmcnt(0)
	s_barrier
	v_mfma_f32_32x32x16_bf16 v[112:127], v[150:153], v[142:145], v[112:127]
	v_mfma_f32_32x32x16_bf16 v[96:111], v[150:153], v[130:133], v[96:111]
	v_add_u32_e32 v194, v214, v179
	v_add_u32_e32 v210, v215, v179
	ds_read_b128 v[190:193], v194 offset:16384
	ds_read_b128 v[194:197], v194 offset:18432
	ds_read_b128 v[198:201], v210
	v_mfma_f32_32x32x16_bf16 v[80:95], v[146:149], v[142:145], v[80:95]
	v_mfma_f32_32x32x16_bf16 v[64:79], v[146:149], v[130:133], v[64:79]
	ds_read_b128 v[202:205], v210 offset:2048
	v_readfirstlane_b32 s3, v128
	s_mov_b32 m0, s3
	s_nop 0
	global_load_lds_dwordx4 v[172:173], off
	v_mfma_f32_32x32x16_bf16 v[48:63], v[138:141], v[142:145], v[48:63]
	v_mfma_f32_32x32x16_bf16 v[32:47], v[138:141], v[130:133], v[32:47]
	ds_read_b128 v[206:209], v210 offset:4096
	s_add_i32 s24, s3, 0x2000
	v_lshl_add_u64 v[150:151], v[172:173], 0, s[26:27]
	s_mov_b32 m0, s24
	s_nop 0
	global_load_lds_dwordx4 v[150:151], off
	v_mfma_f32_32x32x16_bf16 v[16:31], v[134:137], v[142:145], v[16:31]
	v_mfma_f32_32x32x16_bf16 v[0:15], v[134:137], v[130:133], v[0:15]
	ds_read_b128 v[210:213], v210 offset:6144
	s_waitcnt lgkmcnt(3)
	v_mfma_f32_32x32x16_bf16 v[112:127], v[198:201], v[190:193], v[112:127]
	v_add_u32_e32 v128, v214, v180
	ds_read_b128 v[142:145], v128 offset:16384
	v_mfma_f32_32x32x16_bf16 v[96:111], v[198:201], v[194:197], v[96:111]
	ds_read_b128 v[130:133], v128 offset:18432
	s_add_i32 s24, s3, 0x6000
	s_addk_i32 s3, 0x4000
	s_mov_b32 m0, s3
	s_nop 0
	global_load_lds_dwordx4 v[174:175], off
	s_waitcnt lgkmcnt(4)
	v_mfma_f32_32x32x16_bf16 v[80:95], v[202:205], v[190:193], v[80:95]
	v_add_u32_e32 v128, v215, v180
	ds_read_b128 v[150:153], v128
	v_mfma_f32_32x32x16_bf16 v[64:79], v[202:205], v[194:197], v[64:79]
	ds_read_b128 v[146:149], v128 offset:2048
	s_waitcnt lgkmcnt(5)
	v_mfma_f32_32x32x16_bf16 v[48:63], v[206:209], v[190:193], v[48:63]
	ds_read_b128 v[138:141], v128 offset:4096
	v_mfma_f32_32x32x16_bf16 v[32:47], v[206:209], v[194:197], v[32:47]
	ds_read_b128 v[134:137], v128 offset:6144
	v_lshl_add_u64 v[214:215], v[174:175], 0, s[26:27]
	s_mov_b32 m0, s24
	s_nop 0
	global_load_lds_dwordx4 v[214:215], off
	s_waitcnt lgkmcnt(6)
	v_mfma_f32_32x32x16_bf16 v[16:31], v[210:213], v[190:193], v[16:31]
	s_add_i32 s2, s2, 0x8000
	v_lshl_add_u64 v[172:173], v[172:173], 0, 64
	v_lshl_add_u64 v[174:175], v[174:175], 0, 64
	s_cmp_eq_u32 s2, 0x100000
	v_mfma_f32_32x32x16_bf16 v[0:15], v[210:213], v[194:197], v[0:15]
	s_cbranch_scc0 .LBB0_330
	s_waitcnt vmcnt(8) lgkmcnt(0)
	s_barrier
	v_add_u32_e32 v128, v181, v179
	ds_read_b128 v[172:175], v128 offset:49152
	ds_read_b128 v[190:193], v128 offset:51200
	v_add_u32_e32 v128, v178, v179
	ds_read_b128 v[194:197], v128 offset:32768
	ds_read_b128 v[198:201], v128 offset:34816
	ds_read_b128 v[202:205], v128 offset:36864
	ds_read_b128 v[206:209], v128 offset:38912
	s_waitcnt lgkmcnt(9)
	v_mfma_f32_32x32x16_bf16 v[112:127], v[150:153], v[142:145], v[112:127]
	v_mfma_f32_32x32x16_bf16 v[96:111], v[150:153], v[130:133], v[96:111]
	s_waitcnt lgkmcnt(8)
	v_mfma_f32_32x32x16_bf16 v[80:95], v[146:149], v[142:145], v[80:95]
	v_mfma_f32_32x32x16_bf16 v[64:79], v[146:149], v[130:133], v[64:79]
	s_waitcnt lgkmcnt(7)
	v_mfma_f32_32x32x16_bf16 v[48:63], v[138:141], v[142:145], v[48:63]
	v_mfma_f32_32x32x16_bf16 v[32:47], v[138:141], v[130:133], v[32:47]
	s_waitcnt lgkmcnt(6)
	v_mfma_f32_32x32x16_bf16 v[16:31], v[134:137], v[142:145], v[16:31]
	v_mfma_f32_32x32x16_bf16 v[0:15], v[134:137], v[130:133], v[0:15]
	v_add_u32_e32 v128, v181, v180
	ds_read_b128 v[130:133], v128 offset:49152
	ds_read_b128 v[134:137], v128 offset:51200
	v_add_u32_e32 v128, v178, v180
	ds_read_b128 v[138:141], v128 offset:32768
	ds_read_b128 v[142:145], v128 offset:34816
	ds_read_b128 v[146:149], v128 offset:36864
	ds_read_b128 v[150:153], v128 offset:38912
	s_waitcnt lgkmcnt(9)
	v_mfma_f32_32x32x16_bf16 v[112:127], v[194:197], v[172:175], v[112:127]
	v_mfma_f32_32x32x16_bf16 v[96:111], v[194:197], v[190:193], v[96:111]
	s_waitcnt lgkmcnt(8)
	v_mfma_f32_32x32x16_bf16 v[80:95], v[198:201], v[172:175], v[80:95]
	v_mfma_f32_32x32x16_bf16 v[64:79], v[198:201], v[190:193], v[64:79]
	s_waitcnt lgkmcnt(7)
	v_mfma_f32_32x32x16_bf16 v[48:63], v[202:205], v[172:175], v[48:63]
	v_mfma_f32_32x32x16_bf16 v[32:47], v[202:205], v[190:193], v[32:47]
	s_waitcnt vmcnt(4) lgkmcnt(0)
	s_barrier
	v_add_u32_e32 v128, v187, v179
	s_waitcnt lgkmcnt(6)
	v_mfma_f32_32x32x16_bf16 v[16:31], v[206:209], v[172:175], v[16:31]
	v_mfma_f32_32x32x16_bf16 v[0:15], v[206:209], v[190:193], v[0:15]
	ds_read_b128 v[172:175], v128 offset:16384
	ds_read_b128 v[190:193], v128 offset:18432
	v_add_u32_e32 v128, v188, v179
	ds_read_b128 v[194:197], v128
	ds_read_b128 v[198:201], v128 offset:2048
	ds_read_b128 v[202:205], v128 offset:4096
	ds_read_b128 v[206:209], v128 offset:6144
	s_waitcnt lgkmcnt(9)
	v_mfma_f32_32x32x16_bf16 v[112:127], v[138:141], v[130:133], v[112:127]
	v_mfma_f32_32x32x16_bf16 v[96:111], v[138:141], v[134:137], v[96:111]
	s_waitcnt lgkmcnt(8)
	v_mfma_f32_32x32x16_bf16 v[80:95], v[142:145], v[130:133], v[80:95]
	v_mfma_f32_32x32x16_bf16 v[64:79], v[142:145], v[134:137], v[64:79]
	s_waitcnt lgkmcnt(7)
	v_mfma_f32_32x32x16_bf16 v[48:63], v[146:149], v[130:133], v[48:63]
	v_mfma_f32_32x32x16_bf16 v[32:47], v[146:149], v[134:137], v[32:47]
	s_waitcnt lgkmcnt(6)
	v_mfma_f32_32x32x16_bf16 v[16:31], v[150:153], v[130:133], v[16:31]
	v_mfma_f32_32x32x16_bf16 v[0:15], v[150:153], v[134:137], v[0:15]
	v_add_u32_e32 v128, v187, v180
	ds_read_b128 v[130:133], v128 offset:16384
	ds_read_b128 v[134:137], v128 offset:18432
	v_add_u32_e32 v128, v188, v180
	ds_read_b128 v[138:141], v128
	ds_read_b128 v[142:145], v128 offset:2048
	ds_read_b128 v[146:149], v128 offset:4096
	ds_read_b128 v[150:153], v128 offset:6144
	s_waitcnt lgkmcnt(9)
	v_mfma_f32_32x32x16_bf16 v[112:127], v[194:197], v[172:175], v[112:127]
	v_mfma_f32_32x32x16_bf16 v[96:111], v[194:197], v[190:193], v[96:111]
	s_waitcnt lgkmcnt(8)
	v_mfma_f32_32x32x16_bf16 v[80:95], v[198:201], v[172:175], v[80:95]
	v_mfma_f32_32x32x16_bf16 v[64:79], v[198:201], v[190:193], v[64:79]
	s_waitcnt lgkmcnt(7)
	v_mfma_f32_32x32x16_bf16 v[48:63], v[202:205], v[172:175], v[48:63]
	v_mfma_f32_32x32x16_bf16 v[32:47], v[202:205], v[190:193], v[32:47]
	s_waitcnt vmcnt(0) lgkmcnt(0)
	s_barrier
	v_add_u32_e32 v128, v185, v179
	s_waitcnt lgkmcnt(6)
	v_mfma_f32_32x32x16_bf16 v[16:31], v[206:209], v[172:175], v[16:31]
	v_mfma_f32_32x32x16_bf16 v[0:15], v[206:209], v[190:193], v[0:15]
	ds_read_b128 v[172:175], v128 offset:16384
	ds_read_b128 v[190:193], v128 offset:18432
	v_add_u32_e32 v128, v186, v179
	ds_read_b128 v[194:197], v128
	ds_read_b128 v[198:201], v128 offset:2048
	ds_read_b128 v[202:205], v128 offset:4096
	ds_read_b128 v[206:209], v128 offset:6144
	s_waitcnt lgkmcnt(9)
	v_mfma_f32_32x32x16_bf16 v[112:127], v[138:141], v[130:133], v[112:127]
	v_mfma_f32_32x32x16_bf16 v[96:111], v[138:141], v[134:137], v[96:111]
	s_waitcnt lgkmcnt(8)
	v_mfma_f32_32x32x16_bf16 v[80:95], v[142:145], v[130:133], v[80:95]
	v_mfma_f32_32x32x16_bf16 v[64:79], v[142:145], v[134:137], v[64:79]
	s_waitcnt lgkmcnt(7)
	v_mfma_f32_32x32x16_bf16 v[48:63], v[146:149], v[130:133], v[48:63]
	v_mfma_f32_32x32x16_bf16 v[32:47], v[146:149], v[134:137], v[32:47]
	s_waitcnt lgkmcnt(6)
	v_mfma_f32_32x32x16_bf16 v[16:31], v[150:153], v[130:133], v[16:31]
	v_mfma_f32_32x32x16_bf16 v[0:15], v[150:153], v[134:137], v[0:15]
	v_add_u32_e32 v128, v185, v180
	ds_read_b128 v[130:133], v128 offset:16384
	ds_read_b128 v[138:141], v128 offset:18432
	v_add_u32_e32 v128, v186, v180
	ds_read_b128 v[134:137], v128
	ds_read_b128 v[142:145], v128 offset:2048
	ds_read_b128 v[146:149], v128 offset:4096
	ds_read_b128 v[210:213], v128 offset:6144
	s_waitcnt lgkmcnt(9)
	v_mfma_f32_32x32x16_bf16 v[112:127], v[194:197], v[172:175], v[112:127]
	v_mfma_f32_32x32x16_bf16 v[96:111], v[194:197], v[190:193], v[96:111]
	s_waitcnt lgkmcnt(8)
	v_mfma_f32_32x32x16_bf16 v[80:95], v[198:201], v[172:175], v[80:95]
	v_mfma_f32_32x32x16_bf16 v[64:79], v[198:201], v[190:193], v[64:79]
	s_waitcnt lgkmcnt(7)
	v_mfma_f32_32x32x16_bf16 v[48:63], v[202:205], v[172:175], v[48:63]
	v_mfma_f32_32x32x16_bf16 v[32:47], v[202:205], v[190:193], v[32:47]
	s_waitcnt lgkmcnt(6)
	v_mfma_f32_32x32x16_bf16 v[16:31], v[206:209], v[172:175], v[16:31]
	v_add_u32_e32 v150, s0, v157
	s_movk_i32 s2, 0x2000
	s_movk_i32 s0, 0x1fff
	v_cmp_gt_i32_e32 vcc, s2, v150
	s_movk_i32 s2, 0x7ff
	v_mfma_f32_32x32x16_bf16 v[0:15], v[206:209], v[190:193], v[0:15]
	s_waitcnt lgkmcnt(3)
	v_mfma_f32_32x32x16_bf16 v[112:127], v[134:137], v[130:133], v[112:127]
	v_mfma_f32_32x32x16_bf16 v[96:111], v[134:137], v[138:141], v[96:111]
	v_or_b32_e32 v136, s1, v176
	v_cmp_lt_i32_e64 s[0:1], s0, v150
	v_cmp_lt_i32_e64 s[2:3], s2, v136
	s_waitcnt lgkmcnt(2)
	v_mfma_f32_32x32x16_bf16 v[80:95], v[142:145], v[130:133], v[80:95]
	v_mfma_f32_32x32x16_bf16 v[64:79], v[142:145], v[138:141], v[64:79]
	s_waitcnt lgkmcnt(1)
	v_mfma_f32_32x32x16_bf16 v[48:63], v[146:149], v[130:133], v[48:63]
	v_mfma_f32_32x32x16_bf16 v[32:47], v[146:149], v[138:141], v[32:47]
	s_waitcnt lgkmcnt(0)
	v_mfma_f32_32x32x16_bf16 v[16:31], v[210:213], v[130:133], v[16:31]
	v_or_b32_e32 v130, v150, v183
	v_mfma_f32_32x32x16_bf16 v[0:15], v[210:213], v[138:141], v[0:15]
	s_and_saveexec_b64 s[24:25], s[2:3]
	s_xor_b64 s[2:3], exec, s[24:25]
	s_cbranch_execz .LBB0_461
	v_ashrrev_i32_e32 v134, 8, v150
	v_ashrrev_i32_e32 v135, 31, v134
	s_and_saveexec_b64 s[24:25], vcc
	s_xor_b64 s[24:25], exec, s[24:25]
	v_lshlrev_b64 v[140:141], 18, v[134:135]
	v_and_b32_e32 v128, 0x84, v130
	s_or_saveexec_b64 s[24:25], s[24:25]
	v_mov_b64_e32 v[138:139], 0x100
	s_xor_b64 exec, exec, s[24:25]
	v_add_u32_e32 v128, 0xffffe000, v150
	v_lshrrev_b32_e32 v128, 11, v128
	s_mov_b32 s26, 0x240000
	v_mad_u64_u32 v[140:141], s[26:27], v128, s26, v[166:167]
	v_and_b32_e32 v128, 0x784, v130
	v_add_u32_e32 v128, 0x100, v128
	v_mov_b64_e32 v[138:139], 0x900
	s_or_b64 exec, exec, s[24:25]
	v_add_u32_e32 v132, v136, v184
	v_or_b32_e32 v142, 1, v130
	v_or_b32_e32 v144, 2, v130
	v_or_b32_e32 v146, 3, v130
	v_lshl_add_u64 v[140:141], v[140:141], 1, s[6:7]
	v_mad_u64_u32 v[152:153], s[24:25], v138, v132, 0
	v_ashrrev_i32_e32 v131, 31, v130
	v_ashrrev_i32_e32 v143, 31, v142
	v_ashrrev_i32_e32 v145, 31, v144
	v_ashrrev_i32_e32 v147, 31, v146
	v_lshl_add_u64 v[152:153], v[152:153], 1, v[140:141]
	v_lshlrev_b64 v[136:137], 12, v[130:131]
	v_lshlrev_b64 v[142:143], 12, v[142:143]
	v_lshlrev_b64 v[144:145], 12, v[144:145]
	v_lshlrev_b64 v[146:147], 12, v[146:147]
	v_cvt_pk_bf16_f32 v148, v112, v113
	v_cvt_pk_bf16_f32 v149, v114, v115
	v_mov_b32_e32 v133, v129
	v_lshl_add_u64 v[152:153], v[128:129], 1, v[152:153]
	global_store_dwordx2 v[152:153], v[148:149], off
	v_lshl_add_u64 v[148:149], s[18:19], 0, v[136:137]
	v_lshlrev_b64 v[136:137], 2, v[132:133]
	v_lshl_add_u64 v[152:153], s[18:19], 0, v[142:143]
	v_lshl_add_u64 v[172:173], s[18:19], 0, v[144:145]
	v_lshl_add_u64 v[174:175], s[18:19], 0, v[146:147]
	v_lshl_add_u64 v[142:143], v[148:149], 0, v[136:137]
	v_lshl_add_u64 v[144:145], v[152:153], 0, v[136:137]
	v_lshl_add_u64 v[146:147], v[172:173], 0, v[136:137]
	v_lshl_add_u64 v[148:149], v[174:175], 0, v[136:137]
	s_and_saveexec_b64 s[24:25], vcc
	s_cbranch_execz .LBB0_338
	global_store_dword v[142:143], v112, off nt
	global_store_dword v[144:145], v113, off nt
	global_store_dword v[146:147], v114, off nt
	global_store_dword v[148:149], v115, off nt

.LBB0_1102:
	s_and_b32 s7, s6, 0x18000
	v_add_u32_e32 v222, s7, v180
	s_add_i32 s7, s6, 0xfffe8000
	s_and_b32 s7, s7, 0x18000
	v_or_b32_e32 v223, s7, v179
	v_add_u32_e32 v233, s7, v176
	s_waitcnt vmcnt(8) lgkmcnt(0)
	s_barrier
	v_mfma_f32_32x32x16_bf16 v[112:127], v[150:153], v[142:145], v[112:127]
	v_mfma_f32_32x32x16_bf16 v[96:111], v[150:153], v[130:133], v[96:111]
	v_add_u32_e32 v206, v223, v177
	v_add_u32_e32 v234, v233, v177
	ds_read_b128 v[202:205], v206 offset:16384
	ds_read_b128 v[206:209], v206 offset:18432
	ds_read_b128 v[210:213], v234
	v_mfma_f32_32x32x16_bf16 v[80:95], v[146:149], v[142:145], v[80:95]
	v_mfma_f32_32x32x16_bf16 v[64:79], v[146:149], v[130:133], v[64:79]
	ds_read_b128 v[214:217], v234 offset:2048
	v_readfirstlane_b32 s7, v222
	s_mov_b32 m0, s7
	s_nop 0
	global_load_lds_dwordx4 v[170:171], off
	v_mfma_f32_32x32x16_bf16 v[48:63], v[138:141], v[142:145], v[48:63]
	v_mfma_f32_32x32x16_bf16 v[32:47], v[138:141], v[130:133], v[32:47]
	ds_read_b128 v[224:227], v234 offset:4096
	s_add_i32 s10, s7, 0x2000
	v_lshl_add_u64 v[150:151], v[170:171], 0, s[34:35]
	s_mov_b32 m0, s10
	s_nop 0
	global_load_lds_dwordx4 v[150:151], off
	v_mfma_f32_32x32x16_bf16 v[16:31], v[134:137], v[142:145], v[16:31]
	v_mfma_f32_32x32x16_bf16 v[0:15], v[134:137], v[130:133], v[0:15]
	ds_read_b128 v[234:237], v234 offset:6144
	s_waitcnt lgkmcnt(3)
	v_mfma_f32_32x32x16_bf16 v[112:127], v[210:213], v[202:205], v[112:127]
	v_add_u32_e32 v130, v223, v178
	v_add_u32_e32 v134, v233, v178
	ds_read_b128 v[142:145], v130 offset:16384
	v_mfma_f32_32x32x16_bf16 v[96:111], v[210:213], v[206:209], v[96:111]
	ds_read_b128 v[130:133], v130 offset:18432
	s_add_i32 s10, s7, 0x6000
	s_addk_i32 s7, 0x4000
	s_mov_b32 m0, s7
	s_nop 0
	global_load_lds_dwordx4 v[172:173], off
	s_waitcnt lgkmcnt(4)
	v_mfma_f32_32x32x16_bf16 v[80:95], v[214:217], v[202:205], v[80:95]
	ds_read_b128 v[150:153], v134
	v_mfma_f32_32x32x16_bf16 v[64:79], v[214:217], v[206:209], v[64:79]
	ds_read_b128 v[146:149], v134 offset:2048
	s_waitcnt lgkmcnt(5)
	v_mfma_f32_32x32x16_bf16 v[48:63], v[224:227], v[202:205], v[48:63]
	ds_read_b128 v[138:141], v134 offset:4096
	v_mfma_f32_32x32x16_bf16 v[32:47], v[224:227], v[206:209], v[32:47]
	ds_read_b128 v[134:137], v134 offset:6144
	v_lshl_add_u64 v[222:223], v[172:173], 0, s[34:35]
	s_mov_b32 m0, s10
	s_nop 0
	global_load_lds_dwordx4 v[222:223], off
	s_waitcnt lgkmcnt(6)
	v_mfma_f32_32x32x16_bf16 v[16:31], v[234:237], v[202:205], v[16:31]
	s_add_i32 s6, s6, 0x8000
	v_lshl_add_u64 v[170:171], v[170:171], 0, 64
	v_lshl_add_u64 v[172:173], v[172:173], 0, 64
	s_cmp_eq_u32 s6, 0x100000
	v_mfma_f32_32x32x16_bf16 v[0:15], v[234:237], v[206:209], v[0:15]
	s_cbranch_scc0 .LBB0_1102
	s_waitcnt vmcnt(8) lgkmcnt(0)
	s_barrier
	v_add_u32_e32 v202, v179, v177
	v_add_u32_e32 v222, v176, v177
	ds_read_b128 v[170:173], v202 offset:49152
	ds_read_b128 v[202:205], v202 offset:51200
	ds_read_b128 v[206:209], v222 offset:32768
	ds_read_b128 v[210:213], v222 offset:34816
	ds_read_b128 v[214:217], v222 offset:36864
	ds_read_b128 v[224:227], v222 offset:38912
	s_waitcnt lgkmcnt(9)
	v_mfma_f32_32x32x16_bf16 v[112:127], v[150:153], v[142:145], v[112:127]
	v_mfma_f32_32x32x16_bf16 v[96:111], v[150:153], v[130:133], v[96:111]
	s_waitcnt lgkmcnt(8)
	v_mfma_f32_32x32x16_bf16 v[80:95], v[146:149], v[142:145], v[80:95]
	v_mfma_f32_32x32x16_bf16 v[64:79], v[146:149], v[130:133], v[64:79]
	s_waitcnt lgkmcnt(7)
	v_mfma_f32_32x32x16_bf16 v[48:63], v[138:141], v[142:145], v[48:63]
	v_mfma_f32_32x32x16_bf16 v[32:47], v[138:141], v[130:133], v[32:47]
	s_waitcnt lgkmcnt(6)
	v_mfma_f32_32x32x16_bf16 v[16:31], v[134:137], v[142:145], v[16:31]
	v_mfma_f32_32x32x16_bf16 v[0:15], v[134:137], v[130:133], v[0:15]
	v_add_u32_e32 v134, v179, v178
	v_add_u32_e32 v150, v176, v178
	ds_read_b128 v[130:133], v134 offset:49152
	ds_read_b128 v[134:137], v134 offset:51200
	ds_read_b128 v[138:141], v150 offset:32768
	ds_read_b128 v[142:145], v150 offset:34816
	ds_read_b128 v[146:149], v150 offset:36864
	ds_read_b128 v[150:153], v150 offset:38912
	s_waitcnt lgkmcnt(9)
	v_mfma_f32_32x32x16_bf16 v[112:127], v[206:209], v[170:173], v[112:127]
	v_mfma_f32_32x32x16_bf16 v[96:111], v[206:209], v[202:205], v[96:111]
	s_waitcnt lgkmcnt(8)
	v_mfma_f32_32x32x16_bf16 v[80:95], v[210:213], v[170:173], v[80:95]
	v_mfma_f32_32x32x16_bf16 v[64:79], v[210:213], v[202:205], v[64:79]
	s_waitcnt lgkmcnt(7)
	v_mfma_f32_32x32x16_bf16 v[48:63], v[214:217], v[170:173], v[48:63]
	v_mfma_f32_32x32x16_bf16 v[32:47], v[214:217], v[202:205], v[32:47]
	s_waitcnt lgkmcnt(6)
	v_mfma_f32_32x32x16_bf16 v[0:15], v[224:227], v[202:205], v[0:15]
	s_waitcnt vmcnt(4) lgkmcnt(0)
	s_barrier
	v_add_u32_e32 v202, v199, v177
	v_add_u32_e32 v222, v200, v177
	v_mfma_f32_32x32x16_bf16 v[16:31], v[224:227], v[170:173], v[16:31]
	ds_read_b128 v[170:173], v202 offset:16384
	ds_read_b128 v[202:205], v202 offset:18432
	ds_read_b128 v[206:209], v222
	ds_read_b128 v[210:213], v222 offset:2048
	ds_read_b128 v[214:217], v222 offset:4096
	ds_read_b128 v[224:227], v222 offset:6144
	s_waitcnt lgkmcnt(9)
	v_mfma_f32_32x32x16_bf16 v[112:127], v[138:141], v[130:133], v[112:127]
	v_mfma_f32_32x32x16_bf16 v[96:111], v[138:141], v[134:137], v[96:111]
	s_waitcnt lgkmcnt(8)
	v_mfma_f32_32x32x16_bf16 v[80:95], v[142:145], v[130:133], v[80:95]
	v_mfma_f32_32x32x16_bf16 v[64:79], v[142:145], v[134:137], v[64:79]
	s_waitcnt lgkmcnt(7)
	v_mfma_f32_32x32x16_bf16 v[48:63], v[146:149], v[130:133], v[48:63]
	v_mfma_f32_32x32x16_bf16 v[32:47], v[146:149], v[134:137], v[32:47]
	s_waitcnt lgkmcnt(6)
	v_mfma_f32_32x32x16_bf16 v[16:31], v[150:153], v[130:133], v[16:31]
	v_mfma_f32_32x32x16_bf16 v[0:15], v[150:153], v[134:137], v[0:15]
	v_add_u32_e32 v134, v199, v178
	v_add_u32_e32 v150, v200, v178
	ds_read_b128 v[130:133], v134 offset:16384
	ds_read_b128 v[134:137], v134 offset:18432
	ds_read_b128 v[138:141], v150
	ds_read_b128 v[142:145], v150 offset:2048
	ds_read_b128 v[146:149], v150 offset:4096
	ds_read_b128 v[150:153], v150 offset:6144
	s_waitcnt lgkmcnt(9)
	v_mfma_f32_32x32x16_bf16 v[112:127], v[206:209], v[170:173], v[112:127]
	v_mfma_f32_32x32x16_bf16 v[96:111], v[206:209], v[202:205], v[96:111]
	s_waitcnt lgkmcnt(8)
	v_mfma_f32_32x32x16_bf16 v[80:95], v[210:213], v[170:173], v[80:95]
	v_mfma_f32_32x32x16_bf16 v[64:79], v[210:213], v[202:205], v[64:79]
	s_waitcnt lgkmcnt(7)
	v_mfma_f32_32x32x16_bf16 v[48:63], v[214:217], v[170:173], v[48:63]
	v_mfma_f32_32x32x16_bf16 v[32:47], v[214:217], v[202:205], v[32:47]
	s_waitcnt lgkmcnt(6)
	v_mfma_f32_32x32x16_bf16 v[0:15], v[224:227], v[202:205], v[0:15]
	s_waitcnt vmcnt(0) lgkmcnt(0)
	s_barrier
	v_add_u32_e32 v202, v197, v177
	v_add_u32_e32 v222, v198, v177
	v_mfma_f32_32x32x16_bf16 v[16:31], v[224:227], v[170:173], v[16:31]
	ds_read_b128 v[170:173], v202 offset:16384
	ds_read_b128 v[202:205], v202 offset:18432
	ds_read_b128 v[206:209], v222
	ds_read_b128 v[210:213], v222 offset:2048
	ds_read_b128 v[214:217], v222 offset:4096
	ds_read_b128 v[224:227], v222 offset:6144
	s_waitcnt lgkmcnt(9)
	v_mfma_f32_32x32x16_bf16 v[112:127], v[138:141], v[130:133], v[112:127]
	v_mfma_f32_32x32x16_bf16 v[96:111], v[138:141], v[134:137], v[96:111]
	s_waitcnt lgkmcnt(8)
	v_mfma_f32_32x32x16_bf16 v[80:95], v[142:145], v[130:133], v[80:95]
	v_mfma_f32_32x32x16_bf16 v[64:79], v[142:145], v[134:137], v[64:79]
	s_waitcnt lgkmcnt(7)
	v_mfma_f32_32x32x16_bf16 v[48:63], v[146:149], v[130:133], v[48:63]
	v_mfma_f32_32x32x16_bf16 v[32:47], v[146:149], v[134:137], v[32:47]
	s_waitcnt lgkmcnt(6)
	v_mfma_f32_32x32x16_bf16 v[16:31], v[150:153], v[130:133], v[16:31]
	v_mfma_f32_32x32x16_bf16 v[0:15], v[150:153], v[134:137], v[0:15]
	v_add_u32_e32 v134, v197, v178
	v_add_u32_e32 v150, v198, v178
	ds_read_b128 v[130:133], v134 offset:16384
	ds_read_b128 v[134:137], v134 offset:18432
	ds_read_b128 v[138:141], v150
	ds_read_b128 v[142:145], v150 offset:2048
	ds_read_b128 v[146:149], v150 offset:4096
	ds_read_b128 v[150:153], v150 offset:6144
	s_waitcnt lgkmcnt(9)
	v_mfma_f32_32x32x16_bf16 v[112:127], v[206:209], v[170:173], v[112:127]
	v_mfma_f32_32x32x16_bf16 v[96:111], v[206:209], v[202:205], v[96:111]
	s_waitcnt lgkmcnt(8)
	v_mfma_f32_32x32x16_bf16 v[80:95], v[210:213], v[170:173], v[80:95]
	v_mfma_f32_32x32x16_bf16 v[64:79], v[210:213], v[202:205], v[64:79]
	s_waitcnt lgkmcnt(7)
	v_mfma_f32_32x32x16_bf16 v[48:63], v[214:217], v[170:173], v[48:63]
	v_mfma_f32_32x32x16_bf16 v[32:47], v[214:217], v[202:205], v[32:47]
	s_waitcnt lgkmcnt(6)
	v_mfma_f32_32x32x16_bf16 v[16:31], v[224:227], v[170:173], v[16:31]
	v_mfma_f32_32x32x16_bf16 v[0:15], v[224:227], v[202:205], v[0:15]
	s_waitcnt lgkmcnt(3)
	v_mfma_f32_32x32x16_bf16 v[112:127], v[138:141], v[130:133], v[112:127]
	v_mfma_f32_32x32x16_bf16 v[96:111], v[138:141], v[134:137], v[96:111]
	s_nop 10
	v_cvt_pk_bf16_f32 v112, v112, s0
	s_waitcnt lgkmcnt(2)
	v_mfma_f32_32x32x16_bf16 v[80:95], v[142:145], v[130:133], v[80:95]
	v_cvt_pk_bf16_f32 v96, v96, s0
	v_cvt_pk_bf16_f32 v98, v98, s0
	s_waitcnt lgkmcnt(1)
	v_mfma_f32_32x32x16_bf16 v[48:63], v[146:149], v[130:133], v[48:63]
	s_nop 7
	v_cvt_pk_bf16_f32 v80, v80, s0
	s_waitcnt lgkmcnt(0)
	v_mfma_f32_32x32x16_bf16 v[16:31], v[150:153], v[130:133], v[16:31]
	v_add_u32_e32 v132, s3, v128
	v_or_b32_e32 v130, s5, v174
	v_ashrrev_i32_e32 v131, 31, v130
	v_lshl_add_u64 v[130:131], v[130:131], 1, v[158:159]
	v_cvt_pk_bf16_f32 v48, v48, s0
	v_readlane_b32 s3, v252, 7
	s_add_i32 s4, s4, s3
	v_mfma_f32_32x32x16_bf16 v[64:79], v[142:145], v[134:137], v[64:79]
	s_nop 3
	v_cvt_pk_bf16_f32 v16, v16, s0
	v_mfma_f32_32x32x16_bf16 v[32:47], v[146:149], v[134:137], v[32:47]
	s_nop 5
	v_cvt_pk_bf16_f32 v64, v64, s0
	v_cvt_pk_bf16_f32 v66, v66, s0
	v_mfma_f32_32x32x16_bf16 v[0:15], v[150:153], v[134:137], v[0:15]
	v_or_b32_e32 v134, v132, v181
	v_ashrrev_i32_e32 v135, 31, v134
	v_lshlrev_b64 v[134:135], 11, v[134:135]
	v_lshl_add_u64 v[134:135], v[130:131], 0, v[134:135]
	global_store_short v[134:135], v112, off
	global_store_short v[134:135], v96, off offset:64
	v_or_b32_e32 v134, v132, v182
	v_ashrrev_i32_e32 v135, 31, v134
	v_lshlrev_b64 v[134:135], 11, v[134:135]
	v_lshl_add_u64 v[134:135], v[130:131], 0, v[134:135]
	v_cvt_pk_bf16_f32 v96, v113, s0
	global_store_short v[134:135], v96, off
	v_cvt_pk_bf16_f32 v96, v97, s0
	global_store_short v[134:135], v96, off offset:64
	v_or_b32_e32 v96, v132, v183
	v_ashrrev_i32_e32 v97, 31, v96
	v_lshlrev_b64 v[96:97], 11, v[96:97]
	v_lshl_add_u64 v[96:97], v[130:131], 0, v[96:97]
	v_cvt_pk_bf16_f32 v112, v114, s0
	global_store_short v[96:97], v112, off
	global_store_short v[96:97], v98, off offset:64
	v_or_b32_e32 v96, v132, v184
	v_ashrrev_i32_e32 v97, 31, v96
	v_lshlrev_b64 v[96:97], 11, v[96:97]
	v_lshl_add_u64 v[96:97], v[130:131], 0, v[96:97]
	v_cvt_pk_bf16_f32 v98, v115, s0
	global_store_short v[96:97], v98, off
	v_cvt_pk_bf16_f32 v98, v99, s0
	global_store_short v[96:97], v98, off offset:64
	v_or_b32_e32 v96, v132, v185
	v_ashrrev_i32_e32 v97, 31, v96
	v_lshlrev_b64 v[96:97], 11, v[96:97]
	v_lshl_add_u64 v[96:97], v[130:131], 0, v[96:97]
	v_cvt_pk_bf16_f32 v98, v116, s0
	global_store_short v[96:97], v98, off
	v_cvt_pk_bf16_f32 v98, v100, s0
	global_store_short v[96:97], v98, off offset:64
	v_or_b32_e32 v96, v132, v186
	v_ashrrev_i32_e32 v97, 31, v96
	v_lshlrev_b64 v[96:97], 11, v[96:97]
	v_lshl_add_u64 v[96:97], v[130:131], 0, v[96:97]
	v_cvt_pk_bf16_f32 v98, v117, s0
	global_store_short v[96:97], v98, off
	v_cvt_pk_bf16_f32 v98, v101, s0
	global_store_short v[96:97], v98, off offset:64
	v_or_b32_e32 v96, v132, v187
	v_ashrrev_i32_e32 v97, 31, v96
	v_lshlrev_b64 v[96:97], 11, v[96:97]
	v_lshl_add_u64 v[96:97], v[130:131], 0, v[96:97]
	v_cvt_pk_bf16_f32 v98, v118, s0
	global_store_short v[96:97], v98, off
	v_cvt_pk_bf16_f32 v98, v102, s0
	global_store_short v[96:97], v98, off offset:64
	v_or_b32_e32 v96, v132, v188
	v_ashrrev_i32_e32 v97, 31, v96
	v_lshlrev_b64 v[96:97], 11, v[96:97]
	v_lshl_add_u64 v[96:97], v[130:131], 0, v[96:97]
	v_cvt_pk_bf16_f32 v98, v119, s0
	global_store_short v[96:97], v98, off
	v_cvt_pk_bf16_f32 v98, v103, s0
	global_store_short v[96:97], v98, off offset:64
	v_or_b32_e32 v96, v132, v189
	v_ashrrev_i32_e32 v97, 31, v96
	v_lshlrev_b64 v[96:97], 11, v[96:97]
	v_lshl_add_u64 v[96:97], v[130:131], 0, v[96:97]
	v_cvt_pk_bf16_f32 v98, v120, s0
	global_store_short v[96:97], v98, off
	v_cvt_pk_bf16_f32 v98, v104, s0
	global_store_short v[96:97], v98, off offset:64
	v_or_b32_e32 v96, v132, v190
	v_ashrrev_i32_e32 v97, 31, v96
	v_lshlrev_b64 v[96:97], 11, v[96:97]
	v_lshl_add_u64 v[96:97], v[130:131], 0, v[96:97]
	v_cvt_pk_bf16_f32 v98, v121, s0
	global_store_short v[96:97], v98, off
	v_cvt_pk_bf16_f32 v98, v105, s0
	global_store_short v[96:97], v98, off offset:64
	v_or_b32_e32 v96, v132, v191
	v_ashrrev_i32_e32 v97, 31, v96
	v_lshlrev_b64 v[96:97], 11, v[96:97]
	v_lshl_add_u64 v[96:97], v[130:131], 0, v[96:97]
	v_cvt_pk_bf16_f32 v98, v122, s0
	global_store_short v[96:97], v98, off
	v_cvt_pk_bf16_f32 v98, v106, s0
	global_store_short v[96:97], v98, off offset:64
	v_or_b32_e32 v96, v132, v192
	v_ashrrev_i32_e32 v97, 31, v96
	v_lshlrev_b64 v[96:97], 11, v[96:97]
	v_lshl_add_u64 v[96:97], v[130:131], 0, v[96:97]
	v_cvt_pk_bf16_f32 v98, v123, s0
	global_store_short v[96:97], v98, off
	v_cvt_pk_bf16_f32 v98, v107, s0
	global_store_short v[96:97], v98, off offset:64
	v_or_b32_e32 v96, v132, v193
	v_ashrrev_i32_e32 v97, 31, v96
	v_lshlrev_b64 v[96:97], 11, v[96:97]
	v_lshl_add_u64 v[96:97], v[130:131], 0, v[96:97]
	v_cvt_pk_bf16_f32 v98, v124, s0
	global_store_short v[96:97], v98, off
	v_cvt_pk_bf16_f32 v98, v108, s0
	global_store_short v[96:97], v98, off offset:64
	v_or_b32_e32 v96, v132, v194
	v_ashrrev_i32_e32 v97, 31, v96
	v_lshlrev_b64 v[96:97], 11, v[96:97]
	v_lshl_add_u64 v[96:97], v[130:131], 0, v[96:97]
	v_cvt_pk_bf16_f32 v98, v125, s0
	global_store_short v[96:97], v98, off
	v_cvt_pk_bf16_f32 v98, v109, s0
	global_store_short v[96:97], v98, off offset:64
	v_or_b32_e32 v96, v132, v195
	v_ashrrev_i32_e32 v97, 31, v96
	v_lshlrev_b64 v[96:97], 11, v[96:97]
	v_lshl_add_u64 v[96:97], v[130:131], 0, v[96:97]
	v_cvt_pk_bf16_f32 v98, v126, s0
	global_store_short v[96:97], v98, off
	v_cvt_pk_bf16_f32 v98, v110, s0
	global_store_short v[96:97], v98, off offset:64
	v_or_b32_e32 v96, v132, v196
	v_ashrrev_i32_e32 v97, 31, v96
	v_lshlrev_b64 v[96:97], 11, v[96:97]
	v_lshl_add_u64 v[96:97], v[130:131], 0, v[96:97]
	v_cvt_pk_bf16_f32 v98, v127, s0
	global_store_short v[96:97], v98, off
	v_cvt_pk_bf16_f32 v98, v111, s0
	global_store_short v[96:97], v98, off offset:64
	v_or_b32_e32 v98, 32, v132
	v_or_b32_e32 v96, v98, v181
	v_ashrrev_i32_e32 v97, 31, v96
	v_lshlrev_b64 v[96:97], 11, v[96:97]
	v_lshl_add_u64 v[96:97], v[130:131], 0, v[96:97]
	global_store_short v[96:97], v80, off
	global_store_short v[96:97], v64, off offset:64
	v_or_b32_e32 v96, v98, v182
	v_ashrrev_i32_e32 v97, 31, v96
	v_lshlrev_b64 v[96:97], 11, v[96:97]
	v_lshl_add_u64 v[96:97], v[130:131], 0, v[96:97]
	v_cvt_pk_bf16_f32 v64, v81, s0
	global_store_short v[96:97], v64, off
	v_cvt_pk_bf16_f32 v64, v65, s0
	global_store_short v[96:97], v64, off offset:64
	v_or_b32_e32 v64, v98, v183
	v_ashrrev_i32_e32 v65, 31, v64
	v_lshlrev_b64 v[64:65], 11, v[64:65]
	v_lshl_add_u64 v[64:65], v[130:131], 0, v[64:65]
	v_cvt_pk_bf16_f32 v80, v82, s0
	global_store_short v[64:65], v80, off
	global_store_short v[64:65], v66, off offset:64
	v_or_b32_e32 v64, v98, v184
	v_ashrrev_i32_e32 v65, 31, v64
	v_lshlrev_b64 v[64:65], 11, v[64:65]
	v_lshl_add_u64 v[64:65], v[130:131], 0, v[64:65]
	v_cvt_pk_bf16_f32 v66, v83, s0
	global_store_short v[64:65], v66, off
	v_cvt_pk_bf16_f32 v66, v67, s0
	global_store_short v[64:65], v66, off offset:64
	v_or_b32_e32 v64, v98, v185
	v_ashrrev_i32_e32 v65, 31, v64
	v_lshlrev_b64 v[64:65], 11, v[64:65]
	v_lshl_add_u64 v[64:65], v[130:131], 0, v[64:65]
	v_cvt_pk_bf16_f32 v66, v84, s0
	global_store_short v[64:65], v66, off
	v_cvt_pk_bf16_f32 v66, v68, s0
	global_store_short v[64:65], v66, off offset:64
	v_or_b32_e32 v64, v98, v186
	v_ashrrev_i32_e32 v65, 31, v64
	v_lshlrev_b64 v[64:65], 11, v[64:65]
	v_lshl_add_u64 v[64:65], v[130:131], 0, v[64:65]
	v_cvt_pk_bf16_f32 v66, v85, s0
	global_store_short v[64:65], v66, off
	v_cvt_pk_bf16_f32 v66, v69, s0
	global_store_short v[64:65], v66, off offset:64
	v_or_b32_e32 v64, v98, v187
	v_ashrrev_i32_e32 v65, 31, v64
	v_lshlrev_b64 v[64:65], 11, v[64:65]
	v_lshl_add_u64 v[64:65], v[130:131], 0, v[64:65]
	v_cvt_pk_bf16_f32 v66, v86, s0
	global_store_short v[64:65], v66, off
	v_cvt_pk_bf16_f32 v66, v70, s0
	global_store_short v[64:65], v66, off offset:64
	v_or_b32_e32 v64, v98, v188
	v_ashrrev_i32_e32 v65, 31, v64
	v_lshlrev_b64 v[64:65], 11, v[64:65]
	v_lshl_add_u64 v[64:65], v[130:131], 0, v[64:65]
	v_cvt_pk_bf16_f32 v66, v87, s0
	global_store_short v[64:65], v66, off
	v_cvt_pk_bf16_f32 v66, v71, s0
	global_store_short v[64:65], v66, off offset:64
	v_or_b32_e32 v64, v98, v189
	v_ashrrev_i32_e32 v65, 31, v64
	v_lshlrev_b64 v[64:65], 11, v[64:65]
	v_lshl_add_u64 v[64:65], v[130:131], 0, v[64:65]
	v_cvt_pk_bf16_f32 v66, v88, s0
	global_store_short v[64:65], v66, off
	v_cvt_pk_bf16_f32 v66, v72, s0
	global_store_short v[64:65], v66, off offset:64
	v_or_b32_e32 v64, v98, v190
	v_ashrrev_i32_e32 v65, 31, v64
	v_lshlrev_b64 v[64:65], 11, v[64:65]
	v_lshl_add_u64 v[64:65], v[130:131], 0, v[64:65]
	v_cvt_pk_bf16_f32 v66, v89, s0
	global_store_short v[64:65], v66, off
	v_cvt_pk_bf16_f32 v66, v73, s0
	global_store_short v[64:65], v66, off offset:64
	v_or_b32_e32 v64, v98, v191
	v_ashrrev_i32_e32 v65, 31, v64
	v_lshlrev_b64 v[64:65], 11, v[64:65]
	v_lshl_add_u64 v[64:65], v[130:131], 0, v[64:65]
	v_cvt_pk_bf16_f32 v66, v90, s0
	global_store_short v[64:65], v66, off
	v_cvt_pk_bf16_f32 v66, v74, s0
	global_store_short v[64:65], v66, off offset:64
	v_or_b32_e32 v64, v98, v192
	v_ashrrev_i32_e32 v65, 31, v64
	v_lshlrev_b64 v[64:65], 11, v[64:65]
	v_lshl_add_u64 v[64:65], v[130:131], 0, v[64:65]
	v_cvt_pk_bf16_f32 v66, v91, s0
	global_store_short v[64:65], v66, off
	v_cvt_pk_bf16_f32 v66, v75, s0
	global_store_short v[64:65], v66, off offset:64
	v_or_b32_e32 v64, v98, v193
	v_ashrrev_i32_e32 v65, 31, v64
	v_lshlrev_b64 v[64:65], 11, v[64:65]
	v_lshl_add_u64 v[64:65], v[130:131], 0, v[64:65]
	v_cvt_pk_bf16_f32 v66, v92, s0
	global_store_short v[64:65], v66, off
	v_cvt_pk_bf16_f32 v66, v76, s0
	global_store_short v[64:65], v66, off offset:64
	v_or_b32_e32 v64, v98, v194
	v_ashrrev_i32_e32 v65, 31, v64
	v_lshlrev_b64 v[64:65], 11, v[64:65]
	v_lshl_add_u64 v[64:65], v[130:131], 0, v[64:65]
	v_cvt_pk_bf16_f32 v66, v93, s0
	global_store_short v[64:65], v66, off
	v_cvt_pk_bf16_f32 v66, v77, s0
	global_store_short v[64:65], v66, off offset:64
	v_or_b32_e32 v64, v98, v195
	v_ashrrev_i32_e32 v65, 31, v64
	v_lshlrev_b64 v[64:65], 11, v[64:65]
	v_lshl_add_u64 v[64:65], v[130:131], 0, v[64:65]
	v_cvt_pk_bf16_f32 v66, v94, s0
	global_store_short v[64:65], v66, off
	v_cvt_pk_bf16_f32 v66, v78, s0
	global_store_short v[64:65], v66, off offset:64
	v_or_b32_e32 v64, v98, v196
	v_ashrrev_i32_e32 v65, 31, v64
	v_lshlrev_b64 v[64:65], 11, v[64:65]
	v_lshl_add_u64 v[64:65], v[130:131], 0, v[64:65]
	v_cvt_pk_bf16_f32 v66, v95, s0
	global_store_short v[64:65], v66, off
	v_cvt_pk_bf16_f32 v66, v79, s0
	global_store_short v[64:65], v66, off offset:64
	v_or_b32_e32 v66, 64, v132
	v_or_b32_e32 v64, v66, v181
	v_ashrrev_i32_e32 v65, 31, v64
	v_lshlrev_b64 v[64:65], 11, v[64:65]
	v_lshl_add_u64 v[64:65], v[130:131], 0, v[64:65]
	v_cvt_pk_bf16_f32 v32, v32, s0
	global_store_short v[64:65], v48, off
	global_store_short v[64:65], v32, off offset:64
	v_or_b32_e32 v64, v66, v182
	v_ashrrev_i32_e32 v65, 31, v64
	v_lshlrev_b64 v[64:65], 11, v[64:65]
	v_lshl_add_u64 v[64:65], v[130:131], 0, v[64:65]
	v_cvt_pk_bf16_f32 v32, v49, s0
	global_store_short v[64:65], v32, off
	v_cvt_pk_bf16_f32 v32, v33, s0
	global_store_short v[64:65], v32, off offset:64
	v_or_b32_e32 v32, v66, v183
	v_ashrrev_i32_e32 v33, 31, v32
	v_lshlrev_b64 v[32:33], 11, v[32:33]
	v_lshl_add_u64 v[32:33], v[130:131], 0, v[32:33]
	v_cvt_pk_bf16_f32 v48, v50, s0
	v_cvt_pk_bf16_f32 v34, v34, s0
	global_store_short v[32:33], v48, off
	global_store_short v[32:33], v34, off offset:64
	v_or_b32_e32 v32, v66, v184
	v_ashrrev_i32_e32 v33, 31, v32
	v_lshlrev_b64 v[32:33], 11, v[32:33]
	v_lshl_add_u64 v[32:33], v[130:131], 0, v[32:33]
	v_cvt_pk_bf16_f32 v34, v51, s0
	global_store_short v[32:33], v34, off
	v_cvt_pk_bf16_f32 v34, v35, s0
	global_store_short v[32:33], v34, off offset:64
	v_or_b32_e32 v32, v66, v185
	v_ashrrev_i32_e32 v33, 31, v32
	v_lshlrev_b64 v[32:33], 11, v[32:33]
	v_lshl_add_u64 v[32:33], v[130:131], 0, v[32:33]
	v_cvt_pk_bf16_f32 v34, v52, s0
	global_store_short v[32:33], v34, off
	v_cvt_pk_bf16_f32 v34, v36, s0
	global_store_short v[32:33], v34, off offset:64
	v_or_b32_e32 v32, v66, v186
	v_ashrrev_i32_e32 v33, 31, v32
	v_lshlrev_b64 v[32:33], 11, v[32:33]
	v_lshl_add_u64 v[32:33], v[130:131], 0, v[32:33]
	v_cvt_pk_bf16_f32 v34, v53, s0
	global_store_short v[32:33], v34, off
	v_cvt_pk_bf16_f32 v34, v37, s0
	global_store_short v[32:33], v34, off offset:64
	v_or_b32_e32 v32, v66, v187
	v_ashrrev_i32_e32 v33, 31, v32
	v_lshlrev_b64 v[32:33], 11, v[32:33]
	v_lshl_add_u64 v[32:33], v[130:131], 0, v[32:33]
	v_cvt_pk_bf16_f32 v34, v54, s0
	global_store_short v[32:33], v34, off
	v_cvt_pk_bf16_f32 v34, v38, s0
	global_store_short v[32:33], v34, off offset:64
	v_or_b32_e32 v32, v66, v188
	v_ashrrev_i32_e32 v33, 31, v32
	v_lshlrev_b64 v[32:33], 11, v[32:33]
	v_lshl_add_u64 v[32:33], v[130:131], 0, v[32:33]
	v_cvt_pk_bf16_f32 v34, v55, s0
	global_store_short v[32:33], v34, off
	v_cvt_pk_bf16_f32 v34, v39, s0
	global_store_short v[32:33], v34, off offset:64
	v_or_b32_e32 v32, v66, v189
	v_ashrrev_i32_e32 v33, 31, v32
	v_lshlrev_b64 v[32:33], 11, v[32:33]
	v_lshl_add_u64 v[32:33], v[130:131], 0, v[32:33]
	v_cvt_pk_bf16_f32 v34, v56, s0
	global_store_short v[32:33], v34, off
	v_cvt_pk_bf16_f32 v34, v40, s0
	global_store_short v[32:33], v34, off offset:64
	v_or_b32_e32 v32, v66, v190
	v_ashrrev_i32_e32 v33, 31, v32
	v_lshlrev_b64 v[32:33], 11, v[32:33]
	v_lshl_add_u64 v[32:33], v[130:131], 0, v[32:33]
	v_cvt_pk_bf16_f32 v34, v57, s0
	global_store_short v[32:33], v34, off
	v_cvt_pk_bf16_f32 v34, v41, s0
	global_store_short v[32:33], v34, off offset:64
	v_or_b32_e32 v32, v66, v191
	v_ashrrev_i32_e32 v33, 31, v32
	v_lshlrev_b64 v[32:33], 11, v[32:33]
	v_lshl_add_u64 v[32:33], v[130:131], 0, v[32:33]
	v_cvt_pk_bf16_f32 v34, v58, s0
	global_store_short v[32:33], v34, off
	v_cvt_pk_bf16_f32 v34, v42, s0
	global_store_short v[32:33], v34, off offset:64
	v_or_b32_e32 v32, v66, v192
	v_ashrrev_i32_e32 v33, 31, v32
	v_lshlrev_b64 v[32:33], 11, v[32:33]
	v_lshl_add_u64 v[32:33], v[130:131], 0, v[32:33]
	v_cvt_pk_bf16_f32 v34, v59, s0
	global_store_short v[32:33], v34, off
	v_cvt_pk_bf16_f32 v34, v43, s0
	global_store_short v[32:33], v34, off offset:64
	v_or_b32_e32 v32, v66, v193
	v_ashrrev_i32_e32 v33, 31, v32
	v_lshlrev_b64 v[32:33], 11, v[32:33]
	v_lshl_add_u64 v[32:33], v[130:131], 0, v[32:33]
	v_cvt_pk_bf16_f32 v34, v60, s0
	global_store_short v[32:33], v34, off
	v_cvt_pk_bf16_f32 v34, v44, s0
	global_store_short v[32:33], v34, off offset:64
	v_or_b32_e32 v32, v66, v194
	v_ashrrev_i32_e32 v33, 31, v32
	v_lshlrev_b64 v[32:33], 11, v[32:33]
	v_lshl_add_u64 v[32:33], v[130:131], 0, v[32:33]
	v_cvt_pk_bf16_f32 v34, v61, s0
	global_store_short v[32:33], v34, off
	v_cvt_pk_bf16_f32 v34, v45, s0
	global_store_short v[32:33], v34, off offset:64
	v_or_b32_e32 v32, v66, v195
	v_ashrrev_i32_e32 v33, 31, v32
	v_lshlrev_b64 v[32:33], 11, v[32:33]
	v_lshl_add_u64 v[32:33], v[130:131], 0, v[32:33]
	v_cvt_pk_bf16_f32 v34, v62, s0
	global_store_short v[32:33], v34, off
	v_cvt_pk_bf16_f32 v34, v46, s0
	global_store_short v[32:33], v34, off offset:64
	v_or_b32_e32 v32, v66, v196
	v_ashrrev_i32_e32 v33, 31, v32
	v_lshlrev_b64 v[32:33], 11, v[32:33]
	v_lshl_add_u64 v[32:33], v[130:131], 0, v[32:33]
	v_cvt_pk_bf16_f32 v34, v63, s0
	global_store_short v[32:33], v34, off
	v_cvt_pk_bf16_f32 v34, v47, s0
	global_store_short v[32:33], v34, off offset:64
	v_or_b32_e32 v34, 0x60, v132
	v_or_b32_e32 v32, v34, v181
	v_ashrrev_i32_e32 v33, 31, v32
	v_lshlrev_b64 v[32:33], 11, v[32:33]
	v_lshl_add_u64 v[32:33], v[130:131], 0, v[32:33]
	v_cvt_pk_bf16_f32 v0, v0, s0
	global_store_short v[32:33], v16, off
	global_store_short v[32:33], v0, off offset:64
	v_or_b32_e32 v32, v34, v182
	v_ashrrev_i32_e32 v33, 31, v32
	v_lshlrev_b64 v[32:33], 11, v[32:33]
	v_lshl_add_u64 v[32:33], v[130:131], 0, v[32:33]
	v_cvt_pk_bf16_f32 v0, v17, s0
	global_store_short v[32:33], v0, off
	v_cvt_pk_bf16_f32 v0, v1, s0
	global_store_short v[32:33], v0, off offset:64
	v_or_b32_e32 v0, v34, v183
	v_ashrrev_i32_e32 v1, 31, v0
	v_lshlrev_b64 v[0:1], 11, v[0:1]
	v_lshl_add_u64 v[0:1], v[130:131], 0, v[0:1]
	v_cvt_pk_bf16_f32 v16, v18, s0
	v_cvt_pk_bf16_f32 v2, v2, s0
	global_store_short v[0:1], v16, off
	global_store_short v[0:1], v2, off offset:64
	v_or_b32_e32 v0, v34, v184
	v_ashrrev_i32_e32 v1, 31, v0
	v_lshlrev_b64 v[0:1], 11, v[0:1]
	v_lshl_add_u64 v[0:1], v[130:131], 0, v[0:1]
	v_cvt_pk_bf16_f32 v2, v19, s0
	global_store_short v[0:1], v2, off
	v_cvt_pk_bf16_f32 v2, v3, s0
	global_store_short v[0:1], v2, off offset:64
	v_or_b32_e32 v0, v34, v185
	v_ashrrev_i32_e32 v1, 31, v0
	v_lshlrev_b64 v[0:1], 11, v[0:1]
	v_lshl_add_u64 v[0:1], v[130:131], 0, v[0:1]
	v_cvt_pk_bf16_f32 v2, v20, s0
	global_store_short v[0:1], v2, off
	v_cvt_pk_bf16_f32 v2, v4, s0
	global_store_short v[0:1], v2, off offset:64
	v_or_b32_e32 v0, v34, v186
	v_ashrrev_i32_e32 v1, 31, v0
	v_lshlrev_b64 v[0:1], 11, v[0:1]
	v_lshl_add_u64 v[0:1], v[130:131], 0, v[0:1]
	v_cvt_pk_bf16_f32 v2, v21, s0
	global_store_short v[0:1], v2, off
	v_cvt_pk_bf16_f32 v2, v5, s0
	global_store_short v[0:1], v2, off offset:64
	v_or_b32_e32 v0, v34, v187
	v_ashrrev_i32_e32 v1, 31, v0
	v_lshlrev_b64 v[0:1], 11, v[0:1]
	v_lshl_add_u64 v[0:1], v[130:131], 0, v[0:1]
	v_cvt_pk_bf16_f32 v2, v22, s0
	global_store_short v[0:1], v2, off
	v_cvt_pk_bf16_f32 v2, v6, s0
	global_store_short v[0:1], v2, off offset:64
	v_or_b32_e32 v0, v34, v188
	v_ashrrev_i32_e32 v1, 31, v0
	v_lshlrev_b64 v[0:1], 11, v[0:1]
	v_lshl_add_u64 v[0:1], v[130:131], 0, v[0:1]
	v_cvt_pk_bf16_f32 v2, v23, s0
	global_store_short v[0:1], v2, off
	v_cvt_pk_bf16_f32 v2, v7, s0
	global_store_short v[0:1], v2, off offset:64
	v_or_b32_e32 v0, v34, v189
	v_ashrrev_i32_e32 v1, 31, v0
	v_lshlrev_b64 v[0:1], 11, v[0:1]
	v_lshl_add_u64 v[0:1], v[130:131], 0, v[0:1]
	v_cvt_pk_bf16_f32 v2, v24, s0
	global_store_short v[0:1], v2, off
	v_cvt_pk_bf16_f32 v2, v8, s0
	global_store_short v[0:1], v2, off offset:64
	v_or_b32_e32 v0, v34, v190
	v_ashrrev_i32_e32 v1, 31, v0
	v_lshlrev_b64 v[0:1], 11, v[0:1]
	v_lshl_add_u64 v[0:1], v[130:131], 0, v[0:1]
	v_cvt_pk_bf16_f32 v2, v25, s0
	global_store_short v[0:1], v2, off
	v_cvt_pk_bf16_f32 v2, v9, s0
	global_store_short v[0:1], v2, off offset:64
	v_or_b32_e32 v0, v34, v191
	v_ashrrev_i32_e32 v1, 31, v0
	v_lshlrev_b64 v[0:1], 11, v[0:1]
	v_lshl_add_u64 v[0:1], v[130:131], 0, v[0:1]
	v_cvt_pk_bf16_f32 v2, v26, s0
	global_store_short v[0:1], v2, off
	v_cvt_pk_bf16_f32 v2, v10, s0
	global_store_short v[0:1], v2, off offset:64
	v_or_b32_e32 v0, v34, v192
	v_ashrrev_i32_e32 v1, 31, v0
	v_lshlrev_b64 v[0:1], 11, v[0:1]
	v_lshl_add_u64 v[0:1], v[130:131], 0, v[0:1]
	v_cvt_pk_bf16_f32 v2, v27, s0
	global_store_short v[0:1], v2, off
	v_cvt_pk_bf16_f32 v2, v11, s0
	global_store_short v[0:1], v2, off offset:64
	v_or_b32_e32 v0, v34, v193
	v_ashrrev_i32_e32 v1, 31, v0
	v_lshlrev_b64 v[0:1], 11, v[0:1]
	v_lshl_add_u64 v[0:1], v[130:131], 0, v[0:1]
	v_cvt_pk_bf16_f32 v2, v28, s0
	global_store_short v[0:1], v2, off
	v_cvt_pk_bf16_f32 v2, v12, s0
	global_store_short v[0:1], v2, off offset:64
	v_or_b32_e32 v0, v34, v194
	v_ashrrev_i32_e32 v1, 31, v0
	v_lshlrev_b64 v[0:1], 11, v[0:1]
	v_lshl_add_u64 v[0:1], v[130:131], 0, v[0:1]
	v_cvt_pk_bf16_f32 v2, v29, s0
	global_store_short v[0:1], v2, off
	v_cvt_pk_bf16_f32 v2, v13, s0
	global_store_short v[0:1], v2, off offset:64
	v_or_b32_e32 v0, v34, v195
	v_ashrrev_i32_e32 v1, 31, v0
	v_lshlrev_b64 v[0:1], 11, v[0:1]
	v_lshl_add_u64 v[0:1], v[130:131], 0, v[0:1]
	v_cvt_pk_bf16_f32 v2, v30, s0
	global_store_short v[0:1], v2, off
	v_cvt_pk_bf16_f32 v2, v14, s0
	global_store_short v[0:1], v2, off offset:64
	v_or_b32_e32 v0, v34, v196
	v_ashrrev_i32_e32 v1, 31, v0
	v_lshlrev_b64 v[0:1], 11, v[0:1]
	v_lshl_add_u64 v[0:1], v[130:131], 0, v[0:1]
	v_cvt_pk_bf16_f32 v2, v31, s0
	global_store_short v[0:1], v2, off
	v_cvt_pk_bf16_f32 v2, v15, s0
	s_add_i32 s0, s0, s3
	v_readlane_b32 s3, v252, 8
	s_add_i32 s2, s2, s3
	s_cmp_gt_i32 s4, 31
	global_store_short v[0:1], v2, off offset:64
	s_cbranch_scc0 .LBB0_1101

.LBB0_1161:
	s_and_b32 s21, s20, 0x18000
	v_add_u32_e32 v128, s21, v203
	s_add_i32 s21, s20, 0xfffe8000
	s_and_b32 s21, s21, 0x18000
	v_or_b32_e32 v222, s21, v202
	v_add_u32_e32 v223, s21, v199
	s_waitcnt vmcnt(8) lgkmcnt(0)
	s_barrier
	v_mfma_f32_32x32x16_bf16 v[112:127], v[150:153], v[142:145], v[112:127]
	v_mfma_f32_32x32x16_bf16 v[96:111], v[150:153], v[130:133], v[96:111]
	v_add_u32_e32 v180, v222, v200
	v_add_u32_e32 v224, v223, v200
	ds_read_b128 v[176:179], v180 offset:16384
	ds_read_b128 v[180:183], v180 offset:18432
	ds_read_b128 v[184:187], v224
	v_mfma_f32_32x32x16_bf16 v[80:95], v[146:149], v[142:145], v[80:95]
	v_mfma_f32_32x32x16_bf16 v[64:79], v[146:149], v[130:133], v[64:79]
	ds_read_b128 v[188:191], v224 offset:2048
	v_readfirstlane_b32 s21, v128
	s_mov_b32 m0, s21
	s_nop 0
	global_load_lds_dwordx4 v[172:173], off
	v_mfma_f32_32x32x16_bf16 v[48:63], v[138:141], v[142:145], v[48:63]
	v_mfma_f32_32x32x16_bf16 v[32:47], v[138:141], v[130:133], v[32:47]
	ds_read_b128 v[192:195], v224 offset:4096
	s_add_i32 s22, s21, 0x2000
	v_lshl_add_u64 v[150:151], v[172:173], 0, s[26:27]
	s_mov_b32 m0, s22
	s_nop 0
	global_load_lds_dwordx4 v[150:151], off
	v_mfma_f32_32x32x16_bf16 v[16:31], v[134:137], v[142:145], v[16:31]
	v_mfma_f32_32x32x16_bf16 v[0:15], v[134:137], v[130:133], v[0:15]
	ds_read_b128 v[240:243], v224 offset:6144
	s_waitcnt lgkmcnt(3)
	v_mfma_f32_32x32x16_bf16 v[112:127], v[184:187], v[176:179], v[112:127]
	v_add_u32_e32 v128, v222, v201
	ds_read_b128 v[142:145], v128 offset:16384
	v_mfma_f32_32x32x16_bf16 v[96:111], v[184:187], v[180:183], v[96:111]
	ds_read_b128 v[130:133], v128 offset:18432
	s_add_i32 s22, s21, 0x6000
	s_addk_i32 s21, 0x4000
	s_mov_b32 m0, s21
	s_nop 0
	global_load_lds_dwordx4 v[174:175], off
	s_waitcnt lgkmcnt(4)
	v_mfma_f32_32x32x16_bf16 v[80:95], v[188:191], v[176:179], v[80:95]
	v_add_u32_e32 v128, v223, v201
	ds_read_b128 v[150:153], v128
	v_mfma_f32_32x32x16_bf16 v[64:79], v[188:191], v[180:183], v[64:79]
	ds_read_b128 v[146:149], v128 offset:2048
	s_waitcnt lgkmcnt(5)
	v_mfma_f32_32x32x16_bf16 v[48:63], v[192:195], v[176:179], v[48:63]
	ds_read_b128 v[138:141], v128 offset:4096
	v_mfma_f32_32x32x16_bf16 v[32:47], v[192:195], v[180:183], v[32:47]
	ds_read_b128 v[134:137], v128 offset:6144
	v_lshl_add_u64 v[224:225], v[174:175], 0, s[26:27]
	s_mov_b32 m0, s22
	s_nop 0
	global_load_lds_dwordx4 v[224:225], off
	s_waitcnt lgkmcnt(6)
	v_mfma_f32_32x32x16_bf16 v[16:31], v[240:243], v[176:179], v[16:31]
	s_add_i32 s20, s20, 0x8000
	v_lshl_add_u64 v[172:173], v[172:173], 0, 64
	v_lshl_add_u64 v[174:175], v[174:175], 0, 64
	s_cmp_eq_u32 s20, 0x100000
	v_mfma_f32_32x32x16_bf16 v[0:15], v[240:243], v[180:183], v[0:15]
	s_cbranch_scc0 .LBB0_1161
	s_waitcnt vmcnt(8) lgkmcnt(0)
	s_barrier
	v_add_u32_e32 v128, v202, v200
	ds_read_b128 v[172:175], v128 offset:49152
	ds_read_b128 v[176:179], v128 offset:51200
	v_add_u32_e32 v128, v199, v200
	ds_read_b128 v[180:183], v128 offset:32768
	ds_read_b128 v[184:187], v128 offset:34816
	ds_read_b128 v[188:191], v128 offset:36864
	ds_read_b128 v[192:195], v128 offset:38912
	s_waitcnt lgkmcnt(9)
	v_mfma_f32_32x32x16_bf16 v[112:127], v[150:153], v[142:145], v[112:127]
	v_mfma_f32_32x32x16_bf16 v[96:111], v[150:153], v[130:133], v[96:111]
	s_waitcnt lgkmcnt(8)
	v_mfma_f32_32x32x16_bf16 v[80:95], v[146:149], v[142:145], v[80:95]
	v_mfma_f32_32x32x16_bf16 v[64:79], v[146:149], v[130:133], v[64:79]
	s_waitcnt lgkmcnt(7)
	v_mfma_f32_32x32x16_bf16 v[48:63], v[138:141], v[142:145], v[48:63]
	v_mfma_f32_32x32x16_bf16 v[32:47], v[138:141], v[130:133], v[32:47]
	s_waitcnt lgkmcnt(6)
	v_mfma_f32_32x32x16_bf16 v[16:31], v[134:137], v[142:145], v[16:31]
	v_mfma_f32_32x32x16_bf16 v[0:15], v[134:137], v[130:133], v[0:15]
	v_add_u32_e32 v128, v202, v201
	ds_read_b128 v[130:133], v128 offset:49152
	ds_read_b128 v[134:137], v128 offset:51200
	v_add_u32_e32 v128, v199, v201
	ds_read_b128 v[138:141], v128 offset:32768
	ds_read_b128 v[142:145], v128 offset:34816
	ds_read_b128 v[146:149], v128 offset:36864
	ds_read_b128 v[150:153], v128 offset:38912
	s_waitcnt lgkmcnt(9)
	v_mfma_f32_32x32x16_bf16 v[112:127], v[180:183], v[172:175], v[112:127]
	v_mfma_f32_32x32x16_bf16 v[96:111], v[180:183], v[176:179], v[96:111]
	s_waitcnt lgkmcnt(8)
	v_mfma_f32_32x32x16_bf16 v[80:95], v[184:187], v[172:175], v[80:95]
	v_mfma_f32_32x32x16_bf16 v[64:79], v[184:187], v[176:179], v[64:79]
	s_waitcnt lgkmcnt(7)
	v_mfma_f32_32x32x16_bf16 v[48:63], v[188:191], v[172:175], v[48:63]
	v_mfma_f32_32x32x16_bf16 v[32:47], v[188:191], v[176:179], v[32:47]
	s_waitcnt vmcnt(4) lgkmcnt(0)
	s_barrier
	v_add_u32_e32 v128, v236, v200
	s_waitcnt lgkmcnt(6)
	v_mfma_f32_32x32x16_bf16 v[16:31], v[192:195], v[172:175], v[16:31]
	v_mfma_f32_32x32x16_bf16 v[0:15], v[192:195], v[176:179], v[0:15]
	ds_read_b128 v[172:175], v128 offset:16384
	ds_read_b128 v[176:179], v128 offset:18432
	v_add_u32_e32 v128, v237, v200
	ds_read_b128 v[180:183], v128
	ds_read_b128 v[184:187], v128 offset:2048
	ds_read_b128 v[188:191], v128 offset:4096
	ds_read_b128 v[192:195], v128 offset:6144
	s_waitcnt lgkmcnt(9)
	v_mfma_f32_32x32x16_bf16 v[112:127], v[138:141], v[130:133], v[112:127]
	v_mfma_f32_32x32x16_bf16 v[96:111], v[138:141], v[134:137], v[96:111]
	s_waitcnt lgkmcnt(8)
	v_mfma_f32_32x32x16_bf16 v[80:95], v[142:145], v[130:133], v[80:95]
	v_mfma_f32_32x32x16_bf16 v[64:79], v[142:145], v[134:137], v[64:79]
	s_waitcnt lgkmcnt(7)
	v_mfma_f32_32x32x16_bf16 v[48:63], v[146:149], v[130:133], v[48:63]
	v_mfma_f32_32x32x16_bf16 v[32:47], v[146:149], v[134:137], v[32:47]
	s_waitcnt lgkmcnt(6)
	v_mfma_f32_32x32x16_bf16 v[16:31], v[150:153], v[130:133], v[16:31]
	v_mfma_f32_32x32x16_bf16 v[0:15], v[150:153], v[134:137], v[0:15]
	v_add_u32_e32 v128, v236, v201
	ds_read_b128 v[130:133], v128 offset:16384
	ds_read_b128 v[134:137], v128 offset:18432
	v_add_u32_e32 v128, v237, v201
	ds_read_b128 v[138:141], v128
	ds_read_b128 v[142:145], v128 offset:2048
	ds_read_b128 v[146:149], v128 offset:4096
	ds_read_b128 v[150:153], v128 offset:6144
	s_waitcnt lgkmcnt(9)
	v_mfma_f32_32x32x16_bf16 v[112:127], v[180:183], v[172:175], v[112:127]
	v_mfma_f32_32x32x16_bf16 v[96:111], v[180:183], v[176:179], v[96:111]
	s_waitcnt lgkmcnt(8)
	v_mfma_f32_32x32x16_bf16 v[80:95], v[184:187], v[172:175], v[80:95]
	v_mfma_f32_32x32x16_bf16 v[64:79], v[184:187], v[176:179], v[64:79]
	s_waitcnt lgkmcnt(7)
	v_mfma_f32_32x32x16_bf16 v[48:63], v[188:191], v[172:175], v[48:63]
	v_mfma_f32_32x32x16_bf16 v[32:47], v[188:191], v[176:179], v[32:47]
	s_waitcnt vmcnt(0) lgkmcnt(0)
	s_barrier
	v_add_u32_e32 v128, v234, v200
	s_waitcnt lgkmcnt(6)
	v_mfma_f32_32x32x16_bf16 v[16:31], v[192:195], v[172:175], v[16:31]
	v_mfma_f32_32x32x16_bf16 v[0:15], v[192:195], v[176:179], v[0:15]
	ds_read_b128 v[172:175], v128 offset:16384
	ds_read_b128 v[176:179], v128 offset:18432
	v_add_u32_e32 v128, v235, v200
	ds_read_b128 v[180:183], v128
	ds_read_b128 v[184:187], v128 offset:2048
	ds_read_b128 v[188:191], v128 offset:4096
	ds_read_b128 v[192:195], v128 offset:6144
	s_waitcnt lgkmcnt(9)
	v_mfma_f32_32x32x16_bf16 v[112:127], v[138:141], v[130:133], v[112:127]
	v_mfma_f32_32x32x16_bf16 v[96:111], v[138:141], v[134:137], v[96:111]
	s_waitcnt lgkmcnt(8)
	v_mfma_f32_32x32x16_bf16 v[80:95], v[142:145], v[130:133], v[80:95]
	v_mfma_f32_32x32x16_bf16 v[64:79], v[142:145], v[134:137], v[64:79]
	s_waitcnt lgkmcnt(7)
	v_mfma_f32_32x32x16_bf16 v[48:63], v[146:149], v[130:133], v[48:63]
	v_mfma_f32_32x32x16_bf16 v[32:47], v[146:149], v[134:137], v[32:47]
	s_waitcnt lgkmcnt(6)
	v_mfma_f32_32x32x16_bf16 v[16:31], v[150:153], v[130:133], v[16:31]
	v_mfma_f32_32x32x16_bf16 v[0:15], v[150:153], v[134:137], v[0:15]
	v_add_u32_e32 v128, v234, v201
	ds_read_b128 v[130:133], v128 offset:16384
	ds_read_b128 v[136:139], v128 offset:18432
	v_add_u32_e32 v128, v235, v201
	ds_read_b128 v[140:143], v128
	ds_read_b128 v[144:147], v128 offset:2048
	ds_read_b128 v[148:151], v128 offset:4096
	ds_read_b128 v[240:243], v128 offset:6144
	s_waitcnt lgkmcnt(9)
	v_mfma_f32_32x32x16_bf16 v[112:127], v[180:183], v[172:175], v[112:127]
	v_mfma_f32_32x32x16_bf16 v[96:111], v[180:183], v[176:179], v[96:111]
	s_waitcnt lgkmcnt(8)
	v_mfma_f32_32x32x16_bf16 v[80:95], v[184:187], v[172:175], v[80:95]
	v_mfma_f32_32x32x16_bf16 v[64:79], v[184:187], v[176:179], v[64:79]
	s_waitcnt lgkmcnt(7)
	v_mfma_f32_32x32x16_bf16 v[48:63], v[188:191], v[172:175], v[48:63]
	v_mfma_f32_32x32x16_bf16 v[32:47], v[188:191], v[176:179], v[32:47]
	s_waitcnt lgkmcnt(6)
	v_mfma_f32_32x32x16_bf16 v[16:31], v[192:195], v[172:175], v[16:31]
	v_or_b32_e32 v134, s1, v196
	s_movk_i32 s1, 0x1840
	v_cmp_gt_i32_e32 vcc, s1, v134
	v_mfma_f32_32x32x16_bf16 v[0:15], v[192:195], v[176:179], v[0:15]
	s_waitcnt lgkmcnt(3)
	v_mfma_f32_32x32x16_bf16 v[112:127], v[140:143], v[130:133], v[112:127]
	v_mfma_f32_32x32x16_bf16 v[96:111], v[140:143], v[136:139], v[96:111]
	s_waitcnt lgkmcnt(2)
	v_mfma_f32_32x32x16_bf16 v[80:95], v[144:147], v[130:133], v[80:95]
	v_mfma_f32_32x32x16_bf16 v[64:79], v[144:147], v[136:139], v[64:79]
	s_waitcnt lgkmcnt(1)
	v_mfma_f32_32x32x16_bf16 v[48:63], v[148:151], v[130:133], v[48:63]
	v_mfma_f32_32x32x16_bf16 v[32:47], v[148:151], v[136:139], v[32:47]
	s_waitcnt lgkmcnt(0)
	v_mfma_f32_32x32x16_bf16 v[16:31], v[240:243], v[130:133], v[16:31]
	v_mfma_f32_32x32x16_bf16 v[0:15], v[240:243], v[136:139], v[0:15]
	s_and_saveexec_b64 s[20:21], vcc
	s_cbranch_execz .LBB0_1159
	v_add_u32_e32 v239, s0, v159
	s_movk_i32 s0, 0x7ff
	v_cmp_lt_i32_e32 vcc, s0, v134
	s_and_saveexec_b64 s[0:1], vcc
	s_xor_b64 s[22:23], exec, s[0:1]
	s_cbranch_execz .LBB0_1816
	s_cmpk_lt_u32 s24, 0x1800
	v_or_b32_e32 v130, v134, v197
	s_mov_b64 s[0:1], -1
	s_cbranch_scc0 .LBB0_1302
	v_add_u32_e32 v128, 0xfffff800, v130
	v_lshlrev_b64 v[132:133], 2, v[128:129]
	v_lshl_add_u64 v[134:135], s[16:17], 0, v[132:133]
	v_add_co_u32_e32 v136, vcc, 0x4000, v134
	v_lshl_add_u64 v[132:133], s[18:19], 0, v[132:133]
	s_nop 0
	v_addc_co_u32_e32 v137, vcc, 0, v135, vcc
	v_add_co_u32_e32 v138, vcc, 0x8000, v134
	v_mov_b32_e32 v131, v113
	s_nop 0
	v_addc_co_u32_e32 v139, vcc, 0, v135, vcc
	global_load_dword v188, v[134:135], off
	s_nop 0
	global_load_dword v134, v[136:137], off
	global_load_dword v186, v[138:139], off
	global_load_dword v190, v[132:133], off
	v_ashrrev_i32_e32 v132, 7, v239
	v_ashrrev_i32_e32 v133, 31, v132
	v_lshlrev_b64 v[136:137], 15, v[132:133]
	v_lshl_add_u64 v[178:179], s[2:3], 0, v[136:137]
	v_lshl_add_u64 v[136:137], v[128:129], 1, v[178:179]
	s_and_saveexec_b64 s[0:1], s[6:7]
	s_xor_b64 s[0:1], exec, s[0:1]
	s_cbranch_execz .LBB0_1167
	v_add_co_u32_e32 v138, vcc, 0x4000, v136
	v_cvt_pk_bf16_f32 v131, v30, s0
	s_nop 0
	v_addc_co_u32_e32 v139, vcc, 0, v137, vcc
	global_store_short v[138:139], v131, off
	v_mov_b32_e32 v131, v31

.LBB0_2226:
	s_and_b32 s9, s8, 0x18000
	v_add_u32_e32 v222, s9, v180
	s_add_i32 s9, s8, 0xfffe8000
	s_and_b32 s9, s9, 0x18000
	v_or_b32_e32 v223, s9, v179
	v_add_u32_e32 v233, s9, v176
	s_waitcnt vmcnt(8) lgkmcnt(0)
	s_barrier
	v_mfma_f32_32x32x16_bf16 v[112:127], v[150:153], v[142:145], v[112:127]
	v_mfma_f32_32x32x16_bf16 v[96:111], v[150:153], v[130:133], v[96:111]
	v_add_u32_e32 v206, v223, v177
	v_add_u32_e32 v234, v233, v177
	ds_read_b128 v[202:205], v206 offset:16384
	ds_read_b128 v[206:209], v206 offset:18432
	ds_read_b128 v[210:213], v234
	v_mfma_f32_32x32x16_bf16 v[80:95], v[146:149], v[142:145], v[80:95]
	v_mfma_f32_32x32x16_bf16 v[64:79], v[146:149], v[130:133], v[64:79]
	ds_read_b128 v[214:217], v234 offset:2048
	v_readfirstlane_b32 s9, v222
	s_mov_b32 m0, s9
	s_nop 0
	global_load_lds_dwordx4 v[170:171], off
	v_mfma_f32_32x32x16_bf16 v[48:63], v[138:141], v[142:145], v[48:63]
	v_mfma_f32_32x32x16_bf16 v[32:47], v[138:141], v[130:133], v[32:47]
	ds_read_b128 v[224:227], v234 offset:4096
	s_add_i32 s10, s9, 0x2000
	v_lshl_add_u64 v[150:151], v[170:171], 0, s[12:13]
	s_mov_b32 m0, s10
	s_nop 0
	global_load_lds_dwordx4 v[150:151], off
	v_mfma_f32_32x32x16_bf16 v[16:31], v[134:137], v[142:145], v[16:31]
	v_mfma_f32_32x32x16_bf16 v[0:15], v[134:137], v[130:133], v[0:15]
	ds_read_b128 v[234:237], v234 offset:6144
	s_waitcnt lgkmcnt(3)
	v_mfma_f32_32x32x16_bf16 v[112:127], v[210:213], v[202:205], v[112:127]
	v_add_u32_e32 v130, v223, v178
	v_add_u32_e32 v134, v233, v178
	ds_read_b128 v[142:145], v130 offset:16384
	v_mfma_f32_32x32x16_bf16 v[96:111], v[210:213], v[206:209], v[96:111]
	ds_read_b128 v[130:133], v130 offset:18432
	s_add_i32 s10, s9, 0x6000
	s_addk_i32 s9, 0x4000
	s_mov_b32 m0, s9
	s_nop 0
	global_load_lds_dwordx4 v[172:173], off
	s_waitcnt lgkmcnt(4)
	v_mfma_f32_32x32x16_bf16 v[80:95], v[214:217], v[202:205], v[80:95]
	ds_read_b128 v[150:153], v134
	v_mfma_f32_32x32x16_bf16 v[64:79], v[214:217], v[206:209], v[64:79]
	ds_read_b128 v[146:149], v134 offset:2048
	s_waitcnt lgkmcnt(5)
	v_mfma_f32_32x32x16_bf16 v[48:63], v[224:227], v[202:205], v[48:63]
	ds_read_b128 v[138:141], v134 offset:4096
	v_mfma_f32_32x32x16_bf16 v[32:47], v[224:227], v[206:209], v[32:47]
	ds_read_b128 v[134:137], v134 offset:6144
	v_lshl_add_u64 v[222:223], v[172:173], 0, s[12:13]
	s_mov_b32 m0, s10
	s_nop 0
	global_load_lds_dwordx4 v[222:223], off
	s_waitcnt lgkmcnt(6)
	v_mfma_f32_32x32x16_bf16 v[16:31], v[234:237], v[202:205], v[16:31]
	s_add_i32 s8, s8, 0x8000
	v_lshl_add_u64 v[170:171], v[170:171], 0, 64
	v_lshl_add_u64 v[172:173], v[172:173], 0, 64
	s_cmp_eq_u32 s8, 0x200000
	v_mfma_f32_32x32x16_bf16 v[0:15], v[234:237], v[206:209], v[0:15]
	s_cbranch_scc0 .LBB0_2226
	s_waitcnt vmcnt(8) lgkmcnt(0)
	s_barrier
	v_add_u32_e32 v202, v179, v177
	v_add_u32_e32 v222, v176, v177
	ds_read_b128 v[170:173], v202 offset:49152
	ds_read_b128 v[202:205], v202 offset:51200
	ds_read_b128 v[206:209], v222 offset:32768
	ds_read_b128 v[210:213], v222 offset:34816
	ds_read_b128 v[214:217], v222 offset:36864
	ds_read_b128 v[224:227], v222 offset:38912
	s_waitcnt lgkmcnt(9)
	v_mfma_f32_32x32x16_bf16 v[112:127], v[150:153], v[142:145], v[112:127]
	v_mfma_f32_32x32x16_bf16 v[96:111], v[150:153], v[130:133], v[96:111]
	s_waitcnt lgkmcnt(8)
	v_mfma_f32_32x32x16_bf16 v[80:95], v[146:149], v[142:145], v[80:95]
	v_mfma_f32_32x32x16_bf16 v[64:79], v[146:149], v[130:133], v[64:79]
	s_waitcnt lgkmcnt(7)
	v_mfma_f32_32x32x16_bf16 v[48:63], v[138:141], v[142:145], v[48:63]
	v_mfma_f32_32x32x16_bf16 v[32:47], v[138:141], v[130:133], v[32:47]
	s_waitcnt lgkmcnt(6)
	v_mfma_f32_32x32x16_bf16 v[16:31], v[134:137], v[142:145], v[16:31]
	v_mfma_f32_32x32x16_bf16 v[0:15], v[134:137], v[130:133], v[0:15]
	v_add_u32_e32 v134, v179, v178
	v_add_u32_e32 v150, v176, v178
	ds_read_b128 v[130:133], v134 offset:49152
	ds_read_b128 v[134:137], v134 offset:51200
	ds_read_b128 v[138:141], v150 offset:32768
	ds_read_b128 v[142:145], v150 offset:34816
	ds_read_b128 v[146:149], v150 offset:36864
	ds_read_b128 v[150:153], v150 offset:38912
	s_waitcnt lgkmcnt(9)
	v_mfma_f32_32x32x16_bf16 v[112:127], v[206:209], v[170:173], v[112:127]
	v_mfma_f32_32x32x16_bf16 v[96:111], v[206:209], v[202:205], v[96:111]
	s_waitcnt lgkmcnt(8)
	v_mfma_f32_32x32x16_bf16 v[80:95], v[210:213], v[170:173], v[80:95]
	v_mfma_f32_32x32x16_bf16 v[64:79], v[210:213], v[202:205], v[64:79]
	s_waitcnt lgkmcnt(7)
	v_mfma_f32_32x32x16_bf16 v[48:63], v[214:217], v[170:173], v[48:63]
	v_mfma_f32_32x32x16_bf16 v[32:47], v[214:217], v[202:205], v[32:47]
	s_waitcnt lgkmcnt(6)
	v_mfma_f32_32x32x16_bf16 v[0:15], v[224:227], v[202:205], v[0:15]
	s_waitcnt vmcnt(4) lgkmcnt(0)
	s_barrier
	v_add_u32_e32 v202, v199, v177
	v_add_u32_e32 v222, v200, v177
	v_mfma_f32_32x32x16_bf16 v[16:31], v[224:227], v[170:173], v[16:31]
	ds_read_b128 v[170:173], v202 offset:16384
	ds_read_b128 v[202:205], v202 offset:18432
	ds_read_b128 v[206:209], v222
	ds_read_b128 v[210:213], v222 offset:2048
	ds_read_b128 v[214:217], v222 offset:4096
	ds_read_b128 v[224:227], v222 offset:6144
	s_waitcnt lgkmcnt(9)
	v_mfma_f32_32x32x16_bf16 v[112:127], v[138:141], v[130:133], v[112:127]
	v_mfma_f32_32x32x16_bf16 v[96:111], v[138:141], v[134:137], v[96:111]
	s_waitcnt lgkmcnt(8)
	v_mfma_f32_32x32x16_bf16 v[80:95], v[142:145], v[130:133], v[80:95]
	v_mfma_f32_32x32x16_bf16 v[64:79], v[142:145], v[134:137], v[64:79]
	s_waitcnt lgkmcnt(7)
	v_mfma_f32_32x32x16_bf16 v[48:63], v[146:149], v[130:133], v[48:63]
	v_mfma_f32_32x32x16_bf16 v[32:47], v[146:149], v[134:137], v[32:47]
	s_waitcnt lgkmcnt(6)
	v_mfma_f32_32x32x16_bf16 v[16:31], v[150:153], v[130:133], v[16:31]
	v_mfma_f32_32x32x16_bf16 v[0:15], v[150:153], v[134:137], v[0:15]
	v_add_u32_e32 v134, v199, v178
	v_add_u32_e32 v150, v200, v178
	ds_read_b128 v[130:133], v134 offset:16384
	ds_read_b128 v[134:137], v134 offset:18432
	ds_read_b128 v[138:141], v150
	ds_read_b128 v[142:145], v150 offset:2048
	ds_read_b128 v[146:149], v150 offset:4096
	ds_read_b128 v[150:153], v150 offset:6144
	s_waitcnt lgkmcnt(9)
	v_mfma_f32_32x32x16_bf16 v[112:127], v[206:209], v[170:173], v[112:127]
	v_mfma_f32_32x32x16_bf16 v[96:111], v[206:209], v[202:205], v[96:111]
	s_waitcnt lgkmcnt(8)
	v_mfma_f32_32x32x16_bf16 v[80:95], v[210:213], v[170:173], v[80:95]
	v_mfma_f32_32x32x16_bf16 v[64:79], v[210:213], v[202:205], v[64:79]
	s_waitcnt lgkmcnt(7)
	v_mfma_f32_32x32x16_bf16 v[48:63], v[214:217], v[170:173], v[48:63]
	v_mfma_f32_32x32x16_bf16 v[32:47], v[214:217], v[202:205], v[32:47]
	s_waitcnt lgkmcnt(6)
	v_mfma_f32_32x32x16_bf16 v[0:15], v[224:227], v[202:205], v[0:15]
	s_waitcnt vmcnt(0) lgkmcnt(0)
	s_barrier
	v_add_u32_e32 v202, v197, v177
	v_add_u32_e32 v222, v198, v177
	v_mfma_f32_32x32x16_bf16 v[16:31], v[224:227], v[170:173], v[16:31]
	ds_read_b128 v[170:173], v202 offset:16384
	ds_read_b128 v[202:205], v202 offset:18432
	ds_read_b128 v[206:209], v222
	ds_read_b128 v[210:213], v222 offset:2048
	ds_read_b128 v[214:217], v222 offset:4096
	ds_read_b128 v[224:227], v222 offset:6144
	s_waitcnt lgkmcnt(9)
	v_mfma_f32_32x32x16_bf16 v[112:127], v[138:141], v[130:133], v[112:127]
	v_mfma_f32_32x32x16_bf16 v[96:111], v[138:141], v[134:137], v[96:111]
	s_waitcnt lgkmcnt(8)
	v_mfma_f32_32x32x16_bf16 v[80:95], v[142:145], v[130:133], v[80:95]
	v_mfma_f32_32x32x16_bf16 v[64:79], v[142:145], v[134:137], v[64:79]
	s_waitcnt lgkmcnt(7)
	v_mfma_f32_32x32x16_bf16 v[48:63], v[146:149], v[130:133], v[48:63]
	v_mfma_f32_32x32x16_bf16 v[32:47], v[146:149], v[134:137], v[32:47]
	s_waitcnt lgkmcnt(6)
	v_mfma_f32_32x32x16_bf16 v[16:31], v[150:153], v[130:133], v[16:31]
	v_mfma_f32_32x32x16_bf16 v[0:15], v[150:153], v[134:137], v[0:15]
	v_add_u32_e32 v134, v197, v178
	v_add_u32_e32 v150, v198, v178
	ds_read_b128 v[130:133], v134 offset:16384
	ds_read_b128 v[134:137], v134 offset:18432
	ds_read_b128 v[138:141], v150
	ds_read_b128 v[142:145], v150 offset:2048
	ds_read_b128 v[146:149], v150 offset:4096
	ds_read_b128 v[150:153], v150 offset:6144
	s_waitcnt lgkmcnt(9)
	v_mfma_f32_32x32x16_bf16 v[112:127], v[206:209], v[170:173], v[112:127]
	v_mfma_f32_32x32x16_bf16 v[96:111], v[206:209], v[202:205], v[96:111]
	s_waitcnt lgkmcnt(8)
	v_mfma_f32_32x32x16_bf16 v[80:95], v[210:213], v[170:173], v[80:95]
	v_mfma_f32_32x32x16_bf16 v[64:79], v[210:213], v[202:205], v[64:79]
	s_waitcnt lgkmcnt(7)
	v_mfma_f32_32x32x16_bf16 v[48:63], v[214:217], v[170:173], v[48:63]
	v_mfma_f32_32x32x16_bf16 v[32:47], v[214:217], v[202:205], v[32:47]
	s_waitcnt lgkmcnt(6)
	v_mfma_f32_32x32x16_bf16 v[16:31], v[224:227], v[170:173], v[16:31]
	v_mfma_f32_32x32x16_bf16 v[0:15], v[224:227], v[202:205], v[0:15]
	s_waitcnt lgkmcnt(3)
	v_mfma_f32_32x32x16_bf16 v[112:127], v[138:141], v[130:133], v[112:127]
	s_waitcnt lgkmcnt(2)
	v_mfma_f32_32x32x16_bf16 v[80:95], v[142:145], v[130:133], v[80:95]
	s_waitcnt lgkmcnt(1)
	v_mfma_f32_32x32x16_bf16 v[48:63], v[146:149], v[130:133], v[48:63]
	s_waitcnt lgkmcnt(0)
	v_mfma_f32_32x32x16_bf16 v[16:31], v[150:153], v[130:133], v[16:31]
	v_add_u32_e32 v132, s6, v174
	v_or_b32_e32 v130, s7, v128
	v_ashrrev_i32_e32 v131, 31, v130
	v_lshl_add_u64 v[130:131], v[130:131], 1, v[158:159]
	v_readlane_b32 s6, v252, 7
	s_add_i32 s4, s4, s6
	s_add_i32 s2, s2, s6
	v_mfma_f32_32x32x16_bf16 v[96:111], v[138:141], v[134:137], v[96:111]
	v_or_b32_e32 v138, v132, v181
	v_ashrrev_i32_e32 v139, 31, v138
	v_readlane_b32 s6, v252, 8
	s_add_i32 s5, s5, s6
	s_cmp_gt_i32 s4, 31
	v_mfma_f32_32x32x16_bf16 v[64:79], v[142:145], v[134:137], v[64:79]
	v_mfma_f32_32x32x16_bf16 v[32:47], v[146:149], v[134:137], v[32:47]
	v_mfma_f32_32x32x16_bf16 v[0:15], v[150:153], v[134:137], v[0:15]
	v_and_b32_e32 v134, 0xff, v138
	v_lshl_add_u32 v134, v134, 2, v250
	ds_read_b96 v[134:136], v134
	v_lshlrev_b64 v[138:139], 11, v[138:139]
	v_lshl_add_u64 v[138:139], v[130:131], 0, v[138:139]
	s_waitcnt lgkmcnt(0)
	v_mul_f32_e32 v112, v112, v134
	v_mul_f32_e32 v96, v96, v134
	v_cvt_pk_bf16_f32 v112, v112, s0
	v_cvt_pk_bf16_f32 v96, v96, s0
	global_store_short v[138:139], v112, off
	global_store_short v[138:139], v96, off offset:64
	v_or_b32_e32 v138, v132, v182
	v_ashrrev_i32_e32 v139, 31, v138
	v_lshlrev_b64 v[138:139], 11, v[138:139]
	v_mul_f32_e32 v96, v113, v135
	v_lshl_add_u64 v[138:139], v[130:131], 0, v[138:139]
	v_cvt_pk_bf16_f32 v96, v96, s0
	global_store_short v[138:139], v96, off
	v_mul_f32_e32 v96, v97, v135
	v_cvt_pk_bf16_f32 v96, v96, s0
	global_store_short v[138:139], v96, off offset:64
	v_or_b32_e32 v96, v132, v183
	v_ashrrev_i32_e32 v97, 31, v96
	v_lshlrev_b64 v[96:97], 11, v[96:97]
	v_mul_f32_e32 v112, v114, v136
	v_mul_f32_e32 v98, v98, v136
	v_lshl_add_u64 v[96:97], v[130:131], 0, v[96:97]
	v_cvt_pk_bf16_f32 v112, v112, s0
	v_cvt_pk_bf16_f32 v98, v98, s0
	global_store_short v[96:97], v112, off
	global_store_short v[96:97], v98, off offset:64
	v_or_b32_e32 v96, v132, v184
	v_ashrrev_i32_e32 v97, 31, v96
	v_and_b32_e32 v112, 0xff, v96
	v_lshl_add_u32 v112, v112, 2, v250
	ds_read_b32 v98, v112
	v_lshlrev_b64 v[96:97], 11, v[96:97]
	v_lshl_add_u64 v[96:97], v[130:131], 0, v[96:97]
	s_waitcnt lgkmcnt(0)
	v_mul_f32_e32 v112, v115, v98
	v_cvt_pk_bf16_f32 v112, v112, s0
	global_store_short v[96:97], v112, off
	v_mul_f32_e32 v98, v99, v98
	v_or_b32_e32 v112, v132, v185
	v_cvt_pk_bf16_f32 v98, v98, s0
	v_ashrrev_i32_e32 v113, 31, v112
	global_store_short v[96:97], v98, off offset:64
	v_and_b32_e32 v96, 0xff, v112
	v_lshl_add_u32 v96, v96, 2, v250
	ds_read_b96 v[96:98], v96
	v_lshlrev_b64 v[112:113], 11, v[112:113]
	v_lshl_add_u64 v[112:113], v[130:131], 0, v[112:113]
	s_waitcnt lgkmcnt(0)
	v_mul_f32_e32 v99, v116, v96
	v_mul_f32_e32 v96, v100, v96
	v_cvt_pk_bf16_f32 v99, v99, s0
	v_cvt_pk_bf16_f32 v96, v96, s0
	global_store_short v[112:113], v99, off
	global_store_short v[112:113], v96, off offset:64
	v_or_b32_e32 v112, v132, v186
	v_ashrrev_i32_e32 v113, 31, v112
	v_lshlrev_b64 v[112:113], 11, v[112:113]
	v_mul_f32_e32 v96, v117, v97
	v_lshl_add_u64 v[112:113], v[130:131], 0, v[112:113]
	v_cvt_pk_bf16_f32 v96, v96, s0
	global_store_short v[112:113], v96, off
	v_mul_f32_e32 v96, v101, v97
	v_cvt_pk_bf16_f32 v96, v96, s0
	global_store_short v[112:113], v96, off offset:64
	v_or_b32_e32 v96, v132, v187
	v_ashrrev_i32_e32 v97, 31, v96
	v_lshlrev_b64 v[96:97], 11, v[96:97]
	v_mul_f32_e32 v99, v118, v98
	v_mul_f32_e32 v98, v102, v98
	v_lshl_add_u64 v[96:97], v[130:131], 0, v[96:97]
	v_cvt_pk_bf16_f32 v99, v99, s0
	v_cvt_pk_bf16_f32 v98, v98, s0
	global_store_short v[96:97], v99, off
	global_store_short v[96:97], v98, off offset:64
	v_or_b32_e32 v96, v132, v188
	v_ashrrev_i32_e32 v97, 31, v96
	v_and_b32_e32 v98, 0xff, v96
	v_lshl_add_u32 v98, v98, 2, v250
	ds_read_b32 v98, v98
	v_lshlrev_b64 v[96:97], 11, v[96:97]
	v_or_b32_e32 v100, v132, v189
	v_lshl_add_u64 v[96:97], v[130:131], 0, v[96:97]
	v_ashrrev_i32_e32 v101, 31, v100
	s_waitcnt lgkmcnt(0)
	v_mul_f32_e32 v99, v119, v98
	v_mul_f32_e32 v98, v103, v98
	v_cvt_pk_bf16_f32 v99, v99, s0
	v_cvt_pk_bf16_f32 v98, v98, s0
	global_store_short v[96:97], v99, off
	global_store_short v[96:97], v98, off offset:64
	v_and_b32_e32 v96, 0xff, v100
	v_lshl_add_u32 v96, v96, 2, v250
	ds_read_b96 v[96:98], v96
	v_lshlrev_b64 v[100:101], 11, v[100:101]
	v_lshl_add_u64 v[100:101], v[130:131], 0, v[100:101]
	s_waitcnt lgkmcnt(0)
	v_mul_f32_e32 v99, v120, v96
	v_mul_f32_e32 v96, v104, v96
	v_cvt_pk_bf16_f32 v99, v99, s0
	v_cvt_pk_bf16_f32 v96, v96, s0
	global_store_short v[100:101], v99, off
	global_store_short v[100:101], v96, off offset:64
	v_or_b32_e32 v100, v132, v190
	v_ashrrev_i32_e32 v101, 31, v100
	v_lshlrev_b64 v[100:101], 11, v[100:101]
	v_mul_f32_e32 v96, v121, v97
	v_lshl_add_u64 v[100:101], v[130:131], 0, v[100:101]
	v_cvt_pk_bf16_f32 v96, v96, s0
	global_store_short v[100:101], v96, off
	v_mul_f32_e32 v96, v105, v97
	v_cvt_pk_bf16_f32 v96, v96, s0
	global_store_short v[100:101], v96, off offset:64
	v_or_b32_e32 v96, v132, v191
	v_ashrrev_i32_e32 v97, 31, v96
	v_lshlrev_b64 v[96:97], 11, v[96:97]
	v_mul_f32_e32 v99, v122, v98
	v_mul_f32_e32 v98, v106, v98
	v_lshl_add_u64 v[96:97], v[130:131], 0, v[96:97]
	v_cvt_pk_bf16_f32 v99, v99, s0
	v_cvt_pk_bf16_f32 v98, v98, s0
	global_store_short v[96:97], v99, off
	global_store_short v[96:97], v98, off offset:64
	v_or_b32_e32 v96, v132, v192
	v_ashrrev_i32_e32 v97, 31, v96
	v_and_b32_e32 v98, 0xff, v96
	v_lshl_add_u32 v98, v98, 2, v250
	ds_read_b32 v98, v98
	v_lshlrev_b64 v[96:97], 11, v[96:97]
	v_or_b32_e32 v100, v132, v193
	v_lshl_add_u64 v[96:97], v[130:131], 0, v[96:97]
	v_ashrrev_i32_e32 v101, 31, v100
	s_waitcnt lgkmcnt(0)
	v_mul_f32_e32 v99, v123, v98
	v_mul_f32_e32 v98, v107, v98
	v_cvt_pk_bf16_f32 v99, v99, s0
	v_cvt_pk_bf16_f32 v98, v98, s0
	global_store_short v[96:97], v99, off
	global_store_short v[96:97], v98, off offset:64
	v_and_b32_e32 v96, 0xff, v100
	v_lshl_add_u32 v96, v96, 2, v250
	ds_read_b96 v[96:98], v96
	v_lshlrev_b64 v[100:101], 11, v[100:101]
	v_lshl_add_u64 v[100:101], v[130:131], 0, v[100:101]
	s_waitcnt lgkmcnt(0)
	v_mul_f32_e32 v99, v124, v96
	v_mul_f32_e32 v96, v108, v96
	v_cvt_pk_bf16_f32 v99, v99, s0
	v_cvt_pk_bf16_f32 v96, v96, s0
	global_store_short v[100:101], v99, off
	global_store_short v[100:101], v96, off offset:64
	v_or_b32_e32 v100, v132, v194
	v_ashrrev_i32_e32 v101, 31, v100
	v_lshlrev_b64 v[100:101], 11, v[100:101]
	v_mul_f32_e32 v96, v125, v97
	v_lshl_add_u64 v[100:101], v[130:131], 0, v[100:101]
	v_cvt_pk_bf16_f32 v96, v96, s0
	global_store_short v[100:101], v96, off
	v_mul_f32_e32 v96, v109, v97
	v_cvt_pk_bf16_f32 v96, v96, s0
	global_store_short v[100:101], v96, off offset:64
	v_or_b32_e32 v96, v132, v195
	v_ashrrev_i32_e32 v97, 31, v96
	v_lshlrev_b64 v[96:97], 11, v[96:97]
	v_mul_f32_e32 v99, v126, v98
	v_mul_f32_e32 v98, v110, v98
	v_lshl_add_u64 v[96:97], v[130:131], 0, v[96:97]
	v_cvt_pk_bf16_f32 v99, v99, s0
	v_cvt_pk_bf16_f32 v98, v98, s0
	global_store_short v[96:97], v99, off
	global_store_short v[96:97], v98, off offset:64
	v_or_b32_e32 v96, v132, v196
	v_ashrrev_i32_e32 v97, 31, v96
	v_and_b32_e32 v98, 0xff, v96
	v_lshl_add_u32 v98, v98, 2, v250
	ds_read_b32 v98, v98
	v_lshlrev_b64 v[96:97], 11, v[96:97]
	v_lshl_add_u64 v[96:97], v[130:131], 0, v[96:97]
	s_waitcnt lgkmcnt(0)
	v_mul_f32_e32 v99, v127, v98
	v_mul_f32_e32 v98, v111, v98
	v_cvt_pk_bf16_f32 v99, v99, s0
	v_cvt_pk_bf16_f32 v98, v98, s0
	global_store_short v[96:97], v99, off
	global_store_short v[96:97], v98, off offset:64
	v_or_b32_e32 v96, 32, v132
	v_or_b32_e32 v102, v96, v181
	v_ashrrev_i32_e32 v103, 31, v102
	v_and_b32_e32 v98, 0xff, v102
	v_lshl_add_u32 v98, v98, 2, v250
	ds_read_b96 v[98:100], v98
	v_lshlrev_b64 v[102:103], 11, v[102:103]
	v_lshl_add_u64 v[102:103], v[130:131], 0, v[102:103]
	s_waitcnt lgkmcnt(0)
	v_mul_f32_e32 v80, v80, v98
	v_mul_f32_e32 v64, v64, v98
	v_cvt_pk_bf16_f32 v80, v80, s0
	v_cvt_pk_bf16_f32 v64, v64, s0
	global_store_short v[102:103], v80, off
	global_store_short v[102:103], v64, off offset:64
	v_or_b32_e32 v102, v96, v182
	v_ashrrev_i32_e32 v103, 31, v102
	v_lshlrev_b64 v[102:103], 11, v[102:103]
	v_mul_f32_e32 v64, v81, v99
	v_lshl_add_u64 v[102:103], v[130:131], 0, v[102:103]
	v_cvt_pk_bf16_f32 v64, v64, s0
	global_store_short v[102:103], v64, off
	v_mul_f32_e32 v64, v65, v99
	v_cvt_pk_bf16_f32 v64, v64, s0
	global_store_short v[102:103], v64, off offset:64
	v_or_b32_e32 v64, v96, v183
	v_ashrrev_i32_e32 v65, 31, v64
	v_lshlrev_b64 v[64:65], 11, v[64:65]
	v_mul_f32_e32 v80, v82, v100
	v_mul_f32_e32 v66, v66, v100
	v_lshl_add_u64 v[64:65], v[130:131], 0, v[64:65]
	v_cvt_pk_bf16_f32 v80, v80, s0
	v_cvt_pk_bf16_f32 v66, v66, s0
	global_store_short v[64:65], v80, off
	global_store_short v[64:65], v66, off offset:64
	v_or_b32_e32 v64, v96, v184
	v_ashrrev_i32_e32 v65, 31, v64
	v_and_b32_e32 v80, 0xff, v64
	v_lshl_add_u32 v80, v80, 2, v250
	ds_read_b32 v66, v80
	v_lshlrev_b64 v[64:65], 11, v[64:65]
	v_lshl_add_u64 v[64:65], v[130:131], 0, v[64:65]
	s_waitcnt lgkmcnt(0)
	v_mul_f32_e32 v80, v83, v66
	v_cvt_pk_bf16_f32 v80, v80, s0
	global_store_short v[64:65], v80, off
	v_mul_f32_e32 v66, v67, v66
	v_or_b32_e32 v80, v96, v185
	v_cvt_pk_bf16_f32 v66, v66, s0
	v_ashrrev_i32_e32 v81, 31, v80
	global_store_short v[64:65], v66, off offset:64
	v_and_b32_e32 v64, 0xff, v80
	v_lshl_add_u32 v64, v64, 2, v250
	ds_read_b96 v[64:66], v64
	v_lshlrev_b64 v[80:81], 11, v[80:81]
	v_lshl_add_u64 v[80:81], v[130:131], 0, v[80:81]
	s_waitcnt lgkmcnt(0)
	v_mul_f32_e32 v67, v84, v64
	v_mul_f32_e32 v64, v68, v64
	v_cvt_pk_bf16_f32 v67, v67, s0
	v_cvt_pk_bf16_f32 v64, v64, s0
	global_store_short v[80:81], v67, off
	global_store_short v[80:81], v64, off offset:64
	v_or_b32_e32 v80, v96, v186
	v_ashrrev_i32_e32 v81, 31, v80
	v_lshlrev_b64 v[80:81], 11, v[80:81]
	v_mul_f32_e32 v64, v85, v65
	v_lshl_add_u64 v[80:81], v[130:131], 0, v[80:81]
	v_cvt_pk_bf16_f32 v64, v64, s0
	global_store_short v[80:81], v64, off
	v_mul_f32_e32 v64, v69, v65
	v_cvt_pk_bf16_f32 v64, v64, s0
	global_store_short v[80:81], v64, off offset:64
	v_or_b32_e32 v64, v96, v187
	v_ashrrev_i32_e32 v65, 31, v64
	v_lshlrev_b64 v[64:65], 11, v[64:65]
	v_mul_f32_e32 v67, v86, v66
	v_mul_f32_e32 v66, v70, v66
	v_lshl_add_u64 v[64:65], v[130:131], 0, v[64:65]
	v_cvt_pk_bf16_f32 v67, v67, s0
	v_cvt_pk_bf16_f32 v66, v66, s0
	global_store_short v[64:65], v67, off
	global_store_short v[64:65], v66, off offset:64
	v_or_b32_e32 v64, v96, v188
	v_ashrrev_i32_e32 v65, 31, v64
	v_and_b32_e32 v66, 0xff, v64
	v_lshl_add_u32 v66, v66, 2, v250
	ds_read_b32 v66, v66
	v_lshlrev_b64 v[64:65], 11, v[64:65]
	v_or_b32_e32 v68, v96, v189
	v_lshl_add_u64 v[64:65], v[130:131], 0, v[64:65]
	v_ashrrev_i32_e32 v69, 31, v68
	s_waitcnt lgkmcnt(0)
	v_mul_f32_e32 v67, v87, v66
	v_mul_f32_e32 v66, v71, v66
	v_cvt_pk_bf16_f32 v67, v67, s0
	v_cvt_pk_bf16_f32 v66, v66, s0
	global_store_short v[64:65], v67, off
	global_store_short v[64:65], v66, off offset:64
	v_and_b32_e32 v64, 0xff, v68
	v_lshl_add_u32 v64, v64, 2, v250
	ds_read_b96 v[64:66], v64
	v_lshlrev_b64 v[68:69], 11, v[68:69]
	v_lshl_add_u64 v[68:69], v[130:131], 0, v[68:69]
	s_waitcnt lgkmcnt(0)
	v_mul_f32_e32 v67, v88, v64
	v_mul_f32_e32 v64, v72, v64
	v_cvt_pk_bf16_f32 v67, v67, s0
	v_cvt_pk_bf16_f32 v64, v64, s0
	global_store_short v[68:69], v67, off
	global_store_short v[68:69], v64, off offset:64
	v_or_b32_e32 v68, v96, v190
	v_ashrrev_i32_e32 v69, 31, v68
	v_lshlrev_b64 v[68:69], 11, v[68:69]
	v_mul_f32_e32 v64, v89, v65
	v_lshl_add_u64 v[68:69], v[130:131], 0, v[68:69]
	v_cvt_pk_bf16_f32 v64, v64, s0
	global_store_short v[68:69], v64, off
	v_mul_f32_e32 v64, v73, v65
	v_cvt_pk_bf16_f32 v64, v64, s0
	global_store_short v[68:69], v64, off offset:64
	v_or_b32_e32 v64, v96, v191
	v_ashrrev_i32_e32 v65, 31, v64
	v_lshlrev_b64 v[64:65], 11, v[64:65]
	v_mul_f32_e32 v67, v90, v66
	v_mul_f32_e32 v66, v74, v66
	v_lshl_add_u64 v[64:65], v[130:131], 0, v[64:65]
	v_cvt_pk_bf16_f32 v67, v67, s0
	v_cvt_pk_bf16_f32 v66, v66, s0
	global_store_short v[64:65], v67, off
	global_store_short v[64:65], v66, off offset:64
	v_or_b32_e32 v64, v96, v192
	v_ashrrev_i32_e32 v65, 31, v64
	v_and_b32_e32 v66, 0xff, v64
	v_lshl_add_u32 v66, v66, 2, v250
	ds_read_b32 v66, v66
	v_lshlrev_b64 v[64:65], 11, v[64:65]
	v_or_b32_e32 v68, v96, v193
	v_lshl_add_u64 v[64:65], v[130:131], 0, v[64:65]
	v_ashrrev_i32_e32 v69, 31, v68
	s_waitcnt lgkmcnt(0)
	v_mul_f32_e32 v67, v91, v66
	v_mul_f32_e32 v66, v75, v66
	v_cvt_pk_bf16_f32 v67, v67, s0
	v_cvt_pk_bf16_f32 v66, v66, s0
	global_store_short v[64:65], v67, off
	global_store_short v[64:65], v66, off offset:64
	v_and_b32_e32 v64, 0xff, v68
	v_lshl_add_u32 v64, v64, 2, v250
	ds_read_b96 v[64:66], v64
	v_lshlrev_b64 v[68:69], 11, v[68:69]
	v_lshl_add_u64 v[68:69], v[130:131], 0, v[68:69]
	s_waitcnt lgkmcnt(0)
	v_mul_f32_e32 v67, v92, v64
	v_mul_f32_e32 v64, v76, v64
	v_cvt_pk_bf16_f32 v67, v67, s0
	v_cvt_pk_bf16_f32 v64, v64, s0
	global_store_short v[68:69], v67, off
	global_store_short v[68:69], v64, off offset:64
	v_or_b32_e32 v68, v96, v194
	v_ashrrev_i32_e32 v69, 31, v68
	v_lshlrev_b64 v[68:69], 11, v[68:69]
	v_mul_f32_e32 v64, v93, v65
	v_lshl_add_u64 v[68:69], v[130:131], 0, v[68:69]
	v_cvt_pk_bf16_f32 v64, v64, s0
	global_store_short v[68:69], v64, off
	v_mul_f32_e32 v64, v77, v65
	v_cvt_pk_bf16_f32 v64, v64, s0
	global_store_short v[68:69], v64, off offset:64
	v_or_b32_e32 v64, v96, v195
	v_ashrrev_i32_e32 v65, 31, v64
	v_lshlrev_b64 v[64:65], 11, v[64:65]
	v_mul_f32_e32 v67, v94, v66
	v_mul_f32_e32 v66, v78, v66
	v_lshl_add_u64 v[64:65], v[130:131], 0, v[64:65]
	v_cvt_pk_bf16_f32 v67, v67, s0
	v_cvt_pk_bf16_f32 v66, v66, s0
	global_store_short v[64:65], v67, off
	global_store_short v[64:65], v66, off offset:64
	v_or_b32_e32 v64, v96, v196
	v_ashrrev_i32_e32 v65, 31, v64
	v_and_b32_e32 v66, 0xff, v64
	v_lshl_add_u32 v66, v66, 2, v250
	ds_read_b32 v66, v66
	v_lshlrev_b64 v[64:65], 11, v[64:65]
	v_lshl_add_u64 v[64:65], v[130:131], 0, v[64:65]
	s_waitcnt lgkmcnt(0)
	v_mul_f32_e32 v67, v95, v66
	v_mul_f32_e32 v66, v79, v66
	v_cvt_pk_bf16_f32 v67, v67, s0
	v_cvt_pk_bf16_f32 v66, v66, s0
	global_store_short v[64:65], v67, off
	global_store_short v[64:65], v66, off offset:64
	v_or_b32_e32 v64, 64, v132
	v_or_b32_e32 v70, v64, v181
	v_ashrrev_i32_e32 v71, 31, v70
	v_and_b32_e32 v66, 0xff, v70
	v_lshl_add_u32 v66, v66, 2, v250
	ds_read_b96 v[66:68], v66
	v_lshlrev_b64 v[70:71], 11, v[70:71]
	v_lshl_add_u64 v[70:71], v[130:131], 0, v[70:71]
	s_waitcnt lgkmcnt(0)
	v_mul_f32_e32 v48, v48, v66
	v_mul_f32_e32 v32, v32, v66
	v_cvt_pk_bf16_f32 v48, v48, s0
	v_cvt_pk_bf16_f32 v32, v32, s0
	global_store_short v[70:71], v48, off
	global_store_short v[70:71], v32, off offset:64
	v_or_b32_e32 v70, v64, v182
	v_ashrrev_i32_e32 v71, 31, v70
	v_lshlrev_b64 v[70:71], 11, v[70:71]
	v_mul_f32_e32 v32, v49, v67
	v_lshl_add_u64 v[70:71], v[130:131], 0, v[70:71]
	v_cvt_pk_bf16_f32 v32, v32, s0
	global_store_short v[70:71], v32, off
	v_mul_f32_e32 v32, v33, v67
	v_cvt_pk_bf16_f32 v32, v32, s0
	global_store_short v[70:71], v32, off offset:64
	v_or_b32_e32 v32, v64, v183
	v_ashrrev_i32_e32 v33, 31, v32
	v_lshlrev_b64 v[32:33], 11, v[32:33]
	v_mul_f32_e32 v48, v50, v68
	v_mul_f32_e32 v34, v34, v68
	v_lshl_add_u64 v[32:33], v[130:131], 0, v[32:33]
	v_cvt_pk_bf16_f32 v48, v48, s0
	v_cvt_pk_bf16_f32 v34, v34, s0
	global_store_short v[32:33], v48, off
	global_store_short v[32:33], v34, off offset:64
	v_or_b32_e32 v32, v64, v184
	v_ashrrev_i32_e32 v33, 31, v32
	v_and_b32_e32 v48, 0xff, v32
	v_lshl_add_u32 v48, v48, 2, v250
	ds_read_b32 v34, v48
	v_lshlrev_b64 v[32:33], 11, v[32:33]
	v_lshl_add_u64 v[32:33], v[130:131], 0, v[32:33]
	s_waitcnt lgkmcnt(0)
	v_mul_f32_e32 v48, v51, v34
	v_cvt_pk_bf16_f32 v48, v48, s0
	global_store_short v[32:33], v48, off
	v_mul_f32_e32 v34, v35, v34
	v_or_b32_e32 v48, v64, v185
	v_cvt_pk_bf16_f32 v34, v34, s0
	v_ashrrev_i32_e32 v49, 31, v48
	global_store_short v[32:33], v34, off offset:64
	v_and_b32_e32 v32, 0xff, v48
	v_lshl_add_u32 v32, v32, 2, v250
	ds_read_b96 v[32:34], v32
	v_lshlrev_b64 v[48:49], 11, v[48:49]
	v_lshl_add_u64 v[48:49], v[130:131], 0, v[48:49]
	s_waitcnt lgkmcnt(0)
	v_mul_f32_e32 v35, v52, v32
	v_mul_f32_e32 v32, v36, v32
	v_cvt_pk_bf16_f32 v35, v35, s0
	v_cvt_pk_bf16_f32 v32, v32, s0
	global_store_short v[48:49], v35, off
	global_store_short v[48:49], v32, off offset:64
	v_or_b32_e32 v48, v64, v186
	v_ashrrev_i32_e32 v49, 31, v48
	v_lshlrev_b64 v[48:49], 11, v[48:49]
	v_mul_f32_e32 v32, v53, v33
	v_lshl_add_u64 v[48:49], v[130:131], 0, v[48:49]
	v_cvt_pk_bf16_f32 v32, v32, s0
	global_store_short v[48:49], v32, off
	v_mul_f32_e32 v32, v37, v33
	v_cvt_pk_bf16_f32 v32, v32, s0
	global_store_short v[48:49], v32, off offset:64
	v_or_b32_e32 v32, v64, v187
	v_ashrrev_i32_e32 v33, 31, v32
	v_lshlrev_b64 v[32:33], 11, v[32:33]
	v_mul_f32_e32 v35, v54, v34
	v_mul_f32_e32 v34, v38, v34
	v_lshl_add_u64 v[32:33], v[130:131], 0, v[32:33]
	v_cvt_pk_bf16_f32 v35, v35, s0
	v_cvt_pk_bf16_f32 v34, v34, s0
	global_store_short v[32:33], v35, off
	global_store_short v[32:33], v34, off offset:64
	v_or_b32_e32 v32, v64, v188
	v_ashrrev_i32_e32 v33, 31, v32
	v_and_b32_e32 v34, 0xff, v32
	v_lshl_add_u32 v34, v34, 2, v250
	ds_read_b32 v34, v34
	v_lshlrev_b64 v[32:33], 11, v[32:33]
	v_or_b32_e32 v36, v64, v189
	v_lshl_add_u64 v[32:33], v[130:131], 0, v[32:33]
	v_ashrrev_i32_e32 v37, 31, v36
	s_waitcnt lgkmcnt(0)
	v_mul_f32_e32 v35, v55, v34
	v_mul_f32_e32 v34, v39, v34
	v_cvt_pk_bf16_f32 v35, v35, s0
	v_cvt_pk_bf16_f32 v34, v34, s0
	global_store_short v[32:33], v35, off
	global_store_short v[32:33], v34, off offset:64
	v_and_b32_e32 v32, 0xff, v36
	v_lshl_add_u32 v32, v32, 2, v250
	ds_read_b96 v[32:34], v32
	v_lshlrev_b64 v[36:37], 11, v[36:37]
	v_lshl_add_u64 v[36:37], v[130:131], 0, v[36:37]
	s_waitcnt lgkmcnt(0)
	v_mul_f32_e32 v35, v56, v32
	v_mul_f32_e32 v32, v40, v32
	v_cvt_pk_bf16_f32 v35, v35, s0
	v_cvt_pk_bf16_f32 v32, v32, s0
	global_store_short v[36:37], v35, off
	global_store_short v[36:37], v32, off offset:64
	v_or_b32_e32 v36, v64, v190
	v_ashrrev_i32_e32 v37, 31, v36
	v_lshlrev_b64 v[36:37], 11, v[36:37]
	v_mul_f32_e32 v32, v57, v33
	v_lshl_add_u64 v[36:37], v[130:131], 0, v[36:37]
	v_cvt_pk_bf16_f32 v32, v32, s0
	global_store_short v[36:37], v32, off
	v_mul_f32_e32 v32, v41, v33
	v_cvt_pk_bf16_f32 v32, v32, s0
	global_store_short v[36:37], v32, off offset:64
	v_or_b32_e32 v32, v64, v191
	v_ashrrev_i32_e32 v33, 31, v32
	v_lshlrev_b64 v[32:33], 11, v[32:33]
	v_mul_f32_e32 v35, v58, v34
	v_mul_f32_e32 v34, v42, v34
	v_lshl_add_u64 v[32:33], v[130:131], 0, v[32:33]
	v_cvt_pk_bf16_f32 v35, v35, s0
	v_cvt_pk_bf16_f32 v34, v34, s0
	global_store_short v[32:33], v35, off
	global_store_short v[32:33], v34, off offset:64
	v_or_b32_e32 v32, v64, v192
	v_ashrrev_i32_e32 v33, 31, v32
	v_and_b32_e32 v34, 0xff, v32
	v_lshl_add_u32 v34, v34, 2, v250
	ds_read_b32 v34, v34
	v_lshlrev_b64 v[32:33], 11, v[32:33]
	v_or_b32_e32 v36, v64, v193
	v_lshl_add_u64 v[32:33], v[130:131], 0, v[32:33]
	v_ashrrev_i32_e32 v37, 31, v36
	s_waitcnt lgkmcnt(0)
	v_mul_f32_e32 v35, v59, v34
	v_mul_f32_e32 v34, v43, v34
	v_cvt_pk_bf16_f32 v35, v35, s0
	v_cvt_pk_bf16_f32 v34, v34, s0
	global_store_short v[32:33], v35, off
	global_store_short v[32:33], v34, off offset:64
	v_and_b32_e32 v32, 0xff, v36
	v_lshl_add_u32 v32, v32, 2, v250
	ds_read_b96 v[32:34], v32
	v_lshlrev_b64 v[36:37], 11, v[36:37]
	v_lshl_add_u64 v[36:37], v[130:131], 0, v[36:37]
	s_waitcnt lgkmcnt(0)
	v_mul_f32_e32 v35, v60, v32
	v_mul_f32_e32 v32, v44, v32
	v_cvt_pk_bf16_f32 v35, v35, s0
	v_cvt_pk_bf16_f32 v32, v32, s0
	global_store_short v[36:37], v35, off
	global_store_short v[36:37], v32, off offset:64
	v_or_b32_e32 v36, v64, v194
	v_ashrrev_i32_e32 v37, 31, v36
	v_lshlrev_b64 v[36:37], 11, v[36:37]
	v_mul_f32_e32 v32, v61, v33
	v_lshl_add_u64 v[36:37], v[130:131], 0, v[36:37]
	v_cvt_pk_bf16_f32 v32, v32, s0
	global_store_short v[36:37], v32, off
	v_mul_f32_e32 v32, v45, v33
	v_cvt_pk_bf16_f32 v32, v32, s0
	global_store_short v[36:37], v32, off offset:64
	v_or_b32_e32 v32, v64, v195
	v_ashrrev_i32_e32 v33, 31, v32
	v_lshlrev_b64 v[32:33], 11, v[32:33]
	v_mul_f32_e32 v35, v62, v34
	v_mul_f32_e32 v34, v46, v34
	v_lshl_add_u64 v[32:33], v[130:131], 0, v[32:33]
	v_cvt_pk_bf16_f32 v35, v35, s0
	v_cvt_pk_bf16_f32 v34, v34, s0
	global_store_short v[32:33], v35, off
	global_store_short v[32:33], v34, off offset:64
	v_or_b32_e32 v32, v64, v196
	v_ashrrev_i32_e32 v33, 31, v32
	v_and_b32_e32 v34, 0xff, v32
	v_lshl_add_u32 v34, v34, 2, v250
	ds_read_b32 v34, v34
	v_lshlrev_b64 v[32:33], 11, v[32:33]
	v_lshl_add_u64 v[32:33], v[130:131], 0, v[32:33]
	s_waitcnt lgkmcnt(0)
	v_mul_f32_e32 v35, v63, v34
	v_mul_f32_e32 v34, v47, v34
	v_cvt_pk_bf16_f32 v35, v35, s0
	v_cvt_pk_bf16_f32 v34, v34, s0
	global_store_short v[32:33], v35, off
	global_store_short v[32:33], v34, off offset:64
	v_or_b32_e32 v32, 0x60, v132
	v_or_b32_e32 v38, v32, v181
	v_ashrrev_i32_e32 v39, 31, v38
	v_and_b32_e32 v34, 0xff, v38
	v_lshl_add_u32 v34, v34, 2, v250
	ds_read_b96 v[34:36], v34
	v_lshlrev_b64 v[38:39], 11, v[38:39]
	v_lshl_add_u64 v[38:39], v[130:131], 0, v[38:39]
	s_waitcnt lgkmcnt(0)
	v_mul_f32_e32 v16, v16, v34
	v_mul_f32_e32 v0, v0, v34
	v_cvt_pk_bf16_f32 v16, v16, s0
	v_cvt_pk_bf16_f32 v0, v0, s0
	global_store_short v[38:39], v16, off
	global_store_short v[38:39], v0, off offset:64
	v_or_b32_e32 v38, v32, v182
	v_ashrrev_i32_e32 v39, 31, v38
	v_lshlrev_b64 v[38:39], 11, v[38:39]
	v_mul_f32_e32 v0, v17, v35
	v_lshl_add_u64 v[38:39], v[130:131], 0, v[38:39]
	v_cvt_pk_bf16_f32 v0, v0, s0
	global_store_short v[38:39], v0, off
	v_mul_f32_e32 v0, v1, v35
	v_cvt_pk_bf16_f32 v0, v0, s0
	global_store_short v[38:39], v0, off offset:64
	v_or_b32_e32 v0, v32, v183
	v_ashrrev_i32_e32 v1, 31, v0
	v_lshlrev_b64 v[0:1], 11, v[0:1]
	v_mul_f32_e32 v16, v18, v36
	v_mul_f32_e32 v2, v2, v36
	v_lshl_add_u64 v[0:1], v[130:131], 0, v[0:1]
	v_cvt_pk_bf16_f32 v16, v16, s0
	v_cvt_pk_bf16_f32 v2, v2, s0
	global_store_short v[0:1], v16, off
	global_store_short v[0:1], v2, off offset:64
	v_or_b32_e32 v0, v32, v184
	v_ashrrev_i32_e32 v1, 31, v0
	v_and_b32_e32 v16, 0xff, v0
	v_lshl_add_u32 v16, v16, 2, v250
	ds_read_b32 v2, v16
	v_lshlrev_b64 v[0:1], 11, v[0:1]
	v_lshl_add_u64 v[0:1], v[130:131], 0, v[0:1]
	s_waitcnt lgkmcnt(0)
	v_mul_f32_e32 v16, v19, v2
	v_cvt_pk_bf16_f32 v16, v16, s0
	global_store_short v[0:1], v16, off
	v_mul_f32_e32 v2, v3, v2
	v_or_b32_e32 v16, v32, v185
	v_cvt_pk_bf16_f32 v2, v2, s0
	v_ashrrev_i32_e32 v17, 31, v16
	global_store_short v[0:1], v2, off offset:64
	v_and_b32_e32 v0, 0xff, v16
	v_lshl_add_u32 v0, v0, 2, v250
	ds_read_b96 v[0:2], v0
	v_lshlrev_b64 v[16:17], 11, v[16:17]
	v_lshl_add_u64 v[16:17], v[130:131], 0, v[16:17]
	s_waitcnt lgkmcnt(0)
	v_mul_f32_e32 v3, v20, v0
	v_mul_f32_e32 v0, v4, v0
	v_cvt_pk_bf16_f32 v3, v3, s0
	v_cvt_pk_bf16_f32 v0, v0, s0
	global_store_short v[16:17], v3, off
	global_store_short v[16:17], v0, off offset:64
	v_or_b32_e32 v16, v32, v186
	v_ashrrev_i32_e32 v17, 31, v16
	v_lshlrev_b64 v[16:17], 11, v[16:17]
	v_mul_f32_e32 v0, v21, v1
	v_lshl_add_u64 v[16:17], v[130:131], 0, v[16:17]
	v_cvt_pk_bf16_f32 v0, v0, s0
	global_store_short v[16:17], v0, off
	v_mul_f32_e32 v0, v5, v1
	v_cvt_pk_bf16_f32 v0, v0, s0
	global_store_short v[16:17], v0, off offset:64
	v_or_b32_e32 v0, v32, v187
	v_ashrrev_i32_e32 v1, 31, v0
	v_lshlrev_b64 v[0:1], 11, v[0:1]
	v_mul_f32_e32 v3, v22, v2
	v_mul_f32_e32 v2, v6, v2
	v_lshl_add_u64 v[0:1], v[130:131], 0, v[0:1]
	v_cvt_pk_bf16_f32 v3, v3, s0
	v_cvt_pk_bf16_f32 v2, v2, s0
	global_store_short v[0:1], v3, off
	global_store_short v[0:1], v2, off offset:64
	v_or_b32_e32 v0, v32, v188
	v_ashrrev_i32_e32 v1, 31, v0
	v_and_b32_e32 v2, 0xff, v0
	v_lshl_add_u32 v2, v2, 2, v250
	ds_read_b32 v2, v2
	v_lshlrev_b64 v[0:1], 11, v[0:1]
	v_or_b32_e32 v4, v32, v189
	v_lshl_add_u64 v[0:1], v[130:131], 0, v[0:1]
	v_ashrrev_i32_e32 v5, 31, v4
	s_waitcnt lgkmcnt(0)
	v_mul_f32_e32 v3, v23, v2
	v_mul_f32_e32 v2, v7, v2
	v_cvt_pk_bf16_f32 v3, v3, s0
	v_cvt_pk_bf16_f32 v2, v2, s0
	global_store_short v[0:1], v3, off
	global_store_short v[0:1], v2, off offset:64
	v_and_b32_e32 v0, 0xff, v4
	v_lshl_add_u32 v0, v0, 2, v250
	ds_read_b96 v[0:2], v0
	v_lshlrev_b64 v[4:5], 11, v[4:5]
	v_lshl_add_u64 v[4:5], v[130:131], 0, v[4:5]
	s_waitcnt lgkmcnt(0)
	v_mul_f32_e32 v3, v24, v0
	v_mul_f32_e32 v0, v8, v0
	v_cvt_pk_bf16_f32 v3, v3, s0
	v_cvt_pk_bf16_f32 v0, v0, s0
	global_store_short v[4:5], v3, off
	global_store_short v[4:5], v0, off offset:64
	v_or_b32_e32 v4, v32, v190
	v_ashrrev_i32_e32 v5, 31, v4
	v_lshlrev_b64 v[4:5], 11, v[4:5]
	v_mul_f32_e32 v0, v25, v1
	v_lshl_add_u64 v[4:5], v[130:131], 0, v[4:5]
	v_cvt_pk_bf16_f32 v0, v0, s0
	global_store_short v[4:5], v0, off
	v_mul_f32_e32 v0, v9, v1
	v_cvt_pk_bf16_f32 v0, v0, s0
	global_store_short v[4:5], v0, off offset:64
	v_or_b32_e32 v0, v32, v191
	v_ashrrev_i32_e32 v1, 31, v0
	v_lshlrev_b64 v[0:1], 11, v[0:1]
	v_mul_f32_e32 v3, v26, v2
	v_mul_f32_e32 v2, v10, v2
	v_lshl_add_u64 v[0:1], v[130:131], 0, v[0:1]
	v_cvt_pk_bf16_f32 v3, v3, s0
	v_cvt_pk_bf16_f32 v2, v2, s0
	global_store_short v[0:1], v3, off
	global_store_short v[0:1], v2, off offset:64
	v_or_b32_e32 v0, v32, v192
	v_ashrrev_i32_e32 v1, 31, v0
	v_and_b32_e32 v2, 0xff, v0
	v_lshl_add_u32 v2, v2, 2, v250
	ds_read_b32 v2, v2
	v_lshlrev_b64 v[0:1], 11, v[0:1]
	v_or_b32_e32 v4, v32, v193
	v_lshl_add_u64 v[0:1], v[130:131], 0, v[0:1]
	v_ashrrev_i32_e32 v5, 31, v4
	s_waitcnt lgkmcnt(0)
	v_mul_f32_e32 v3, v27, v2
	v_mul_f32_e32 v2, v11, v2
	v_cvt_pk_bf16_f32 v3, v3, s0
	v_cvt_pk_bf16_f32 v2, v2, s0
	global_store_short v[0:1], v3, off
	global_store_short v[0:1], v2, off offset:64
	v_and_b32_e32 v0, 0xff, v4
	v_lshl_add_u32 v0, v0, 2, v250
	ds_read_b96 v[0:2], v0
	v_lshlrev_b64 v[4:5], 11, v[4:5]
	v_lshl_add_u64 v[4:5], v[130:131], 0, v[4:5]
	s_waitcnt lgkmcnt(0)
	v_mul_f32_e32 v3, v28, v0
	v_mul_f32_e32 v0, v12, v0
	v_cvt_pk_bf16_f32 v3, v3, s0
	v_cvt_pk_bf16_f32 v0, v0, s0
	global_store_short v[4:5], v3, off
	global_store_short v[4:5], v0, off offset:64
	v_or_b32_e32 v4, v32, v194
	v_ashrrev_i32_e32 v5, 31, v4
	v_lshlrev_b64 v[4:5], 11, v[4:5]
	v_mul_f32_e32 v0, v29, v1
	v_lshl_add_u64 v[4:5], v[130:131], 0, v[4:5]
	v_cvt_pk_bf16_f32 v0, v0, s0
	global_store_short v[4:5], v0, off
	v_mul_f32_e32 v0, v13, v1
	v_cvt_pk_bf16_f32 v0, v0, s0
	global_store_short v[4:5], v0, off offset:64
	v_or_b32_e32 v0, v32, v195
	v_ashrrev_i32_e32 v1, 31, v0
	v_lshlrev_b64 v[0:1], 11, v[0:1]
	v_mul_f32_e32 v3, v30, v2
	v_mul_f32_e32 v2, v14, v2
	v_lshl_add_u64 v[0:1], v[130:131], 0, v[0:1]
	v_cvt_pk_bf16_f32 v3, v3, s0
	v_cvt_pk_bf16_f32 v2, v2, s0
	global_store_short v[0:1], v3, off
	global_store_short v[0:1], v2, off offset:64
	v_or_b32_e32 v0, v32, v196
	v_ashrrev_i32_e32 v1, 31, v0
	v_and_b32_e32 v2, 0xff, v0
	v_lshl_add_u32 v2, v2, 2, v250
	ds_read_b32 v2, v2
	v_lshlrev_b64 v[0:1], 11, v[0:1]
	v_lshl_add_u64 v[0:1], v[130:131], 0, v[0:1]
	s_waitcnt lgkmcnt(0)
	v_mul_f32_e32 v3, v31, v2
	v_mul_f32_e32 v2, v15, v2
	v_cvt_pk_bf16_f32 v3, v3, s0
	v_cvt_pk_bf16_f32 v2, v2, s0
	global_store_short v[0:1], v3, off
	global_store_short v[0:1], v2, off offset:64
	s_cbranch_scc0 .LBB0_2225

.LBB0_2340:
	s_and_b32 s19, s18, 0x18000
	v_add_u32_e32 v187, s19, v180
	s_add_i32 s19, s18, 0xfffe8000
	s_and_b32 s19, s19, 0x18000
	v_or_b32_e32 v212, s19, v179
	v_add_u32_e32 v213, s19, v176
	s_waitcnt vmcnt(8) lgkmcnt(0)
	s_barrier
	v_mfma_f32_32x32x16_bf16 v[112:127], v[150:153], v[142:145], v[112:127]
	v_mfma_f32_32x32x16_bf16 v[96:111], v[150:153], v[130:133], v[96:111]
	v_add_u32_e32 v192, v212, v177
	v_add_u32_e32 v208, v213, v177
	ds_read_b128 v[188:191], v192 offset:16384
	ds_read_b128 v[192:195], v192 offset:18432
	ds_read_b128 v[196:199], v208
	v_mfma_f32_32x32x16_bf16 v[80:95], v[146:149], v[142:145], v[80:95]
	v_mfma_f32_32x32x16_bf16 v[64:79], v[146:149], v[130:133], v[64:79]
	ds_read_b128 v[200:203], v208 offset:2048
	v_readfirstlane_b32 s19, v187
	s_mov_b32 m0, s19
	s_nop 0
	global_load_lds_dwordx4 v[170:171], off
	v_mfma_f32_32x32x16_bf16 v[48:63], v[138:141], v[142:145], v[48:63]
	v_mfma_f32_32x32x16_bf16 v[32:47], v[138:141], v[130:133], v[32:47]
	ds_read_b128 v[204:207], v208 offset:4096
	s_add_i32 s20, s19, 0x2000
	v_lshl_add_u64 v[150:151], v[170:171], 0, s[34:35]
	s_mov_b32 m0, s20
	s_nop 0
	global_load_lds_dwordx4 v[150:151], off
	v_mfma_f32_32x32x16_bf16 v[16:31], v[134:137], v[142:145], v[16:31]
	v_mfma_f32_32x32x16_bf16 v[0:15], v[134:137], v[130:133], v[0:15]
	ds_read_b128 v[208:211], v208 offset:6144
	s_waitcnt lgkmcnt(3)
	v_mfma_f32_32x32x16_bf16 v[112:127], v[196:199], v[188:191], v[112:127]
	v_add_u32_e32 v130, v212, v178
	v_add_u32_e32 v134, v213, v178
	ds_read_b128 v[142:145], v130 offset:16384
	v_mfma_f32_32x32x16_bf16 v[96:111], v[196:199], v[192:195], v[96:111]
	ds_read_b128 v[130:133], v130 offset:18432
	s_add_i32 s20, s19, 0x6000
	s_addk_i32 s19, 0x4000
	s_mov_b32 m0, s19
	s_nop 0
	global_load_lds_dwordx4 v[172:173], off
	s_waitcnt lgkmcnt(4)
	v_mfma_f32_32x32x16_bf16 v[80:95], v[200:203], v[188:191], v[80:95]
	ds_read_b128 v[150:153], v134
	v_mfma_f32_32x32x16_bf16 v[64:79], v[200:203], v[192:195], v[64:79]
	ds_read_b128 v[146:149], v134 offset:2048
	s_waitcnt lgkmcnt(5)
	v_mfma_f32_32x32x16_bf16 v[48:63], v[204:207], v[188:191], v[48:63]
	ds_read_b128 v[138:141], v134 offset:4096
	v_mfma_f32_32x32x16_bf16 v[32:47], v[204:207], v[192:195], v[32:47]
	ds_read_b128 v[134:137], v134 offset:6144
	v_lshl_add_u64 v[212:213], v[172:173], 0, s[34:35]
	s_mov_b32 m0, s20
	s_nop 0
	global_load_lds_dwordx4 v[212:213], off
	s_waitcnt lgkmcnt(6)
	v_mfma_f32_32x32x16_bf16 v[16:31], v[208:211], v[188:191], v[16:31]
	s_add_i32 s18, s18, 0x8000
	v_lshl_add_u64 v[170:171], v[170:171], 0, 64
	v_lshl_add_u64 v[172:173], v[172:173], 0, 64
	s_cmp_eq_u32 s18, 0x100000
	v_mfma_f32_32x32x16_bf16 v[0:15], v[208:211], v[192:195], v[0:15]
	s_cbranch_scc0 .LBB0_2340
	s_waitcnt vmcnt(8) lgkmcnt(0)
	s_barrier
	v_add_u32_e32 v187, v179, v177
	ds_read_b128 v[170:173], v187 offset:49152
	ds_read_b128 v[188:191], v187 offset:51200
	v_add_u32_e32 v187, v176, v177
	ds_read_b128 v[192:195], v187 offset:32768
	ds_read_b128 v[196:199], v187 offset:34816
	ds_read_b128 v[200:203], v187 offset:36864
	ds_read_b128 v[204:207], v187 offset:38912
	s_waitcnt lgkmcnt(9)
	v_mfma_f32_32x32x16_bf16 v[112:127], v[150:153], v[142:145], v[112:127]
	v_mfma_f32_32x32x16_bf16 v[96:111], v[150:153], v[130:133], v[96:111]
	s_waitcnt lgkmcnt(8)
	v_mfma_f32_32x32x16_bf16 v[80:95], v[146:149], v[142:145], v[80:95]
	v_mfma_f32_32x32x16_bf16 v[64:79], v[146:149], v[130:133], v[64:79]
	s_waitcnt lgkmcnt(7)
	v_mfma_f32_32x32x16_bf16 v[48:63], v[138:141], v[142:145], v[48:63]
	v_mfma_f32_32x32x16_bf16 v[32:47], v[138:141], v[130:133], v[32:47]
	s_waitcnt lgkmcnt(6)
	v_mfma_f32_32x32x16_bf16 v[16:31], v[134:137], v[142:145], v[16:31]
	v_mfma_f32_32x32x16_bf16 v[0:15], v[134:137], v[130:133], v[0:15]
	v_add_u32_e32 v134, v179, v178
	v_add_u32_e32 v150, v176, v178
	ds_read_b128 v[130:133], v134 offset:49152
	ds_read_b128 v[134:137], v134 offset:51200
	ds_read_b128 v[138:141], v150 offset:32768
	ds_read_b128 v[142:145], v150 offset:34816
	ds_read_b128 v[146:149], v150 offset:36864
	ds_read_b128 v[150:153], v150 offset:38912
	s_waitcnt lgkmcnt(9)
	v_mfma_f32_32x32x16_bf16 v[112:127], v[192:195], v[170:173], v[112:127]
	v_mfma_f32_32x32x16_bf16 v[96:111], v[192:195], v[188:191], v[96:111]
	s_waitcnt lgkmcnt(8)
	v_mfma_f32_32x32x16_bf16 v[80:95], v[196:199], v[170:173], v[80:95]
	v_mfma_f32_32x32x16_bf16 v[64:79], v[196:199], v[188:191], v[64:79]
	s_waitcnt lgkmcnt(7)
	v_mfma_f32_32x32x16_bf16 v[48:63], v[200:203], v[170:173], v[48:63]
	v_mfma_f32_32x32x16_bf16 v[32:47], v[200:203], v[188:191], v[32:47]
	s_waitcnt vmcnt(4) lgkmcnt(0)
	s_barrier
	v_add_u32_e32 v187, v184, v177
	s_waitcnt lgkmcnt(6)
	v_mfma_f32_32x32x16_bf16 v[16:31], v[204:207], v[170:173], v[16:31]
	v_mfma_f32_32x32x16_bf16 v[0:15], v[204:207], v[188:191], v[0:15]
	ds_read_b128 v[170:173], v187 offset:16384
	ds_read_b128 v[188:191], v187 offset:18432
	v_add_u32_e32 v187, v185, v177
	ds_read_b128 v[192:195], v187
	ds_read_b128 v[196:199], v187 offset:2048
	ds_read_b128 v[200:203], v187 offset:4096
	ds_read_b128 v[204:207], v187 offset:6144
	s_waitcnt lgkmcnt(9)
	v_mfma_f32_32x32x16_bf16 v[112:127], v[138:141], v[130:133], v[112:127]
	v_mfma_f32_32x32x16_bf16 v[96:111], v[138:141], v[134:137], v[96:111]
	s_waitcnt lgkmcnt(8)
	v_mfma_f32_32x32x16_bf16 v[80:95], v[142:145], v[130:133], v[80:95]
	v_mfma_f32_32x32x16_bf16 v[64:79], v[142:145], v[134:137], v[64:79]
	s_waitcnt lgkmcnt(7)
	v_mfma_f32_32x32x16_bf16 v[48:63], v[146:149], v[130:133], v[48:63]
	v_mfma_f32_32x32x16_bf16 v[32:47], v[146:149], v[134:137], v[32:47]
	s_waitcnt lgkmcnt(6)
	v_mfma_f32_32x32x16_bf16 v[16:31], v[150:153], v[130:133], v[16:31]
	v_mfma_f32_32x32x16_bf16 v[0:15], v[150:153], v[134:137], v[0:15]
	v_add_u32_e32 v134, v184, v178
	v_add_u32_e32 v150, v185, v178
	ds_read_b128 v[130:133], v134 offset:16384
	ds_read_b128 v[134:137], v134 offset:18432
	ds_read_b128 v[138:141], v150
	ds_read_b128 v[142:145], v150 offset:2048
	ds_read_b128 v[146:149], v150 offset:4096
	ds_read_b128 v[150:153], v150 offset:6144
	s_waitcnt lgkmcnt(9)
	v_mfma_f32_32x32x16_bf16 v[112:127], v[192:195], v[170:173], v[112:127]
	v_mfma_f32_32x32x16_bf16 v[96:111], v[192:195], v[188:191], v[96:111]
	s_waitcnt lgkmcnt(8)
	v_mfma_f32_32x32x16_bf16 v[80:95], v[196:199], v[170:173], v[80:95]
	v_mfma_f32_32x32x16_bf16 v[64:79], v[196:199], v[188:191], v[64:79]
	s_waitcnt lgkmcnt(7)
	v_mfma_f32_32x32x16_bf16 v[48:63], v[200:203], v[170:173], v[48:63]
	v_mfma_f32_32x32x16_bf16 v[32:47], v[200:203], v[188:191], v[32:47]
	s_waitcnt vmcnt(0) lgkmcnt(0)
	s_barrier
	v_add_u32_e32 v187, v182, v177
	s_waitcnt lgkmcnt(6)
	v_mfma_f32_32x32x16_bf16 v[16:31], v[204:207], v[170:173], v[16:31]
	v_mfma_f32_32x32x16_bf16 v[0:15], v[204:207], v[188:191], v[0:15]
	ds_read_b128 v[170:173], v187 offset:16384
	ds_read_b128 v[188:191], v187 offset:18432
	v_add_u32_e32 v187, v183, v177
	ds_read_b128 v[192:195], v187
	ds_read_b128 v[196:199], v187 offset:2048
	ds_read_b128 v[200:203], v187 offset:4096
	ds_read_b128 v[204:207], v187 offset:6144
	s_waitcnt lgkmcnt(9)
	v_mfma_f32_32x32x16_bf16 v[112:127], v[138:141], v[130:133], v[112:127]
	v_mfma_f32_32x32x16_bf16 v[96:111], v[138:141], v[134:137], v[96:111]
	s_waitcnt lgkmcnt(8)
	v_mfma_f32_32x32x16_bf16 v[80:95], v[142:145], v[130:133], v[80:95]
	v_mfma_f32_32x32x16_bf16 v[64:79], v[142:145], v[134:137], v[64:79]
	s_waitcnt lgkmcnt(7)
	v_mfma_f32_32x32x16_bf16 v[48:63], v[146:149], v[130:133], v[48:63]
	v_mfma_f32_32x32x16_bf16 v[32:47], v[146:149], v[134:137], v[32:47]
	s_waitcnt lgkmcnt(6)
	v_mfma_f32_32x32x16_bf16 v[16:31], v[150:153], v[130:133], v[16:31]
	v_mfma_f32_32x32x16_bf16 v[0:15], v[150:153], v[134:137], v[0:15]
	v_add_u32_e32 v134, v182, v178
	v_add_u32_e32 v150, v183, v178
	ds_read_b128 v[130:133], v134 offset:16384
	ds_read_b128 v[134:137], v134 offset:18432
	ds_read_b128 v[138:141], v150
	ds_read_b128 v[142:145], v150 offset:2048
	ds_read_b128 v[146:149], v150 offset:4096
	ds_read_b128 v[150:153], v150 offset:6144
	s_waitcnt lgkmcnt(9)
	v_mfma_f32_32x32x16_bf16 v[112:127], v[192:195], v[170:173], v[112:127]
	v_mfma_f32_32x32x16_bf16 v[96:111], v[192:195], v[188:191], v[96:111]
	s_waitcnt lgkmcnt(8)
	v_mfma_f32_32x32x16_bf16 v[80:95], v[196:199], v[170:173], v[80:95]
	v_mfma_f32_32x32x16_bf16 v[64:79], v[196:199], v[188:191], v[64:79]
	s_waitcnt lgkmcnt(7)
	v_mfma_f32_32x32x16_bf16 v[48:63], v[200:203], v[170:173], v[48:63]
	v_mfma_f32_32x32x16_bf16 v[32:47], v[200:203], v[188:191], v[32:47]
	s_waitcnt lgkmcnt(6)
	v_mfma_f32_32x32x16_bf16 v[16:31], v[204:207], v[170:173], v[16:31]
	v_mfma_f32_32x32x16_bf16 v[0:15], v[204:207], v[188:191], v[0:15]
	s_waitcnt lgkmcnt(3)
	v_mfma_f32_32x32x16_bf16 v[112:127], v[138:141], v[130:133], v[112:127]
	s_waitcnt lgkmcnt(2)
	v_mfma_f32_32x32x16_bf16 v[80:95], v[142:145], v[130:133], v[80:95]
	s_waitcnt lgkmcnt(1)
	v_mfma_f32_32x32x16_bf16 v[48:63], v[146:149], v[130:133], v[48:63]
	s_waitcnt lgkmcnt(0)
	v_mfma_f32_32x32x16_bf16 v[16:31], v[150:153], v[130:133], v[16:31]
	v_or_b32_e32 v132, s12, v174
	v_ashrrev_i32_e32 v130, 1, v132
	v_or_b32_e32 v130, v130, v154
	v_ashrrev_i32_e32 v131, 31, v130
	s_movk_i32 s12, 0x5000
	v_mfma_f32_32x32x16_bf16 v[96:111], v[138:141], v[134:137], v[96:111]
	v_mfma_f32_32x32x16_bf16 v[64:79], v[142:145], v[134:137], v[64:79]
	v_add_u32_e32 v142, s13, v155
	s_mov_b32 s13, 0xb000
	v_ashrrev_i32_e32 v133, 7, v142
	v_mfma_f32_32x32x16_bf16 v[32:47], v[146:149], v[134:137], v[32:47]
	v_mfma_f32_32x32x16_bf16 v[0:15], v[150:153], v[134:137], v[0:15]
	v_lshl_add_u64 v[134:135], v[130:131], 2, s[10:11]
	v_add_co_u32_e32 v138, vcc, s12, v134
	s_mov_b32 s12, 0x8000
	s_nop 0
	v_addc_co_u32_e32 v139, vcc, 0, v135, vcc
	global_load_dword v137, v[138:139], off offset:2048
	v_add_co_u32_e32 v138, vcc, s13, v134
	global_load_dword v136, v[134:135], off
	s_nop 0
	v_addc_co_u32_e32 v139, vcc, 0, v135, vcc
	v_add_co_u32_e32 v140, vcc, s47, v134
	global_load_dword v139, v[138:139], off
	s_nop 0
	v_addc_co_u32_e32 v141, vcc, 0, v135, vcc
	global_load_dword v138, v[140:141], off offset:3072
	v_add_co_u32_e32 v140, vcc, s12, v134
	s_mov_b32 s12, 0xd000
	s_nop 0
	v_addc_co_u32_e32 v141, vcc, 0, v135, vcc
	v_add_co_u32_e32 v134, vcc, s12, v134
	global_load_dword v140, v[140:141], off offset:1024
	s_nop 0
	v_addc_co_u32_e32 v135, vcc, 0, v135, vcc
	global_load_dword v141, v[134:135], off offset:3072
	v_readlane_b32 s100, v252, 7
	s_add_i32 s100, s14, s100
	s_cmpk_lt_i32 s100, 0xb0
	s_cbranch_scc0 .Lpf_none_up
	s_and_b32 vcc_lo, s100, 7
	s_or_b32 vcc_lo, vcc_lo, s16
	s_lshl_b32 vcc_lo, vcc_lo, 8
	v_add_u32_e32 v238, vcc_lo, v175
	v_ashrrev_i32_e32 v239, 31, v238
	v_lshlrev_b64 v[238:239], 11, v[238:239]
	v_lshl_add_u64 v[238:239], v[156:157], 0, v[238:239]
	s_lshl_b32 vcc_lo, s100, 5
	s_and_b32 vcc_lo, vcc_lo, 0xffffff00
	v_add_u32_e32 v240, vcc_lo, v175
	v_ashrrev_i32_e32 v241, 31, v240
	v_lshlrev_b64 v[240:241], 11, v[240:241]
	v_lshl_add_u64 v[240:241], v[158:159], 0, v[240:241]
	v_readfirstlane_b32 s100, v180
	s_mov_b32 m0, s100
	s_nop 0
	global_load_lds_dwordx4 v[238:239], off
	v_lshl_add_u64 v[242:243], v[238:239], 0, s[34:35]
	s_add_i32 m0, s100, 0x2000
	s_nop 0
	global_load_lds_dwordx4 v[242:243], off
	s_add_i32 m0, s100, 0x4000
	s_nop 0
	global_load_lds_dwordx4 v[240:241], off
	v_lshl_add_u64 v[242:243], v[240:241], 0, s[34:35]
	s_add_i32 m0, s100, 0x6000
	s_nop 0
	global_load_lds_dwordx4 v[242:243], off
	v_lshl_add_u64 v[242:243], v[238:239], 0, 64
	s_add_i32 m0, s100, 0x8000
	s_nop 0
	global_load_lds_dwordx4 v[242:243], off
	s_mov_b64 vcc, 0x40040
	v_lshl_add_u64 v[242:243], v[238:239], 0, vcc
	s_add_i32 m0, s100, 0xa000
	s_nop 0
	global_load_lds_dwordx4 v[242:243], off
	v_lshl_add_u64 v[242:243], v[240:241], 0, 64
	s_add_i32 m0, s100, 0xc000
	s_nop 0
	global_load_lds_dwordx4 v[242:243], off
	s_mov_b64 vcc, 0x40040
	v_lshl_add_u64 v[242:243], v[240:241], 0, vcc
	s_add_i32 m0, s100, 0xe000
	s_nop 0
	global_load_lds_dwordx4 v[242:243], off
	s_mov_b64 vcc, 0x80
	v_lshl_add_u64 v[242:243], v[238:239], 0, vcc
	s_add_i32 m0, s100, 0x10000
	s_nop 0
	global_load_lds_dwordx4 v[242:243], off
	s_mov_b64 vcc, 0x40080
	v_lshl_add_u64 v[242:243], v[238:239], 0, vcc
	s_add_i32 m0, s100, 0x12000
	s_nop 0
	global_load_lds_dwordx4 v[242:243], off
	s_mov_b64 vcc, 0x80
	v_lshl_add_u64 v[242:243], v[240:241], 0, vcc
	s_add_i32 m0, s100, 0x14000
	s_nop 0
	global_load_lds_dwordx4 v[242:243], off
	s_mov_b64 vcc, 0x40080
	v_lshl_add_u64 v[242:243], v[240:241], 0, vcc
	s_add_i32 m0, s100, 0x16000
	s_nop 0
	global_load_lds_dwordx4 v[242:243], off
	s_mov_b32 s101, 1
	s_branch .Lpf_done_up

.LBB0_2551:
	s_and_b32 s7, s5, 0x18000
	v_add_u32_e32 v222, s7, v180
	s_add_i32 s7, s5, 0xfffe8000
	s_and_b32 s7, s7, 0x18000
	v_or_b32_e32 v223, s7, v179
	v_add_u32_e32 v233, s7, v176
	s_waitcnt vmcnt(8) lgkmcnt(0)
	s_barrier
	v_mfma_f32_32x32x16_bf16 v[112:127], v[150:153], v[142:145], v[112:127]
	v_mfma_f32_32x32x16_bf16 v[96:111], v[150:153], v[130:133], v[96:111]
	v_add_u32_e32 v206, v223, v177
	v_add_u32_e32 v234, v233, v177
	ds_read_b128 v[202:205], v206 offset:16384
	ds_read_b128 v[206:209], v206 offset:18432
	ds_read_b128 v[210:213], v234
	v_mfma_f32_32x32x16_bf16 v[80:95], v[146:149], v[142:145], v[80:95]
	v_mfma_f32_32x32x16_bf16 v[64:79], v[146:149], v[130:133], v[64:79]
	ds_read_b128 v[214:217], v234 offset:2048
	v_readfirstlane_b32 s7, v222
	s_mov_b32 m0, s7
	s_nop 0
	global_load_lds_dwordx4 v[170:171], off
	v_mfma_f32_32x32x16_bf16 v[48:63], v[138:141], v[142:145], v[48:63]
	v_mfma_f32_32x32x16_bf16 v[32:47], v[138:141], v[130:133], v[32:47]
	ds_read_b128 v[224:227], v234 offset:4096
	s_add_i32 s8, s7, 0x2000
	v_lshl_add_u64 v[150:151], v[170:171], 0, s[10:11]
	s_mov_b32 m0, s8
	s_nop 0
	global_load_lds_dwordx4 v[150:151], off
	v_mfma_f32_32x32x16_bf16 v[16:31], v[134:137], v[142:145], v[16:31]
	v_mfma_f32_32x32x16_bf16 v[0:15], v[134:137], v[130:133], v[0:15]
	ds_read_b128 v[234:237], v234 offset:6144
	s_waitcnt lgkmcnt(3)
	v_mfma_f32_32x32x16_bf16 v[112:127], v[210:213], v[202:205], v[112:127]
	v_add_u32_e32 v130, v223, v178
	v_add_u32_e32 v134, v233, v178
	ds_read_b128 v[142:145], v130 offset:16384
	v_mfma_f32_32x32x16_bf16 v[96:111], v[210:213], v[206:209], v[96:111]
	ds_read_b128 v[130:133], v130 offset:18432
	s_add_i32 s8, s7, 0x6000
	s_addk_i32 s7, 0x4000
	s_mov_b32 m0, s7
	s_nop 0
	global_load_lds_dwordx4 v[172:173], off
	s_waitcnt lgkmcnt(4)
	v_mfma_f32_32x32x16_bf16 v[80:95], v[214:217], v[202:205], v[80:95]
	ds_read_b128 v[150:153], v134
	v_mfma_f32_32x32x16_bf16 v[64:79], v[214:217], v[206:209], v[64:79]
	ds_read_b128 v[146:149], v134 offset:2048
	s_waitcnt lgkmcnt(5)
	v_mfma_f32_32x32x16_bf16 v[48:63], v[224:227], v[202:205], v[48:63]
	ds_read_b128 v[138:141], v134 offset:4096
	v_mfma_f32_32x32x16_bf16 v[32:47], v[224:227], v[206:209], v[32:47]
	ds_read_b128 v[134:137], v134 offset:6144
	v_lshl_add_u64 v[222:223], v[172:173], 0, s[10:11]
	s_mov_b32 m0, s8
	s_nop 0
	global_load_lds_dwordx4 v[222:223], off
	s_waitcnt lgkmcnt(6)
	v_mfma_f32_32x32x16_bf16 v[16:31], v[234:237], v[202:205], v[16:31]
	s_add_i32 s5, s5, 0x8000
	v_lshl_add_u64 v[170:171], v[170:171], 0, 64
	v_lshl_add_u64 v[172:173], v[172:173], 0, 64
	s_cmp_eq_u32 s5, 0x2c0000
	v_mfma_f32_32x32x16_bf16 v[0:15], v[234:237], v[206:209], v[0:15]
	s_cbranch_scc0 .LBB0_2551
	s_waitcnt vmcnt(8) lgkmcnt(0)
	s_barrier
	v_add_u32_e32 v202, v179, v177
	v_add_u32_e32 v222, v176, v177
	ds_read_b128 v[170:173], v202 offset:49152
	ds_read_b128 v[202:205], v202 offset:51200
	ds_read_b128 v[206:209], v222 offset:32768
	ds_read_b128 v[210:213], v222 offset:34816
	ds_read_b128 v[214:217], v222 offset:36864
	ds_read_b128 v[224:227], v222 offset:38912
	s_waitcnt lgkmcnt(9)
	v_mfma_f32_32x32x16_bf16 v[112:127], v[150:153], v[142:145], v[112:127]
	v_mfma_f32_32x32x16_bf16 v[96:111], v[150:153], v[130:133], v[96:111]
	s_waitcnt lgkmcnt(8)
	v_mfma_f32_32x32x16_bf16 v[80:95], v[146:149], v[142:145], v[80:95]
	v_mfma_f32_32x32x16_bf16 v[64:79], v[146:149], v[130:133], v[64:79]
	s_waitcnt lgkmcnt(7)
	v_mfma_f32_32x32x16_bf16 v[48:63], v[138:141], v[142:145], v[48:63]
	v_mfma_f32_32x32x16_bf16 v[32:47], v[138:141], v[130:133], v[32:47]
	s_waitcnt lgkmcnt(6)
	v_mfma_f32_32x32x16_bf16 v[16:31], v[134:137], v[142:145], v[16:31]
	v_mfma_f32_32x32x16_bf16 v[0:15], v[134:137], v[130:133], v[0:15]
	v_add_u32_e32 v134, v179, v178
	v_add_u32_e32 v150, v176, v178
	ds_read_b128 v[130:133], v134 offset:49152
	ds_read_b128 v[134:137], v134 offset:51200
	ds_read_b128 v[138:141], v150 offset:32768
	ds_read_b128 v[142:145], v150 offset:34816
	ds_read_b128 v[146:149], v150 offset:36864
	ds_read_b128 v[150:153], v150 offset:38912
	s_waitcnt lgkmcnt(9)
	v_mfma_f32_32x32x16_bf16 v[112:127], v[206:209], v[170:173], v[112:127]
	v_mfma_f32_32x32x16_bf16 v[96:111], v[206:209], v[202:205], v[96:111]
	s_waitcnt lgkmcnt(8)
	v_mfma_f32_32x32x16_bf16 v[80:95], v[210:213], v[170:173], v[80:95]
	v_mfma_f32_32x32x16_bf16 v[64:79], v[210:213], v[202:205], v[64:79]
	s_waitcnt lgkmcnt(7)
	v_mfma_f32_32x32x16_bf16 v[48:63], v[214:217], v[170:173], v[48:63]
	v_mfma_f32_32x32x16_bf16 v[32:47], v[214:217], v[202:205], v[32:47]
	s_waitcnt lgkmcnt(6)
	v_mfma_f32_32x32x16_bf16 v[0:15], v[224:227], v[202:205], v[0:15]
	s_waitcnt vmcnt(4) lgkmcnt(0)
	s_barrier
	v_add_u32_e32 v202, v199, v177
	v_add_u32_e32 v222, v200, v177
	v_mfma_f32_32x32x16_bf16 v[16:31], v[224:227], v[170:173], v[16:31]
	ds_read_b128 v[170:173], v202 offset:16384
	ds_read_b128 v[202:205], v202 offset:18432
	ds_read_b128 v[206:209], v222
	ds_read_b128 v[210:213], v222 offset:2048
	ds_read_b128 v[214:217], v222 offset:4096
	ds_read_b128 v[224:227], v222 offset:6144
	s_waitcnt lgkmcnt(9)
	v_mfma_f32_32x32x16_bf16 v[112:127], v[138:141], v[130:133], v[112:127]
	v_mfma_f32_32x32x16_bf16 v[96:111], v[138:141], v[134:137], v[96:111]
	s_waitcnt lgkmcnt(8)
	v_mfma_f32_32x32x16_bf16 v[80:95], v[142:145], v[130:133], v[80:95]
	v_mfma_f32_32x32x16_bf16 v[64:79], v[142:145], v[134:137], v[64:79]
	s_waitcnt lgkmcnt(7)
	v_mfma_f32_32x32x16_bf16 v[48:63], v[146:149], v[130:133], v[48:63]
	v_mfma_f32_32x32x16_bf16 v[32:47], v[146:149], v[134:137], v[32:47]
	s_waitcnt lgkmcnt(6)
	v_mfma_f32_32x32x16_bf16 v[16:31], v[150:153], v[130:133], v[16:31]
	v_mfma_f32_32x32x16_bf16 v[0:15], v[150:153], v[134:137], v[0:15]
	v_add_u32_e32 v134, v199, v178
	v_add_u32_e32 v150, v200, v178
	ds_read_b128 v[130:133], v134 offset:16384
	ds_read_b128 v[134:137], v134 offset:18432
	ds_read_b128 v[138:141], v150
	ds_read_b128 v[142:145], v150 offset:2048
	ds_read_b128 v[146:149], v150 offset:4096
	ds_read_b128 v[150:153], v150 offset:6144
	s_waitcnt lgkmcnt(9)
	v_mfma_f32_32x32x16_bf16 v[112:127], v[206:209], v[170:173], v[112:127]
	v_mfma_f32_32x32x16_bf16 v[96:111], v[206:209], v[202:205], v[96:111]
	s_waitcnt lgkmcnt(8)
	v_mfma_f32_32x32x16_bf16 v[80:95], v[210:213], v[170:173], v[80:95]
	v_mfma_f32_32x32x16_bf16 v[64:79], v[210:213], v[202:205], v[64:79]
	s_waitcnt lgkmcnt(7)
	v_mfma_f32_32x32x16_bf16 v[48:63], v[214:217], v[170:173], v[48:63]
	v_mfma_f32_32x32x16_bf16 v[32:47], v[214:217], v[202:205], v[32:47]
	s_waitcnt lgkmcnt(6)
	v_mfma_f32_32x32x16_bf16 v[0:15], v[224:227], v[202:205], v[0:15]
	s_waitcnt vmcnt(0) lgkmcnt(0)
	s_barrier
	v_add_u32_e32 v202, v197, v177
	v_add_u32_e32 v222, v198, v177
	v_mfma_f32_32x32x16_bf16 v[16:31], v[224:227], v[170:173], v[16:31]
	ds_read_b128 v[170:173], v202 offset:16384
	ds_read_b128 v[202:205], v202 offset:18432
	ds_read_b128 v[206:209], v222
	ds_read_b128 v[210:213], v222 offset:2048
	ds_read_b128 v[214:217], v222 offset:4096
	ds_read_b128 v[224:227], v222 offset:6144
	s_waitcnt lgkmcnt(9)
	v_mfma_f32_32x32x16_bf16 v[112:127], v[138:141], v[130:133], v[112:127]
	v_mfma_f32_32x32x16_bf16 v[96:111], v[138:141], v[134:137], v[96:111]
	s_waitcnt lgkmcnt(8)
	v_mfma_f32_32x32x16_bf16 v[80:95], v[142:145], v[130:133], v[80:95]
	v_mfma_f32_32x32x16_bf16 v[64:79], v[142:145], v[134:137], v[64:79]
	s_waitcnt lgkmcnt(7)
	v_mfma_f32_32x32x16_bf16 v[48:63], v[146:149], v[130:133], v[48:63]
	v_mfma_f32_32x32x16_bf16 v[32:47], v[146:149], v[134:137], v[32:47]
	s_waitcnt lgkmcnt(6)
	v_mfma_f32_32x32x16_bf16 v[16:31], v[150:153], v[130:133], v[16:31]
	v_mfma_f32_32x32x16_bf16 v[0:15], v[150:153], v[134:137], v[0:15]
	v_add_u32_e32 v134, v197, v178
	v_add_u32_e32 v150, v198, v178
	ds_read_b128 v[130:133], v134 offset:16384
	ds_read_b128 v[134:137], v134 offset:18432
	ds_read_b128 v[138:141], v150
	ds_read_b128 v[142:145], v150 offset:2048
	ds_read_b128 v[146:149], v150 offset:4096
	ds_read_b128 v[150:153], v150 offset:6144
	s_waitcnt lgkmcnt(9)
	v_mfma_f32_32x32x16_bf16 v[112:127], v[206:209], v[170:173], v[112:127]
	v_mfma_f32_32x32x16_bf16 v[96:111], v[206:209], v[202:205], v[96:111]
	s_waitcnt lgkmcnt(8)
	v_mfma_f32_32x32x16_bf16 v[80:95], v[210:213], v[170:173], v[80:95]
	v_mfma_f32_32x32x16_bf16 v[64:79], v[210:213], v[202:205], v[64:79]
	s_waitcnt lgkmcnt(7)
	v_mfma_f32_32x32x16_bf16 v[48:63], v[214:217], v[170:173], v[48:63]
	v_mfma_f32_32x32x16_bf16 v[32:47], v[214:217], v[202:205], v[32:47]
	s_waitcnt lgkmcnt(6)
	v_mfma_f32_32x32x16_bf16 v[16:31], v[224:227], v[170:173], v[16:31]
	s_movk_i32 s7, 0x1600
	v_mfma_f32_32x32x16_bf16 v[0:15], v[224:227], v[202:205], v[0:15]
	s_waitcnt lgkmcnt(3)
	v_mfma_f32_32x32x16_bf16 v[112:127], v[138:141], v[130:133], v[112:127]
	v_mfma_f32_32x32x16_bf16 v[96:111], v[138:141], v[134:137], v[96:111]
	s_nop 10
	v_cvt_pk_bf16_f32 v112, v112, s0
	s_waitcnt lgkmcnt(2)
	v_mfma_f32_32x32x16_bf16 v[80:95], v[142:145], v[130:133], v[80:95]
	v_cvt_pk_bf16_f32 v96, v96, s0
	v_cvt_pk_bf16_f32 v98, v98, s0
	s_waitcnt lgkmcnt(1)
	v_mfma_f32_32x32x16_bf16 v[48:63], v[146:149], v[130:133], v[48:63]
	s_nop 7
	v_cvt_pk_bf16_f32 v80, v80, s0
	s_waitcnt lgkmcnt(0)
	v_mfma_f32_32x32x16_bf16 v[16:31], v[150:153], v[130:133], v[16:31]
	v_add_u32_e32 v132, s3, v128
	v_or_b32_e32 v130, s4, v174
	v_ashrrev_i32_e32 v131, 31, v130
	v_lshl_add_u64 v[130:131], v[130:131], 1, v[158:159]
	v_cvt_pk_bf16_f32 v48, v48, s0
	v_readlane_b32 s3, v252, 7
	s_add_i32 s6, s6, s3
	v_mfma_f32_32x32x16_bf16 v[64:79], v[142:145], v[134:137], v[64:79]
	s_nop 3
	v_cvt_pk_bf16_f32 v16, v16, s0
	v_mfma_f32_32x32x16_bf16 v[32:47], v[146:149], v[134:137], v[32:47]
	s_nop 5
	v_cvt_pk_bf16_f32 v64, v64, s0
	v_cvt_pk_bf16_f32 v66, v66, s0
	v_mfma_f32_32x32x16_bf16 v[0:15], v[150:153], v[134:137], v[0:15]
	v_or_b32_e32 v134, v132, v181
	v_ashrrev_i32_e32 v135, 31, v134
	v_lshlrev_b64 v[134:135], 11, v[134:135]
	v_lshl_add_u64 v[134:135], v[130:131], 0, v[134:135]
	global_store_short v[134:135], v112, off
	global_store_short v[134:135], v96, off offset:64
	v_or_b32_e32 v134, v132, v182
	v_ashrrev_i32_e32 v135, 31, v134
	v_lshlrev_b64 v[134:135], 11, v[134:135]
	v_lshl_add_u64 v[134:135], v[130:131], 0, v[134:135]
	v_cvt_pk_bf16_f32 v96, v113, s0
	global_store_short v[134:135], v96, off
	v_cvt_pk_bf16_f32 v96, v97, s0
	global_store_short v[134:135], v96, off offset:64
	v_or_b32_e32 v96, v132, v183
	v_ashrrev_i32_e32 v97, 31, v96
	v_lshlrev_b64 v[96:97], 11, v[96:97]
	v_lshl_add_u64 v[96:97], v[130:131], 0, v[96:97]
	v_cvt_pk_bf16_f32 v112, v114, s0
	global_store_short v[96:97], v112, off
	global_store_short v[96:97], v98, off offset:64
	v_or_b32_e32 v96, v132, v184
	v_ashrrev_i32_e32 v97, 31, v96
	v_lshlrev_b64 v[96:97], 11, v[96:97]
	v_lshl_add_u64 v[96:97], v[130:131], 0, v[96:97]
	v_cvt_pk_bf16_f32 v98, v115, s0
	global_store_short v[96:97], v98, off
	v_cvt_pk_bf16_f32 v98, v99, s0
	global_store_short v[96:97], v98, off offset:64
	v_or_b32_e32 v96, v132, v185
	v_ashrrev_i32_e32 v97, 31, v96
	v_lshlrev_b64 v[96:97], 11, v[96:97]
	v_lshl_add_u64 v[96:97], v[130:131], 0, v[96:97]
	v_cvt_pk_bf16_f32 v98, v116, s0
	global_store_short v[96:97], v98, off
	v_cvt_pk_bf16_f32 v98, v100, s0
	global_store_short v[96:97], v98, off offset:64
	v_or_b32_e32 v96, v132, v186
	v_ashrrev_i32_e32 v97, 31, v96
	v_lshlrev_b64 v[96:97], 11, v[96:97]
	v_lshl_add_u64 v[96:97], v[130:131], 0, v[96:97]
	v_cvt_pk_bf16_f32 v98, v117, s0
	global_store_short v[96:97], v98, off
	v_cvt_pk_bf16_f32 v98, v101, s0
	global_store_short v[96:97], v98, off offset:64
	v_or_b32_e32 v96, v132, v187
	v_ashrrev_i32_e32 v97, 31, v96
	v_lshlrev_b64 v[96:97], 11, v[96:97]
	v_lshl_add_u64 v[96:97], v[130:131], 0, v[96:97]
	v_cvt_pk_bf16_f32 v98, v118, s0
	global_store_short v[96:97], v98, off
	v_cvt_pk_bf16_f32 v98, v102, s0
	global_store_short v[96:97], v98, off offset:64
	v_or_b32_e32 v96, v132, v188
	v_ashrrev_i32_e32 v97, 31, v96
	v_lshlrev_b64 v[96:97], 11, v[96:97]
	v_lshl_add_u64 v[96:97], v[130:131], 0, v[96:97]
	v_cvt_pk_bf16_f32 v98, v119, s0
	global_store_short v[96:97], v98, off
	v_cvt_pk_bf16_f32 v98, v103, s0
	global_store_short v[96:97], v98, off offset:64
	v_or_b32_e32 v96, v132, v189
	v_ashrrev_i32_e32 v97, 31, v96
	v_lshlrev_b64 v[96:97], 11, v[96:97]
	v_lshl_add_u64 v[96:97], v[130:131], 0, v[96:97]
	v_cvt_pk_bf16_f32 v98, v120, s0
	global_store_short v[96:97], v98, off
	v_cvt_pk_bf16_f32 v98, v104, s0
	global_store_short v[96:97], v98, off offset:64
	v_or_b32_e32 v96, v132, v190
	v_ashrrev_i32_e32 v97, 31, v96
	v_lshlrev_b64 v[96:97], 11, v[96:97]
	v_lshl_add_u64 v[96:97], v[130:131], 0, v[96:97]
	v_cvt_pk_bf16_f32 v98, v121, s0
	global_store_short v[96:97], v98, off
	v_cvt_pk_bf16_f32 v98, v105, s0
	global_store_short v[96:97], v98, off offset:64
	v_or_b32_e32 v96, v132, v191
	v_ashrrev_i32_e32 v97, 31, v96
	v_lshlrev_b64 v[96:97], 11, v[96:97]
	v_lshl_add_u64 v[96:97], v[130:131], 0, v[96:97]
	v_cvt_pk_bf16_f32 v98, v122, s0
	global_store_short v[96:97], v98, off
	v_cvt_pk_bf16_f32 v98, v106, s0
	global_store_short v[96:97], v98, off offset:64
	v_or_b32_e32 v96, v132, v192
	v_ashrrev_i32_e32 v97, 31, v96
	v_lshlrev_b64 v[96:97], 11, v[96:97]
	v_lshl_add_u64 v[96:97], v[130:131], 0, v[96:97]
	v_cvt_pk_bf16_f32 v98, v123, s0
	global_store_short v[96:97], v98, off
	v_cvt_pk_bf16_f32 v98, v107, s0
	global_store_short v[96:97], v98, off offset:64
	v_or_b32_e32 v96, v132, v193
	v_ashrrev_i32_e32 v97, 31, v96
	v_lshlrev_b64 v[96:97], 11, v[96:97]
	v_lshl_add_u64 v[96:97], v[130:131], 0, v[96:97]
	v_cvt_pk_bf16_f32 v98, v124, s0
	global_store_short v[96:97], v98, off
	v_cvt_pk_bf16_f32 v98, v108, s0
	global_store_short v[96:97], v98, off offset:64
	v_or_b32_e32 v96, v132, v194
	v_ashrrev_i32_e32 v97, 31, v96
	v_lshlrev_b64 v[96:97], 11, v[96:97]
	v_lshl_add_u64 v[96:97], v[130:131], 0, v[96:97]
	v_cvt_pk_bf16_f32 v98, v125, s0
	global_store_short v[96:97], v98, off
	v_cvt_pk_bf16_f32 v98, v109, s0
	global_store_short v[96:97], v98, off offset:64
	v_or_b32_e32 v96, v132, v195
	v_ashrrev_i32_e32 v97, 31, v96
	v_lshlrev_b64 v[96:97], 11, v[96:97]
	v_lshl_add_u64 v[96:97], v[130:131], 0, v[96:97]
	v_cvt_pk_bf16_f32 v98, v126, s0
	global_store_short v[96:97], v98, off
	v_cvt_pk_bf16_f32 v98, v110, s0
	global_store_short v[96:97], v98, off offset:64
	v_or_b32_e32 v96, v132, v196
	v_ashrrev_i32_e32 v97, 31, v96
	v_lshlrev_b64 v[96:97], 11, v[96:97]
	v_lshl_add_u64 v[96:97], v[130:131], 0, v[96:97]
	v_cvt_pk_bf16_f32 v98, v127, s0
	global_store_short v[96:97], v98, off
	v_cvt_pk_bf16_f32 v98, v111, s0
	global_store_short v[96:97], v98, off offset:64
	v_or_b32_e32 v98, 32, v132
	v_or_b32_e32 v96, v98, v181
	v_ashrrev_i32_e32 v97, 31, v96
	v_lshlrev_b64 v[96:97], 11, v[96:97]
	v_lshl_add_u64 v[96:97], v[130:131], 0, v[96:97]
	global_store_short v[96:97], v80, off
	global_store_short v[96:97], v64, off offset:64
	v_or_b32_e32 v96, v98, v182
	v_ashrrev_i32_e32 v97, 31, v96
	v_lshlrev_b64 v[96:97], 11, v[96:97]
	v_lshl_add_u64 v[96:97], v[130:131], 0, v[96:97]
	v_cvt_pk_bf16_f32 v64, v81, s0
	global_store_short v[96:97], v64, off
	v_cvt_pk_bf16_f32 v64, v65, s0
	global_store_short v[96:97], v64, off offset:64
	v_or_b32_e32 v64, v98, v183
	v_ashrrev_i32_e32 v65, 31, v64
	v_lshlrev_b64 v[64:65], 11, v[64:65]
	v_lshl_add_u64 v[64:65], v[130:131], 0, v[64:65]
	v_cvt_pk_bf16_f32 v80, v82, s0
	global_store_short v[64:65], v80, off
	global_store_short v[64:65], v66, off offset:64
	v_or_b32_e32 v64, v98, v184
	v_ashrrev_i32_e32 v65, 31, v64
	v_lshlrev_b64 v[64:65], 11, v[64:65]
	v_lshl_add_u64 v[64:65], v[130:131], 0, v[64:65]
	v_cvt_pk_bf16_f32 v66, v83, s0
	global_store_short v[64:65], v66, off
	v_cvt_pk_bf16_f32 v66, v67, s0
	global_store_short v[64:65], v66, off offset:64
	v_or_b32_e32 v64, v98, v185
	v_ashrrev_i32_e32 v65, 31, v64
	v_lshlrev_b64 v[64:65], 11, v[64:65]
	v_lshl_add_u64 v[64:65], v[130:131], 0, v[64:65]
	v_cvt_pk_bf16_f32 v66, v84, s0
	global_store_short v[64:65], v66, off
	v_cvt_pk_bf16_f32 v66, v68, s0
	global_store_short v[64:65], v66, off offset:64
	v_or_b32_e32 v64, v98, v186
	v_ashrrev_i32_e32 v65, 31, v64
	v_lshlrev_b64 v[64:65], 11, v[64:65]
	v_lshl_add_u64 v[64:65], v[130:131], 0, v[64:65]
	v_cvt_pk_bf16_f32 v66, v85, s0
	global_store_short v[64:65], v66, off
	v_cvt_pk_bf16_f32 v66, v69, s0
	global_store_short v[64:65], v66, off offset:64
	v_or_b32_e32 v64, v98, v187
	v_ashrrev_i32_e32 v65, 31, v64
	v_lshlrev_b64 v[64:65], 11, v[64:65]
	v_lshl_add_u64 v[64:65], v[130:131], 0, v[64:65]
	v_cvt_pk_bf16_f32 v66, v86, s0
	global_store_short v[64:65], v66, off
	v_cvt_pk_bf16_f32 v66, v70, s0
	global_store_short v[64:65], v66, off offset:64
	v_or_b32_e32 v64, v98, v188
	v_ashrrev_i32_e32 v65, 31, v64
	v_lshlrev_b64 v[64:65], 11, v[64:65]
	v_lshl_add_u64 v[64:65], v[130:131], 0, v[64:65]
	v_cvt_pk_bf16_f32 v66, v87, s0
	global_store_short v[64:65], v66, off
	v_cvt_pk_bf16_f32 v66, v71, s0
	global_store_short v[64:65], v66, off offset:64
	v_or_b32_e32 v64, v98, v189
	v_ashrrev_i32_e32 v65, 31, v64
	v_lshlrev_b64 v[64:65], 11, v[64:65]
	v_lshl_add_u64 v[64:65], v[130:131], 0, v[64:65]
	v_cvt_pk_bf16_f32 v66, v88, s0
	global_store_short v[64:65], v66, off
	v_cvt_pk_bf16_f32 v66, v72, s0
	global_store_short v[64:65], v66, off offset:64
	v_or_b32_e32 v64, v98, v190
	v_ashrrev_i32_e32 v65, 31, v64
	v_lshlrev_b64 v[64:65], 11, v[64:65]
	v_lshl_add_u64 v[64:65], v[130:131], 0, v[64:65]
	v_cvt_pk_bf16_f32 v66, v89, s0
	global_store_short v[64:65], v66, off
	v_cvt_pk_bf16_f32 v66, v73, s0
	global_store_short v[64:65], v66, off offset:64
	v_or_b32_e32 v64, v98, v191
	v_ashrrev_i32_e32 v65, 31, v64
	v_lshlrev_b64 v[64:65], 11, v[64:65]
	v_lshl_add_u64 v[64:65], v[130:131], 0, v[64:65]
	v_cvt_pk_bf16_f32 v66, v90, s0
	global_store_short v[64:65], v66, off
	v_cvt_pk_bf16_f32 v66, v74, s0
	global_store_short v[64:65], v66, off offset:64
	v_or_b32_e32 v64, v98, v192
	v_ashrrev_i32_e32 v65, 31, v64
	v_lshlrev_b64 v[64:65], 11, v[64:65]
	v_lshl_add_u64 v[64:65], v[130:131], 0, v[64:65]
	v_cvt_pk_bf16_f32 v66, v91, s0
	global_store_short v[64:65], v66, off
	v_cvt_pk_bf16_f32 v66, v75, s0
	global_store_short v[64:65], v66, off offset:64
	v_or_b32_e32 v64, v98, v193
	v_ashrrev_i32_e32 v65, 31, v64
	v_lshlrev_b64 v[64:65], 11, v[64:65]
	v_lshl_add_u64 v[64:65], v[130:131], 0, v[64:65]
	v_cvt_pk_bf16_f32 v66, v92, s0
	global_store_short v[64:65], v66, off
	v_cvt_pk_bf16_f32 v66, v76, s0
	global_store_short v[64:65], v66, off offset:64
	v_or_b32_e32 v64, v98, v194
	v_ashrrev_i32_e32 v65, 31, v64
	v_lshlrev_b64 v[64:65], 11, v[64:65]
	v_lshl_add_u64 v[64:65], v[130:131], 0, v[64:65]
	v_cvt_pk_bf16_f32 v66, v93, s0
	global_store_short v[64:65], v66, off
	v_cvt_pk_bf16_f32 v66, v77, s0
	global_store_short v[64:65], v66, off offset:64
	v_or_b32_e32 v64, v98, v195
	v_ashrrev_i32_e32 v65, 31, v64
	v_lshlrev_b64 v[64:65], 11, v[64:65]
	v_lshl_add_u64 v[64:65], v[130:131], 0, v[64:65]
	v_cvt_pk_bf16_f32 v66, v94, s0
	global_store_short v[64:65], v66, off
	v_cvt_pk_bf16_f32 v66, v78, s0
	global_store_short v[64:65], v66, off offset:64
	v_or_b32_e32 v64, v98, v196
	v_ashrrev_i32_e32 v65, 31, v64
	v_lshlrev_b64 v[64:65], 11, v[64:65]
	v_lshl_add_u64 v[64:65], v[130:131], 0, v[64:65]
	v_cvt_pk_bf16_f32 v66, v95, s0
	global_store_short v[64:65], v66, off
	v_cvt_pk_bf16_f32 v66, v79, s0
	global_store_short v[64:65], v66, off offset:64
	v_or_b32_e32 v66, 64, v132
	v_or_b32_e32 v64, v66, v181
	v_ashrrev_i32_e32 v65, 31, v64
	v_lshlrev_b64 v[64:65], 11, v[64:65]
	v_lshl_add_u64 v[64:65], v[130:131], 0, v[64:65]
	v_cvt_pk_bf16_f32 v32, v32, s0
	global_store_short v[64:65], v48, off
	global_store_short v[64:65], v32, off offset:64
	v_or_b32_e32 v64, v66, v182
	v_ashrrev_i32_e32 v65, 31, v64
	v_lshlrev_b64 v[64:65], 11, v[64:65]
	v_lshl_add_u64 v[64:65], v[130:131], 0, v[64:65]
	v_cvt_pk_bf16_f32 v32, v49, s0
	global_store_short v[64:65], v32, off
	v_cvt_pk_bf16_f32 v32, v33, s0
	global_store_short v[64:65], v32, off offset:64
	v_or_b32_e32 v32, v66, v183
	v_ashrrev_i32_e32 v33, 31, v32
	v_lshlrev_b64 v[32:33], 11, v[32:33]
	v_lshl_add_u64 v[32:33], v[130:131], 0, v[32:33]
	v_cvt_pk_bf16_f32 v48, v50, s0
	v_cvt_pk_bf16_f32 v34, v34, s0
	global_store_short v[32:33], v48, off
	global_store_short v[32:33], v34, off offset:64
	v_or_b32_e32 v32, v66, v184
	v_ashrrev_i32_e32 v33, 31, v32
	v_lshlrev_b64 v[32:33], 11, v[32:33]
	v_lshl_add_u64 v[32:33], v[130:131], 0, v[32:33]
	v_cvt_pk_bf16_f32 v34, v51, s0
	global_store_short v[32:33], v34, off
	v_cvt_pk_bf16_f32 v34, v35, s0
	global_store_short v[32:33], v34, off offset:64
	v_or_b32_e32 v32, v66, v185
	v_ashrrev_i32_e32 v33, 31, v32
	v_lshlrev_b64 v[32:33], 11, v[32:33]
	v_lshl_add_u64 v[32:33], v[130:131], 0, v[32:33]
	v_cvt_pk_bf16_f32 v34, v52, s0
	global_store_short v[32:33], v34, off
	v_cvt_pk_bf16_f32 v34, v36, s0
	global_store_short v[32:33], v34, off offset:64
	v_or_b32_e32 v32, v66, v186
	v_ashrrev_i32_e32 v33, 31, v32
	v_lshlrev_b64 v[32:33], 11, v[32:33]
	v_lshl_add_u64 v[32:33], v[130:131], 0, v[32:33]
	v_cvt_pk_bf16_f32 v34, v53, s0
	global_store_short v[32:33], v34, off
	v_cvt_pk_bf16_f32 v34, v37, s0
	global_store_short v[32:33], v34, off offset:64
	v_or_b32_e32 v32, v66, v187
	v_ashrrev_i32_e32 v33, 31, v32
	v_lshlrev_b64 v[32:33], 11, v[32:33]
	v_lshl_add_u64 v[32:33], v[130:131], 0, v[32:33]
	v_cvt_pk_bf16_f32 v34, v54, s0
	global_store_short v[32:33], v34, off
	v_cvt_pk_bf16_f32 v34, v38, s0
	global_store_short v[32:33], v34, off offset:64
	v_or_b32_e32 v32, v66, v188
	v_ashrrev_i32_e32 v33, 31, v32
	v_lshlrev_b64 v[32:33], 11, v[32:33]
	v_lshl_add_u64 v[32:33], v[130:131], 0, v[32:33]
	v_cvt_pk_bf16_f32 v34, v55, s0
	global_store_short v[32:33], v34, off
	v_cvt_pk_bf16_f32 v34, v39, s0
	global_store_short v[32:33], v34, off offset:64
	v_or_b32_e32 v32, v66, v189
	v_ashrrev_i32_e32 v33, 31, v32
	v_lshlrev_b64 v[32:33], 11, v[32:33]
	v_lshl_add_u64 v[32:33], v[130:131], 0, v[32:33]
	v_cvt_pk_bf16_f32 v34, v56, s0
	global_store_short v[32:33], v34, off
	v_cvt_pk_bf16_f32 v34, v40, s0
	global_store_short v[32:33], v34, off offset:64
	v_or_b32_e32 v32, v66, v190
	v_ashrrev_i32_e32 v33, 31, v32
	v_lshlrev_b64 v[32:33], 11, v[32:33]
	v_lshl_add_u64 v[32:33], v[130:131], 0, v[32:33]
	v_cvt_pk_bf16_f32 v34, v57, s0
	global_store_short v[32:33], v34, off
	v_cvt_pk_bf16_f32 v34, v41, s0
	global_store_short v[32:33], v34, off offset:64
	v_or_b32_e32 v32, v66, v191
	v_ashrrev_i32_e32 v33, 31, v32
	v_lshlrev_b64 v[32:33], 11, v[32:33]
	v_lshl_add_u64 v[32:33], v[130:131], 0, v[32:33]
	v_cvt_pk_bf16_f32 v34, v58, s0
	global_store_short v[32:33], v34, off
	v_cvt_pk_bf16_f32 v34, v42, s0
	global_store_short v[32:33], v34, off offset:64
	v_or_b32_e32 v32, v66, v192
	v_ashrrev_i32_e32 v33, 31, v32
	v_lshlrev_b64 v[32:33], 11, v[32:33]
	v_lshl_add_u64 v[32:33], v[130:131], 0, v[32:33]
	v_cvt_pk_bf16_f32 v34, v59, s0
	global_store_short v[32:33], v34, off
	v_cvt_pk_bf16_f32 v34, v43, s0
	global_store_short v[32:33], v34, off offset:64
	v_or_b32_e32 v32, v66, v193
	v_ashrrev_i32_e32 v33, 31, v32
	v_lshlrev_b64 v[32:33], 11, v[32:33]
	v_lshl_add_u64 v[32:33], v[130:131], 0, v[32:33]
	v_cvt_pk_bf16_f32 v34, v60, s0
	global_store_short v[32:33], v34, off
	v_cvt_pk_bf16_f32 v34, v44, s0
	global_store_short v[32:33], v34, off offset:64
	v_or_b32_e32 v32, v66, v194
	v_ashrrev_i32_e32 v33, 31, v32
	v_lshlrev_b64 v[32:33], 11, v[32:33]
	v_lshl_add_u64 v[32:33], v[130:131], 0, v[32:33]
	v_cvt_pk_bf16_f32 v34, v61, s0
	global_store_short v[32:33], v34, off
	v_cvt_pk_bf16_f32 v34, v45, s0
	global_store_short v[32:33], v34, off offset:64
	v_or_b32_e32 v32, v66, v195
	v_ashrrev_i32_e32 v33, 31, v32
	v_lshlrev_b64 v[32:33], 11, v[32:33]
	v_lshl_add_u64 v[32:33], v[130:131], 0, v[32:33]
	v_cvt_pk_bf16_f32 v34, v62, s0
	global_store_short v[32:33], v34, off
	v_cvt_pk_bf16_f32 v34, v46, s0
	global_store_short v[32:33], v34, off offset:64
	v_or_b32_e32 v32, v66, v196
	v_ashrrev_i32_e32 v33, 31, v32
	v_lshlrev_b64 v[32:33], 11, v[32:33]
	v_lshl_add_u64 v[32:33], v[130:131], 0, v[32:33]
	v_cvt_pk_bf16_f32 v34, v63, s0
	global_store_short v[32:33], v34, off
	v_cvt_pk_bf16_f32 v34, v47, s0
	global_store_short v[32:33], v34, off offset:64
	v_or_b32_e32 v34, 0x60, v132
	v_or_b32_e32 v32, v34, v181
	v_ashrrev_i32_e32 v33, 31, v32
	v_lshlrev_b64 v[32:33], 11, v[32:33]
	v_lshl_add_u64 v[32:33], v[130:131], 0, v[32:33]
	v_cvt_pk_bf16_f32 v0, v0, s0
	global_store_short v[32:33], v16, off
	global_store_short v[32:33], v0, off offset:64
	v_or_b32_e32 v32, v34, v182
	v_ashrrev_i32_e32 v33, 31, v32
	v_lshlrev_b64 v[32:33], 11, v[32:33]
	v_lshl_add_u64 v[32:33], v[130:131], 0, v[32:33]
	v_cvt_pk_bf16_f32 v0, v17, s0
	global_store_short v[32:33], v0, off
	v_cvt_pk_bf16_f32 v0, v1, s0
	global_store_short v[32:33], v0, off offset:64
	v_or_b32_e32 v0, v34, v183
	v_ashrrev_i32_e32 v1, 31, v0
	v_lshlrev_b64 v[0:1], 11, v[0:1]
	v_lshl_add_u64 v[0:1], v[130:131], 0, v[0:1]
	v_cvt_pk_bf16_f32 v16, v18, s0
	v_cvt_pk_bf16_f32 v2, v2, s0
	global_store_short v[0:1], v16, off
	global_store_short v[0:1], v2, off offset:64
	v_or_b32_e32 v0, v34, v184
	v_ashrrev_i32_e32 v1, 31, v0
	v_lshlrev_b64 v[0:1], 11, v[0:1]
	v_lshl_add_u64 v[0:1], v[130:131], 0, v[0:1]
	v_cvt_pk_bf16_f32 v2, v19, s0
	global_store_short v[0:1], v2, off
	v_cvt_pk_bf16_f32 v2, v3, s0
	global_store_short v[0:1], v2, off offset:64
	v_or_b32_e32 v0, v34, v185
	v_ashrrev_i32_e32 v1, 31, v0
	v_lshlrev_b64 v[0:1], 11, v[0:1]
	v_lshl_add_u64 v[0:1], v[130:131], 0, v[0:1]
	v_cvt_pk_bf16_f32 v2, v20, s0
	global_store_short v[0:1], v2, off
	v_cvt_pk_bf16_f32 v2, v4, s0
	global_store_short v[0:1], v2, off offset:64
	v_or_b32_e32 v0, v34, v186
	v_ashrrev_i32_e32 v1, 31, v0
	v_lshlrev_b64 v[0:1], 11, v[0:1]
	v_lshl_add_u64 v[0:1], v[130:131], 0, v[0:1]
	v_cvt_pk_bf16_f32 v2, v21, s0
	global_store_short v[0:1], v2, off
	v_cvt_pk_bf16_f32 v2, v5, s0
	global_store_short v[0:1], v2, off offset:64
	v_or_b32_e32 v0, v34, v187
	v_ashrrev_i32_e32 v1, 31, v0
	v_lshlrev_b64 v[0:1], 11, v[0:1]
	v_lshl_add_u64 v[0:1], v[130:131], 0, v[0:1]
	v_cvt_pk_bf16_f32 v2, v22, s0
	global_store_short v[0:1], v2, off
	v_cvt_pk_bf16_f32 v2, v6, s0
	global_store_short v[0:1], v2, off offset:64
	v_or_b32_e32 v0, v34, v188
	v_ashrrev_i32_e32 v1, 31, v0
	v_lshlrev_b64 v[0:1], 11, v[0:1]
	v_lshl_add_u64 v[0:1], v[130:131], 0, v[0:1]
	v_cvt_pk_bf16_f32 v2, v23, s0
	global_store_short v[0:1], v2, off
	v_cvt_pk_bf16_f32 v2, v7, s0
	global_store_short v[0:1], v2, off offset:64
	v_or_b32_e32 v0, v34, v189
	v_ashrrev_i32_e32 v1, 31, v0
	v_lshlrev_b64 v[0:1], 11, v[0:1]
	v_lshl_add_u64 v[0:1], v[130:131], 0, v[0:1]
	v_cvt_pk_bf16_f32 v2, v24, s0
	global_store_short v[0:1], v2, off
	v_cvt_pk_bf16_f32 v2, v8, s0
	global_store_short v[0:1], v2, off offset:64
	v_or_b32_e32 v0, v34, v190
	v_ashrrev_i32_e32 v1, 31, v0
	v_lshlrev_b64 v[0:1], 11, v[0:1]
	v_lshl_add_u64 v[0:1], v[130:131], 0, v[0:1]
	v_cvt_pk_bf16_f32 v2, v25, s0
	global_store_short v[0:1], v2, off
	v_cvt_pk_bf16_f32 v2, v9, s0
	global_store_short v[0:1], v2, off offset:64
	v_or_b32_e32 v0, v34, v191
	v_ashrrev_i32_e32 v1, 31, v0
	v_lshlrev_b64 v[0:1], 11, v[0:1]
	v_lshl_add_u64 v[0:1], v[130:131], 0, v[0:1]
	v_cvt_pk_bf16_f32 v2, v26, s0
	global_store_short v[0:1], v2, off
	v_cvt_pk_bf16_f32 v2, v10, s0
	global_store_short v[0:1], v2, off offset:64
	v_or_b32_e32 v0, v34, v192
	v_ashrrev_i32_e32 v1, 31, v0
	v_lshlrev_b64 v[0:1], 11, v[0:1]
	v_lshl_add_u64 v[0:1], v[130:131], 0, v[0:1]
	v_cvt_pk_bf16_f32 v2, v27, s0
	global_store_short v[0:1], v2, off
	v_cvt_pk_bf16_f32 v2, v11, s0
	global_store_short v[0:1], v2, off offset:64
	v_or_b32_e32 v0, v34, v193
	v_ashrrev_i32_e32 v1, 31, v0
	v_lshlrev_b64 v[0:1], 11, v[0:1]
	v_lshl_add_u64 v[0:1], v[130:131], 0, v[0:1]
	v_cvt_pk_bf16_f32 v2, v28, s0
	global_store_short v[0:1], v2, off
	v_cvt_pk_bf16_f32 v2, v12, s0
	global_store_short v[0:1], v2, off offset:64
	v_or_b32_e32 v0, v34, v194
	v_ashrrev_i32_e32 v1, 31, v0
	v_lshlrev_b64 v[0:1], 11, v[0:1]
	v_lshl_add_u64 v[0:1], v[130:131], 0, v[0:1]
	v_cvt_pk_bf16_f32 v2, v29, s0
	global_store_short v[0:1], v2, off
	v_cvt_pk_bf16_f32 v2, v13, s0
	global_store_short v[0:1], v2, off offset:64
	v_or_b32_e32 v0, v34, v195
	v_ashrrev_i32_e32 v1, 31, v0
	v_lshlrev_b64 v[0:1], 11, v[0:1]
	v_lshl_add_u64 v[0:1], v[130:131], 0, v[0:1]
	v_cvt_pk_bf16_f32 v2, v30, s0
	global_store_short v[0:1], v2, off
	v_cvt_pk_bf16_f32 v2, v14, s0
	global_store_short v[0:1], v2, off offset:64
	v_or_b32_e32 v0, v34, v196
	v_ashrrev_i32_e32 v1, 31, v0
	v_lshlrev_b64 v[0:1], 11, v[0:1]
	v_lshl_add_u64 v[0:1], v[130:131], 0, v[0:1]
	v_cvt_pk_bf16_f32 v2, v31, s0
	global_store_short v[0:1], v2, off
	v_cvt_pk_bf16_f32 v2, v15, s0
	s_add_i32 s0, s0, s3
	v_readlane_b32 s3, v252, 8
	s_add_i32 s2, s2, s3
	s_cmp_gt_i32 s6, 31
	global_store_short v[0:1], v2, off offset:64
	s_cbranch_scc0 .LBB0_2550
